# static s_setprio 1 for waves 0-3 before each K-loop (doc 6.3/7.4), reset after the loop
# baseline (speedup 1.0000x reference)
; #define PG8_STAGE(bufoff, gbase, voff) do { _Pragma("unroll") for (int _i = 0; _i < 2; ++_i) \
;         __builtin_amdgcn_global_load_lds((const unsigned*)((const char*)(gbase) + (voff)[_i]), (PG8_LAS unsigned*)(lds + (bufoff) + ldsw + _i * 8192), 16, 0, 0); } while (0)
; #define PG8_LDA(dst, b, h) do { _Pragma("unroll") for (int m = 0; m < 4; ++m) _Pragma("unroll") for (int k = 0; k < 2; ++k) dst[m][k] = *(const PG8_LAS bf16x8*)(lds + PG8_SA(b, h) + aoff + m * 2048 + k * 1024); } while (0)
; #define PG8_LDB(dst, b, h) do { _Pragma("unroll") for (int n = 0; n < 2; ++n) _Pragma("unroll") for (int k = 0; k < 2; ++k) dst[n][k] = *(const PG8_LAS bf16x8*)(lds + PG8_SB(b, h) + boff + n * 2048 + k * 1024); } while (0)
; #define PG8_WAIT_V(n) asm volatile("s_waitcnt vmcnt(" #n ")" ::: "memory")
; #define PG8_WAIT_L(n) asm volatile("s_waitcnt lgkmcnt(" #n ")" ::: "memory")
; #define PG8_BAR __builtin_amdgcn_s_barrier()
; #define PG8_SCHED __builtin_amdgcn_sched_barrier(0)
; template <class Epi, class Sched, bool ALIGN_EPI = false, bool SP2 = false>
; __device__ __forceinline__ void gemm_phase(PG8_LAS unsigned char* lds, const Gemm g, const Sched& S, const Epi& E) {
;     ...
;     for (;;) {
;         const bool has_next = S.next(ui + 1, nxt);
;         const char* nA = has_next ? (const char*)g.A + (size_t)nxt.pm * tstep : cA; const char* nB = has_next ? (const char*)g.Bt + (size_t)nxt.pn * tstep : cB;
;         for (int t = 0; t < nt; t += 2) {
;             const bool last = (t == nt - 2);
;             const char* a1 = cA + (size_t)(t + 1) * kstepA;
;             const char* a2 = last ? nA : cA + (size_t)(t + 2) * kstepA; const char* b2 = last ? nB : cB + (size_t)(t + 2) * kstep;
;             const char* a3 = a2 + kstepA; const char* b3 = b2 + kstep;
;             if (last && has_next) S.a_ready(nxt);
;             if constexpr (SP2) {
;             PG8_LDB(B0, 0, 0); PG8_LDB(B1, 0, 1); PG8_SCHED; PG8_LDA(At, 0, 0); PG8_STAGE(PG8_SA(1, 1), a1 + hstepA, voffA);
;             PG8_WAIT_V(8); PG8_WAIT_L(0); PG8_BAR; PG8_MMA(0, 0, At, B0); PG8_MMA(0, 1, At, B1); PG8_BAR; PG8_SCHED;
;     ...
;         for (int a = 0; a < 2; ++a)
; #pragma unroll
;             for (int b = 0; b < 2; ++b)
; #pragma unroll
;                 for (int m = 0; m < 4; ++m)
; #pragma unroll
;                     for (int n = 0; n < 2; ++n) acc[a][b][m][n] = (f32x4){0.f, 0.f, 0.f, 0.f};
.LBB0_114:
	s_ashr_i32 s21, s20, 31
	s_lshl_b64 s[22:23], s[20:21], 21
	s_add_u32 s22, s92, s22
	s_addc_u32 s23, s93, s23
	s_and_b64 s[24:25], s[0:1], exec
	s_cselect_b32 s21, s23, s35
	s_cselect_b32 s27, s22, s34
	s_ashr_i32 s19, s18, 31
	s_lshl_b64 s[24:25], s[18:19], 21
	s_add_u32 s24, s3, s24
	s_addc_u32 s25, s29, s25
	s_and_b64 s[66:67], s[0:1], exec
	s_cselect_b32 s19, s25, s85
	s_cselect_b32 s31, s24, s84
	s_add_u32 s34, s34, 0x100080
	s_addc_u32 s35, s35, 0
	s_add_u32 s65, s84, 0x100
	v_mov_b32_e32 v0, 0
	s_addc_u32 s66, s85, 0
	s_mov_b32 s67, -2
	v_mov_b32_e32 v1, v0
	v_mov_b32_e32 v2, v0
	v_mov_b32_e32 v3, v0
	v_mov_b32_e32 v4, v0
	v_mov_b32_e32 v5, v0
	v_mov_b32_e32 v6, v0
	v_mov_b32_e32 v7, v0
	v_mov_b32_e32 v16, v0
	v_mov_b32_e32 v17, v0
	v_mov_b32_e32 v18, v0
	v_mov_b32_e32 v19, v0
	v_mov_b32_e32 v20, v0
	v_mov_b32_e32 v21, v0
	v_mov_b32_e32 v22, v0
	v_mov_b32_e32 v23, v0
	v_mov_b32_e32 v32, v0
	v_mov_b32_e32 v33, v0
	v_mov_b32_e32 v34, v0
	v_mov_b32_e32 v35, v0
	v_mov_b32_e32 v36, v0
	v_mov_b32_e32 v37, v0
	v_mov_b32_e32 v38, v0
	v_mov_b32_e32 v39, v0
	v_mov_b32_e32 v48, v0
	v_mov_b32_e32 v49, v0
	v_mov_b32_e32 v50, v0
	v_mov_b32_e32 v51, v0
	v_mov_b32_e32 v52, v0
	v_mov_b32_e32 v53, v0
	v_mov_b32_e32 v54, v0
	v_mov_b32_e32 v55, v0
	v_mov_b32_e32 v8, v0
	v_mov_b32_e32 v9, v0
	v_mov_b32_e32 v10, v0
	v_mov_b32_e32 v11, v0
	v_mov_b32_e32 v12, v0
	v_mov_b32_e32 v13, v0
	v_mov_b32_e32 v14, v0
	v_mov_b32_e32 v15, v0
	v_mov_b32_e32 v24, v0
	v_mov_b32_e32 v25, v0
	v_mov_b32_e32 v26, v0
	v_mov_b32_e32 v27, v0
	v_mov_b32_e32 v28, v0
	v_mov_b32_e32 v29, v0
	v_mov_b32_e32 v30, v0
	v_mov_b32_e32 v31, v0
	v_mov_b32_e32 v40, v0
	v_mov_b32_e32 v41, v0
	v_mov_b32_e32 v42, v0
	v_mov_b32_e32 v43, v0
	v_mov_b32_e32 v44, v0
	v_mov_b32_e32 v45, v0
	v_mov_b32_e32 v46, v0
	v_mov_b32_e32 v47, v0
	v_mov_b32_e32 v56, v0
	v_mov_b32_e32 v57, v0
	v_mov_b32_e32 v58, v0
	v_mov_b32_e32 v59, v0
	v_mov_b32_e32 v60, v0
	v_mov_b32_e32 v61, v0
	v_mov_b32_e32 v62, v0
	v_mov_b32_e32 v63, v0
	v_mov_b32_e32 v64, v0
	v_mov_b32_e32 v65, v0
	v_mov_b32_e32 v66, v0
	v_mov_b32_e32 v67, v0
	v_mov_b32_e32 v68, v0
	v_mov_b32_e32 v69, v0
	v_mov_b32_e32 v70, v0
	v_mov_b32_e32 v71, v0
	v_mov_b32_e32 v80, v0
	v_mov_b32_e32 v81, v0
	v_mov_b32_e32 v82, v0
	v_mov_b32_e32 v83, v0
	v_mov_b32_e32 v84, v0
	v_mov_b32_e32 v85, v0
	v_mov_b32_e32 v86, v0
	v_mov_b32_e32 v87, v0
	v_mov_b32_e32 v96, v0
	v_mov_b32_e32 v97, v0
	v_mov_b32_e32 v98, v0
	v_mov_b32_e32 v99, v0
	v_mov_b32_e32 v100, v0
	v_mov_b32_e32 v101, v0
	v_mov_b32_e32 v102, v0
	v_mov_b32_e32 v103, v0
	v_mov_b32_e32 v112, v0
	v_mov_b32_e32 v113, v0
	v_mov_b32_e32 v114, v0
	v_mov_b32_e32 v115, v0
	v_mov_b32_e32 v116, v0
	v_mov_b32_e32 v117, v0
	v_mov_b32_e32 v118, v0
	v_mov_b32_e32 v119, v0
	v_mov_b32_e32 v72, v0
	v_mov_b32_e32 v73, v0
	v_mov_b32_e32 v74, v0
	v_mov_b32_e32 v75, v0
	v_mov_b32_e32 v76, v0
	v_mov_b32_e32 v77, v0
	v_mov_b32_e32 v78, v0
	v_mov_b32_e32 v79, v0
	v_mov_b32_e32 v88, v0
	v_mov_b32_e32 v89, v0
	v_mov_b32_e32 v90, v0
	v_mov_b32_e32 v91, v0
	v_mov_b32_e32 v92, v0
	v_mov_b32_e32 v93, v0
	v_mov_b32_e32 v94, v0
	v_mov_b32_e32 v95, v0
	v_mov_b32_e32 v104, v0
	v_mov_b32_e32 v105, v0
	v_mov_b32_e32 v106, v0
	v_mov_b32_e32 v107, v0
	v_mov_b32_e32 v108, v0
	v_mov_b32_e32 v109, v0
	v_mov_b32_e32 v110, v0
	v_mov_b32_e32 v111, v0
	v_mov_b32_e32 v120, v0
	v_mov_b32_e32 v121, v0
	v_mov_b32_e32 v122, v0
	v_mov_b32_e32 v123, v0
	v_mov_b32_e32 v124, v0
	v_mov_b32_e32 v125, v0
	v_mov_b32_e32 v126, v0
	v_mov_b32_e32 v127, v0
	s_cmp_ge_u32 s33, 0x1000
	s_cbranch_scc1 .Lsprio_10
	s_setprio 1
.Lsprio_10:
.LBB0_115:
	ds_read_b128 v[150:153], v158
	ds_read_b128 v[162:165], v158 offset:1024
	ds_read_b128 v[166:169], v158 offset:2048
	ds_read_b128 v[170:173], v158 offset:3072
	ds_read_b128 v[174:177], v159
	ds_read_b128 v[178:181], v159 offset:1024
	ds_read_b128 v[182:185], v159 offset:2048
	ds_read_b128 v[186:189], v159 offset:3072
	s_add_u32 s68, s34, 0xfff00080
	s_addc_u32 s69, s35, -1
	s_cmp_eq_u32 s67, 60
	s_cselect_b32 s87, s21, s69
	s_cselect_b32 s86, s27, s68
	s_cselect_b32 s85, s19, s66
	s_cselect_b32 s84, s31, s65
	s_add_i32 m0, s53, 0xc000
	ds_read_b128 v[190:193], v160
	ds_read_b128 v[194:197], v160 offset:1024
	ds_read_b128 v[198:201], v160 offset:2048
	ds_read_b128 v[202:205], v160 offset:3072
	ds_read_b128 v[206:209], v160 offset:4096
	ds_read_b128 v[210:213], v160 offset:5120
	ds_read_b128 v[214:217], v160 offset:6144
	ds_read_b128 v[218:221], v160 offset:7168
	global_load_lds_dwordx4 v140, s[34:35]
	s_add_i32 m0, s53, 0xe000
	s_nop 0
	global_load_lds_dwordx4 v142, s[34:35]
	s_waitcnt vmcnt(8)
	s_waitcnt lgkmcnt(0)
	s_barrier
; #define PG8_STAGE(bufoff, gbase, voff) do { _Pragma("unroll") for (int _i = 0; _i < 2; ++_i) \
;         __builtin_amdgcn_global_load_lds((const unsigned*)((const char*)(gbase) + (voff)[_i]), (PG8_LAS unsigned*)(lds + (bufoff) + ldsw + _i * 8192), 16, 0, 0); } while (0)
; #define PG8_LDA(dst, b, h) do { _Pragma("unroll") for (int m = 0; m < 4; ++m) _Pragma("unroll") for (int k = 0; k < 2; ++k) dst[m][k] = *(const PG8_LAS bf16x8*)(lds + PG8_SA(b, h) + aoff + m * 2048 + k * 1024); } while (0)
; #define PG8_MMA(ai, bj, At, Bt) do { __builtin_amdgcn_s_setprio(1); _Pragma("unroll") for (int m = 0; m < 4; ++m) _Pragma("unroll") for (int n = 0; n < 2; ++n) _Pragma("unroll") for (int k = 0; k < 2; ++k) \
;         acc[ai][bj][m][n] = __builtin_amdgcn_mfma_f32_16x16x32_bf16(Bt[n][k], At[m][k], acc[ai][bj][m][n], 0, 0, 0); __builtin_amdgcn_s_setprio(0); } while (0)
; #define PG8_WAIT_V(n) asm volatile("s_waitcnt vmcnt(" #n ")" ::: "memory")
; #define PG8_WAIT_L(n) asm volatile("s_waitcnt lgkmcnt(" #n ")" ::: "memory")
; #define PG8_BAR __builtin_amdgcn_s_barrier()
; #define PG8_SCHED __builtin_amdgcn_sched_barrier(0)
; template <class Epi, class Sched, bool ALIGN_EPI = false, bool SP2 = false>
; __device__ __forceinline__ void gemm_phase(PG8_LAS unsigned char* lds, const Gemm g, const Sched& S, const Epi& E) {
;     ...
;             PG8_WAIT_V(8); PG8_WAIT_L(0); PG8_BAR; PG8_MMA(0, 0, At, B0); PG8_MMA(0, 1, At, B1); PG8_BAR; PG8_SCHED;
;             PG8_LDA(At, 0, 1); PG8_STAGE(PG8_SB(0, 0), b2, voffB); PG8_STAGE(PG8_SB(0, 1), b2 + hstep, voffB); PG8_STAGE(PG8_SA(0, 0), a2, voffA);
;             PG8_WAIT_V(8); PG8_WAIT_L(0); PG8_BAR; PG8_MMA(1, 0, At, B0); PG8_MMA(1, 1, At, B1); PG8_BAR; PG8_SCHED;
	v_mfma_f32_16x16x32_bf16 v[124:127], v[150:153], v[190:193], v[124:127]
	v_mfma_f32_16x16x32_bf16 v[120:123], v[166:169], v[190:193], v[120:123]
	v_mfma_f32_16x16x32_bf16 v[108:111], v[150:153], v[198:201], v[108:111]
	v_mfma_f32_16x16x32_bf16 v[104:107], v[166:169], v[198:201], v[104:107]
	v_mfma_f32_16x16x32_bf16 v[92:95], v[150:153], v[206:209], v[92:95]
	v_mfma_f32_16x16x32_bf16 v[88:91], v[166:169], v[206:209], v[88:91]
	v_mfma_f32_16x16x32_bf16 v[76:79], v[150:153], v[214:217], v[76:79]
	v_mfma_f32_16x16x32_bf16 v[72:75], v[166:169], v[214:217], v[72:75]
	v_mfma_f32_16x16x32_bf16 v[124:127], v[162:165], v[194:197], v[124:127]
	v_mfma_f32_16x16x32_bf16 v[120:123], v[170:173], v[194:197], v[120:123]
	v_mfma_f32_16x16x32_bf16 v[108:111], v[162:165], v[202:205], v[108:111]
	v_mfma_f32_16x16x32_bf16 v[104:107], v[170:173], v[202:205], v[104:107]
	v_mfma_f32_16x16x32_bf16 v[92:95], v[162:165], v[210:213], v[92:95]
	v_mfma_f32_16x16x32_bf16 v[88:91], v[170:173], v[210:213], v[88:91]
	v_mfma_f32_16x16x32_bf16 v[76:79], v[162:165], v[218:221], v[76:79]
	v_mfma_f32_16x16x32_bf16 v[72:75], v[170:173], v[218:221], v[72:75]
	v_mfma_f32_16x16x32_bf16 v[116:119], v[174:177], v[190:193], v[116:119]
	v_mfma_f32_16x16x32_bf16 v[112:115], v[182:185], v[190:193], v[112:115]
	v_mfma_f32_16x16x32_bf16 v[100:103], v[174:177], v[198:201], v[100:103]
	v_mfma_f32_16x16x32_bf16 v[96:99], v[182:185], v[198:201], v[96:99]
	v_mfma_f32_16x16x32_bf16 v[84:87], v[174:177], v[206:209], v[84:87]
	v_mfma_f32_16x16x32_bf16 v[80:83], v[182:185], v[206:209], v[80:83]
	v_mfma_f32_16x16x32_bf16 v[68:71], v[174:177], v[214:217], v[68:71]
	v_mfma_f32_16x16x32_bf16 v[64:67], v[182:185], v[214:217], v[64:67]
	v_mfma_f32_16x16x32_bf16 v[116:119], v[178:181], v[194:197], v[116:119]
	v_mfma_f32_16x16x32_bf16 v[112:115], v[186:189], v[194:197], v[112:115]
	v_mfma_f32_16x16x32_bf16 v[100:103], v[178:181], v[202:205], v[100:103]
	v_mfma_f32_16x16x32_bf16 v[96:99], v[186:189], v[202:205], v[96:99]
	v_mfma_f32_16x16x32_bf16 v[84:87], v[178:181], v[210:213], v[84:87]
	v_mfma_f32_16x16x32_bf16 v[80:83], v[186:189], v[210:213], v[80:83]
	v_mfma_f32_16x16x32_bf16 v[68:71], v[178:181], v[218:221], v[68:71]
	v_mfma_f32_16x16x32_bf16 v[64:67], v[186:189], v[218:221], v[64:67]
	s_barrier
	s_add_u32 s98, s84, s12
	s_addc_u32 s99, s85, s13
	s_add_u32 s100, s86, s12
	s_addc_u32 s101, s87, s13
	s_add_i32 s68, s62, s33
	s_mov_b32 m0, s68
	ds_read_b128 v[190:193], v160 offset:16384
	ds_read_b128 v[194:197], v160 offset:17408
	ds_read_b128 v[198:201], v160 offset:18432
	ds_read_b128 v[202:205], v160 offset:19456
	ds_read_b128 v[206:209], v160 offset:20480
	ds_read_b128 v[210:213], v160 offset:21504
	ds_read_b128 v[214:217], v160 offset:22528
	ds_read_b128 v[218:221], v160 offset:23552
	global_load_lds_dwordx4 v132, s[84:85]
	s_add_i32 m0, s68, 0x2000
	s_add_u32 s68, s84, 0x100000
	s_addc_u32 s69, s85, 0
	s_add_i32 s70, s63, s33
	global_load_lds_dwordx4 v128, s[84:85]
	s_mov_b32 m0, s70
	s_nop 0
	global_load_lds_dwordx4 v132, s[68:69]
	s_add_i32 m0, s70, 0x2000
	s_nop 0
	global_load_lds_dwordx4 v128, s[68:69]
	s_mov_b32 m0, s53
	s_nop 0
	global_load_lds_dwordx4 v134, s[86:87]
	s_mov_b32 m0, s54
	s_nop 0
	global_load_lds_dwordx4 v130, s[86:87]
	s_waitcnt vmcnt(8)
	s_waitcnt lgkmcnt(0)
	s_barrier
	v_mfma_f32_16x16x32_bf16 v[60:63], v[150:153], v[190:193], v[60:63]
	v_mfma_f32_16x16x32_bf16 v[56:59], v[166:169], v[190:193], v[56:59]
	v_mfma_f32_16x16x32_bf16 v[44:47], v[150:153], v[198:201], v[44:47]
	v_mfma_f32_16x16x32_bf16 v[40:43], v[166:169], v[198:201], v[40:43]
	v_mfma_f32_16x16x32_bf16 v[28:31], v[150:153], v[206:209], v[28:31]
	v_mfma_f32_16x16x32_bf16 v[24:27], v[166:169], v[206:209], v[24:27]
	v_mfma_f32_16x16x32_bf16 v[12:15], v[150:153], v[214:217], v[12:15]
	v_mfma_f32_16x16x32_bf16 v[8:11], v[166:169], v[214:217], v[8:11]
	v_mfma_f32_16x16x32_bf16 v[60:63], v[162:165], v[194:197], v[60:63]
	v_mfma_f32_16x16x32_bf16 v[56:59], v[170:173], v[194:197], v[56:59]
	v_mfma_f32_16x16x32_bf16 v[44:47], v[162:165], v[202:205], v[44:47]
	v_mfma_f32_16x16x32_bf16 v[40:43], v[170:173], v[202:205], v[40:43]
	v_mfma_f32_16x16x32_bf16 v[28:31], v[162:165], v[210:213], v[28:31]
	v_mfma_f32_16x16x32_bf16 v[24:27], v[170:173], v[210:213], v[24:27]
	v_mfma_f32_16x16x32_bf16 v[12:15], v[162:165], v[218:221], v[12:15]
	v_mfma_f32_16x16x32_bf16 v[8:11], v[170:173], v[218:221], v[8:11]
	v_mfma_f32_16x16x32_bf16 v[52:55], v[174:177], v[190:193], v[52:55]
	v_mfma_f32_16x16x32_bf16 v[48:51], v[182:185], v[190:193], v[48:51]
	v_mfma_f32_16x16x32_bf16 v[36:39], v[174:177], v[198:201], v[36:39]
	v_mfma_f32_16x16x32_bf16 v[32:35], v[182:185], v[198:201], v[32:35]
	v_mfma_f32_16x16x32_bf16 v[20:23], v[174:177], v[206:209], v[20:23]
	v_mfma_f32_16x16x32_bf16 v[16:19], v[182:185], v[206:209], v[16:19]
	v_mfma_f32_16x16x32_bf16 v[4:7], v[174:177], v[214:217], v[4:7]
	v_mfma_f32_16x16x32_bf16 v[0:3], v[182:185], v[214:217], v[0:3]
	v_mfma_f32_16x16x32_bf16 v[52:55], v[178:181], v[194:197], v[52:55]
	v_mfma_f32_16x16x32_bf16 v[48:51], v[186:189], v[194:197], v[48:51]
	v_mfma_f32_16x16x32_bf16 v[36:39], v[178:181], v[202:205], v[36:39]
	v_mfma_f32_16x16x32_bf16 v[32:35], v[186:189], v[202:205], v[32:35]
	v_mfma_f32_16x16x32_bf16 v[20:23], v[178:181], v[210:213], v[20:23]
	v_mfma_f32_16x16x32_bf16 v[16:19], v[186:189], v[210:213], v[16:19]
	v_mfma_f32_16x16x32_bf16 v[4:7], v[178:181], v[218:221], v[4:7]
	v_mfma_f32_16x16x32_bf16 v[0:3], v[186:189], v[218:221], v[0:3]
	s_barrier
; #define PG8_STAGE(bufoff, gbase, voff) do { _Pragma("unroll") for (int _i = 0; _i < 2; ++_i) \
;         __builtin_amdgcn_global_load_lds((const unsigned*)((const char*)(gbase) + (voff)[_i]), (PG8_LAS unsigned*)(lds + (bufoff) + ldsw + _i * 8192), 16, 0, 0); } while (0)
; #define PG8_LDA(dst, b, h) do { _Pragma("unroll") for (int m = 0; m < 4; ++m) _Pragma("unroll") for (int k = 0; k < 2; ++k) dst[m][k] = *(const PG8_LAS bf16x8*)(lds + PG8_SA(b, h) + aoff + m * 2048 + k * 1024); } while (0)
; #define PG8_LDB(dst, b, h) do { _Pragma("unroll") for (int n = 0; n < 2; ++n) _Pragma("unroll") for (int k = 0; k < 2; ++k) dst[n][k] = *(const PG8_LAS bf16x8*)(lds + PG8_SB(b, h) + boff + n * 2048 + k * 1024); } while (0)
; #define PG8_MMA(ai, bj, At, Bt) do { __builtin_amdgcn_s_setprio(1); _Pragma("unroll") for (int m = 0; m < 4; ++m) _Pragma("unroll") for (int n = 0; n < 2; ++n) _Pragma("unroll") for (int k = 0; k < 2; ++k) \
;         acc[ai][bj][m][n] = __builtin_amdgcn_mfma_f32_16x16x32_bf16(Bt[n][k], At[m][k], acc[ai][bj][m][n], 0, 0, 0); __builtin_amdgcn_s_setprio(0); } while (0)
; #define PG8_WAIT_V(n) asm volatile("s_waitcnt vmcnt(" #n ")" ::: "memory")
; #define PG8_WAIT_L(n) asm volatile("s_waitcnt lgkmcnt(" #n ")" ::: "memory")
; #define PG8_BAR __builtin_amdgcn_s_barrier()
; #define PG8_SCHED __builtin_amdgcn_sched_barrier(0)
; template <class Epi, class Sched, bool ALIGN_EPI = false, bool SP2 = false>
; __device__ __forceinline__ void gemm_phase(PG8_LAS unsigned char* lds, const Gemm g, const Sched& S, const Epi& E) {
;     ...
;             PG8_LDB(B0, 1, 0); PG8_LDB(B1, 1, 1); PG8_SCHED; PG8_LDA(At, 1, 0); PG8_STAGE(PG8_SA(0, 1), a2 + hstepA, voffA);
;             PG8_WAIT_V(8); PG8_WAIT_L(0); PG8_BAR; PG8_MMA(0, 0, At, B0); PG8_MMA(0, 1, At, B1); PG8_BAR; PG8_SCHED;
;             PG8_LDA(At, 1, 1); PG8_STAGE(PG8_SB(1, 0), b3, voffB); PG8_STAGE(PG8_SB(1, 1), b3 + hstep, voffB); PG8_STAGE(PG8_SA(1, 0), a3, voffA);
;             PG8_WAIT_V(8); PG8_WAIT_L(0); PG8_BAR; PG8_MMA(1, 0, At, B0); PG8_MMA(1, 1, At, B1); PG8_BAR; PG8_SCHED;
;     ...
;         if constexpr (ALIGN_EPI) { if (wr == 0) PG8_BAR; }
	s_add_i32 s70, 0, 0x18000
	v_add_u32_e32 v136, s70, v157
	s_add_i32 s71, 0, 0x1c000
	ds_read_b128 v[150:153], v136
	ds_read_b128 v[162:165], v136 offset:1024
	ds_read_b128 v[166:169], v136 offset:2048
	ds_read_b128 v[170:173], v136 offset:3072
	v_add_u32_e32 v136, s71, v157
	ds_read_b128 v[174:177], v136
	ds_read_b128 v[178:181], v136 offset:1024
	ds_read_b128 v[182:185], v136 offset:2048
	ds_read_b128 v[186:189], v136 offset:3072
	s_add_u32 s68, s86, 0x100000
	s_addc_u32 s69, s87, 0
	s_mov_b32 m0, s55
	ds_read_b128 v[190:193], v160 offset:32768
	ds_read_b128 v[194:197], v160 offset:33792
	ds_read_b128 v[198:201], v160 offset:34816
	ds_read_b128 v[202:205], v160 offset:35840
	ds_read_b128 v[206:209], v160 offset:36864
	ds_read_b128 v[210:213], v160 offset:37888
	ds_read_b128 v[214:217], v160 offset:38912
	ds_read_b128 v[218:221], v160 offset:39936
	global_load_lds_dwordx4 v134, s[68:69]
	s_mov_b32 m0, s56
	s_nop 0
	global_load_lds_dwordx4 v130, s[68:69]
	s_waitcnt vmcnt(8)
	s_waitcnt lgkmcnt(0)
	s_barrier
	v_mfma_f32_16x16x32_bf16 v[124:127], v[150:153], v[190:193], v[124:127]
	v_mfma_f32_16x16x32_bf16 v[120:123], v[166:169], v[190:193], v[120:123]
	v_mfma_f32_16x16x32_bf16 v[108:111], v[150:153], v[198:201], v[108:111]
	v_mfma_f32_16x16x32_bf16 v[104:107], v[166:169], v[198:201], v[104:107]
	v_mfma_f32_16x16x32_bf16 v[92:95], v[150:153], v[206:209], v[92:95]
	v_mfma_f32_16x16x32_bf16 v[88:91], v[166:169], v[206:209], v[88:91]
	v_mfma_f32_16x16x32_bf16 v[76:79], v[150:153], v[214:217], v[76:79]
	v_mfma_f32_16x16x32_bf16 v[72:75], v[166:169], v[214:217], v[72:75]
	v_mfma_f32_16x16x32_bf16 v[124:127], v[162:165], v[194:197], v[124:127]
	v_mfma_f32_16x16x32_bf16 v[120:123], v[170:173], v[194:197], v[120:123]
	v_mfma_f32_16x16x32_bf16 v[108:111], v[162:165], v[202:205], v[108:111]
	v_mfma_f32_16x16x32_bf16 v[104:107], v[170:173], v[202:205], v[104:107]
	v_mfma_f32_16x16x32_bf16 v[92:95], v[162:165], v[210:213], v[92:95]
	v_mfma_f32_16x16x32_bf16 v[88:91], v[170:173], v[210:213], v[88:91]
	v_mfma_f32_16x16x32_bf16 v[76:79], v[162:165], v[218:221], v[76:79]
	v_mfma_f32_16x16x32_bf16 v[72:75], v[170:173], v[218:221], v[72:75]
	v_mfma_f32_16x16x32_bf16 v[116:119], v[174:177], v[190:193], v[116:119]
	v_mfma_f32_16x16x32_bf16 v[112:115], v[182:185], v[190:193], v[112:115]
	v_mfma_f32_16x16x32_bf16 v[100:103], v[174:177], v[198:201], v[100:103]
	v_mfma_f32_16x16x32_bf16 v[96:99], v[182:185], v[198:201], v[96:99]
	v_mfma_f32_16x16x32_bf16 v[84:87], v[174:177], v[206:209], v[84:87]
	v_mfma_f32_16x16x32_bf16 v[80:83], v[182:185], v[206:209], v[80:83]
	v_mfma_f32_16x16x32_bf16 v[68:71], v[174:177], v[214:217], v[68:71]
	v_mfma_f32_16x16x32_bf16 v[64:67], v[182:185], v[214:217], v[64:67]
	v_mfma_f32_16x16x32_bf16 v[116:119], v[178:181], v[194:197], v[116:119]
	v_mfma_f32_16x16x32_bf16 v[112:115], v[186:189], v[194:197], v[112:115]
	v_mfma_f32_16x16x32_bf16 v[100:103], v[178:181], v[202:205], v[100:103]
	v_mfma_f32_16x16x32_bf16 v[96:99], v[186:189], v[202:205], v[96:99]
	v_mfma_f32_16x16x32_bf16 v[84:87], v[178:181], v[210:213], v[84:87]
	v_mfma_f32_16x16x32_bf16 v[80:83], v[186:189], v[210:213], v[80:83]
	v_mfma_f32_16x16x32_bf16 v[68:71], v[178:181], v[218:221], v[68:71]
	v_mfma_f32_16x16x32_bf16 v[64:67], v[186:189], v[218:221], v[64:67]
	s_barrier
	s_add_i32 s68, s70, s33
	s_mov_b32 m0, s68
	ds_read_b128 v[190:193], v160 offset:49152
	ds_read_b128 v[194:197], v160 offset:50176
	ds_read_b128 v[198:201], v160 offset:51200
	ds_read_b128 v[202:205], v160 offset:52224
	ds_read_b128 v[206:209], v160 offset:53248
	ds_read_b128 v[210:213], v160 offset:54272
	ds_read_b128 v[214:217], v160 offset:55296
	ds_read_b128 v[218:221], v160 offset:56320
	global_load_lds_dwordx4 v132, s[98:99]
	s_add_i32 m0, s68, 0x2000
	s_add_u32 s68, s84, 0x100080
	s_addc_u32 s69, s85, 0
	s_add_i32 s70, s71, s33
	global_load_lds_dwordx4 v128, s[98:99]
	s_mov_b32 m0, s70
	s_nop 0
	global_load_lds_dwordx4 v132, s[68:69]
	s_add_i32 m0, s70, 0x2000
	s_nop 0
	global_load_lds_dwordx4 v128, s[68:69]
	s_mov_b32 m0, s60
	s_nop 0
	global_load_lds_dwordx4 v134, s[100:101]
	s_mov_b32 m0, s61
	s_nop 0
	global_load_lds_dwordx4 v130, s[100:101]
	s_waitcnt vmcnt(8)
	s_waitcnt lgkmcnt(0)
	s_barrier
	v_mfma_f32_16x16x32_bf16 v[60:63], v[150:153], v[190:193], v[60:63]
	v_mfma_f32_16x16x32_bf16 v[56:59], v[166:169], v[190:193], v[56:59]
	v_mfma_f32_16x16x32_bf16 v[44:47], v[150:153], v[198:201], v[44:47]
	v_mfma_f32_16x16x32_bf16 v[40:43], v[166:169], v[198:201], v[40:43]
	v_mfma_f32_16x16x32_bf16 v[28:31], v[150:153], v[206:209], v[28:31]
	v_mfma_f32_16x16x32_bf16 v[24:27], v[166:169], v[206:209], v[24:27]
	v_mfma_f32_16x16x32_bf16 v[12:15], v[150:153], v[214:217], v[12:15]
	v_mfma_f32_16x16x32_bf16 v[8:11], v[166:169], v[214:217], v[8:11]
	v_mfma_f32_16x16x32_bf16 v[60:63], v[162:165], v[194:197], v[60:63]
	v_mfma_f32_16x16x32_bf16 v[56:59], v[170:173], v[194:197], v[56:59]
	v_mfma_f32_16x16x32_bf16 v[44:47], v[162:165], v[202:205], v[44:47]
	v_mfma_f32_16x16x32_bf16 v[40:43], v[170:173], v[202:205], v[40:43]
	v_mfma_f32_16x16x32_bf16 v[28:31], v[162:165], v[210:213], v[28:31]
	v_mfma_f32_16x16x32_bf16 v[24:27], v[170:173], v[210:213], v[24:27]
	v_mfma_f32_16x16x32_bf16 v[12:15], v[162:165], v[218:221], v[12:15]
	v_mfma_f32_16x16x32_bf16 v[8:11], v[170:173], v[218:221], v[8:11]
	v_mfma_f32_16x16x32_bf16 v[52:55], v[174:177], v[190:193], v[52:55]
	v_mfma_f32_16x16x32_bf16 v[48:51], v[182:185], v[190:193], v[48:51]
	v_mfma_f32_16x16x32_bf16 v[36:39], v[174:177], v[198:201], v[36:39]
	v_mfma_f32_16x16x32_bf16 v[32:35], v[182:185], v[198:201], v[32:35]
	v_mfma_f32_16x16x32_bf16 v[20:23], v[174:177], v[206:209], v[20:23]
	v_mfma_f32_16x16x32_bf16 v[16:19], v[182:185], v[206:209], v[16:19]
	v_mfma_f32_16x16x32_bf16 v[4:7], v[174:177], v[214:217], v[4:7]
	v_mfma_f32_16x16x32_bf16 v[0:3], v[182:185], v[214:217], v[0:3]
	v_mfma_f32_16x16x32_bf16 v[52:55], v[178:181], v[194:197], v[52:55]
	v_mfma_f32_16x16x32_bf16 v[48:51], v[186:189], v[194:197], v[48:51]
	v_mfma_f32_16x16x32_bf16 v[36:39], v[178:181], v[202:205], v[36:39]
	v_mfma_f32_16x16x32_bf16 v[32:35], v[186:189], v[202:205], v[32:35]
	v_mfma_f32_16x16x32_bf16 v[20:23], v[178:181], v[210:213], v[20:23]
	v_mfma_f32_16x16x32_bf16 v[16:19], v[186:189], v[210:213], v[16:19]
	v_mfma_f32_16x16x32_bf16 v[4:7], v[178:181], v[218:221], v[4:7]
	v_mfma_f32_16x16x32_bf16 v[0:3], v[186:189], v[218:221], v[0:3]
	s_barrier
	s_add_i32 s67, s67, 2
	s_add_u32 s34, s34, 0x100
	s_addc_u32 s35, s35, 0
	s_add_u32 s65, s65, 0x100
	s_addc_u32 s66, s66, 0
	s_cmp_gt_u32 s67, 61
	s_cbranch_scc0 .LBB0_115
	s_setprio 0
	s_and_b64 vcc, exec, s[14:15]
	s_cbranch_vccz .LBB0_118
	s_barrier

; #define PG8_STAGE(bufoff, gbase, voff) do { _Pragma("unroll") for (int _i = 0; _i < 2; ++_i) \
;         __builtin_amdgcn_global_load_lds((const unsigned*)((const char*)(gbase) + (voff)[_i]), (PG8_LAS unsigned*)(lds + (bufoff) + ldsw + _i * 8192), 16, 0, 0); } while (0)
; #define PG8_LDA(dst, b, h) do { _Pragma("unroll") for (int m = 0; m < 4; ++m) _Pragma("unroll") for (int k = 0; k < 2; ++k) dst[m][k] = *(const PG8_LAS bf16x8*)(lds + PG8_SA(b, h) + aoff + m * 2048 + k * 1024); } while (0)
; #define PG8_LDB(dst, b, h) do { _Pragma("unroll") for (int n = 0; n < 2; ++n) _Pragma("unroll") for (int k = 0; k < 2; ++k) dst[n][k] = *(const PG8_LAS bf16x8*)(lds + PG8_SB(b, h) + boff + n * 2048 + k * 1024); } while (0)
; #define PG8_WAIT_V(n) asm volatile("s_waitcnt vmcnt(" #n ")" ::: "memory")
; #define PG8_WAIT_L(n) asm volatile("s_waitcnt lgkmcnt(" #n ")" ::: "memory")
; #define PG8_BAR __builtin_amdgcn_s_barrier()
; #define PG8_SCHED __builtin_amdgcn_sched_barrier(0)
; template <class Epi, class Sched, bool ALIGN_EPI = false, bool SP2 = false>
; __device__ __forceinline__ void gemm_phase(PG8_LAS unsigned char* lds, const Gemm g, const Sched& S, const Epi& E) {
;     ...
;     for (;;) {
;         const bool has_next = S.next(ui + 1, nxt);
;         const char* nA = has_next ? (const char*)g.A + (size_t)nxt.pm * tstep : cA; const char* nB = has_next ? (const char*)g.Bt + (size_t)nxt.pn * tstep : cB;
;         for (int t = 0; t < nt; t += 2) {
;             const bool last = (t == nt - 2);
;             const char* a1 = cA + (size_t)(t + 1) * kstepA;
;             const char* a2 = last ? nA : cA + (size_t)(t + 2) * kstepA; const char* b2 = last ? nB : cB + (size_t)(t + 2) * kstep;
;             const char* a3 = a2 + kstepA; const char* b3 = b2 + kstep;
;             if (last && has_next) S.a_ready(nxt);
;             if constexpr (SP2) {
;             PG8_LDB(B0, 0, 0); PG8_LDB(B1, 0, 1); PG8_SCHED; PG8_LDA(At, 0, 0); PG8_STAGE(PG8_SA(1, 1), a1 + hstepA, voffA);
;             PG8_WAIT_V(8); PG8_WAIT_L(0); PG8_BAR; PG8_MMA(0, 0, At, B0); PG8_MMA(0, 1, At, B1); PG8_BAR; PG8_SCHED;
;     ...
;         for (int a = 0; a < 2; ++a)
; #pragma unroll
;             for (int b = 0; b < 2; ++b)
; #pragma unroll
;                 for (int m = 0; m < 4; ++m)
; #pragma unroll
;                     for (int n = 0; n < 2; ++n) acc[a][b][m][n] = (f32x4){0.f, 0.f, 0.f, 0.f};
.LBB0_1197:
	s_ashr_i32 s21, s20, 31
	s_lshl_b64 s[22:23], s[20:21], 21
	s_add_u32 s22, s3, s22
	s_addc_u32 s23, s29, s23
	s_and_b64 s[24:25], s[4:5], exec
	s_cselect_b32 s21, s23, s35
	s_cselect_b32 s27, s22, s34
	s_ashr_i32 s19, s18, 31
	s_lshl_b64 s[24:25], s[18:19], 21
	s_add_u32 s24, s10, s24
	s_addc_u32 s25, s11, s25
	s_and_b64 s[40:41], s[4:5], exec
	s_cselect_b32 s19, s25, s39
	s_cselect_b32 s62, s24, s38
	s_add_u32 s34, s34, 0x100080
	s_addc_u32 s35, s35, 0
	s_add_u32 s63, s38, 0x100
	v_mov_b32_e32 v0, 0
	s_addc_u32 s64, s39, 0
	s_mov_b32 s65, -2
	s_waitcnt lgkmcnt(0)
	v_mov_b32_e32 v1, v0
	v_mov_b32_e32 v2, v0
	v_mov_b32_e32 v3, v0
	v_mov_b32_e32 v4, v0
	v_mov_b32_e32 v5, v0
	v_mov_b32_e32 v6, v0
	v_mov_b32_e32 v7, v0
	v_mov_b32_e32 v16, v0
	v_mov_b32_e32 v17, v0
	v_mov_b32_e32 v18, v0
	v_mov_b32_e32 v19, v0
	v_mov_b32_e32 v20, v0
	v_mov_b32_e32 v21, v0
	v_mov_b32_e32 v22, v0
	v_mov_b32_e32 v23, v0
	v_mov_b32_e32 v32, v0
	v_mov_b32_e32 v33, v0
	v_mov_b32_e32 v34, v0
	v_mov_b32_e32 v35, v0
	s_waitcnt vmcnt(0)
	v_mov_b32_e32 v36, v0
	v_mov_b32_e32 v37, v0
	v_mov_b32_e32 v38, v0
	v_mov_b32_e32 v39, v0
	v_mov_b32_e32 v56, v0
	v_mov_b32_e32 v57, v0
	v_mov_b32_e32 v58, v0
	v_mov_b32_e32 v59, v0
	v_mov_b32_e32 v60, v0
	v_mov_b32_e32 v61, v0
	v_mov_b32_e32 v62, v0
	v_mov_b32_e32 v63, v0
	v_mov_b32_e32 v8, v0
	v_mov_b32_e32 v9, v0
	v_mov_b32_e32 v10, v0
	v_mov_b32_e32 v11, v0
	v_mov_b32_e32 v12, v0
	v_mov_b32_e32 v13, v0
	v_mov_b32_e32 v14, v0
	v_mov_b32_e32 v15, v0
	v_mov_b32_e32 v24, v0
	v_mov_b32_e32 v25, v0
	v_mov_b32_e32 v26, v0
	v_mov_b32_e32 v27, v0
	v_mov_b32_e32 v28, v0
	v_mov_b32_e32 v29, v0
	v_mov_b32_e32 v30, v0
	v_mov_b32_e32 v31, v0
	v_mov_b32_e32 v40, v0
	v_mov_b32_e32 v41, v0
	v_mov_b32_e32 v42, v0
	v_mov_b32_e32 v43, v0
	v_mov_b32_e32 v44, v0
	v_mov_b32_e32 v45, v0
	v_mov_b32_e32 v46, v0
	v_mov_b32_e32 v47, v0
	v_mov_b32_e32 v68, v0
	v_mov_b32_e32 v69, v0
	v_mov_b32_e32 v70, v0
	v_mov_b32_e32 v71, v0
	v_mov_b32_e32 v72, v0
	v_mov_b32_e32 v73, v0
	v_mov_b32_e32 v74, v0
	v_mov_b32_e32 v75, v0
	v_mov_b32_e32 v84, v0
	v_mov_b32_e32 v85, v0
	v_mov_b32_e32 v86, v0
	v_mov_b32_e32 v87, v0
	v_mov_b32_e32 v88, v0
	v_mov_b32_e32 v89, v0
	v_mov_b32_e32 v90, v0
	v_mov_b32_e32 v91, v0
	v_mov_b32_e32 v76, v0
	v_mov_b32_e32 v77, v0
	v_mov_b32_e32 v78, v0
	v_mov_b32_e32 v79, v0
	v_mov_b32_e32 v96, v0
	v_mov_b32_e32 v97, v0
	v_mov_b32_e32 v98, v0
	v_mov_b32_e32 v99, v0
	v_mov_b32_e32 v52, v0
	v_mov_b32_e32 v53, v0
	v_mov_b32_e32 v54, v0
	v_mov_b32_e32 v55, v0
	v_mov_b32_e32 v104, v0
	v_mov_b32_e32 v105, v0
	v_mov_b32_e32 v106, v0
	v_mov_b32_e32 v107, v0
	v_mov_b32_e32 v112, v0
	v_mov_b32_e32 v113, v0
	v_mov_b32_e32 v114, v0
	v_mov_b32_e32 v115, v0
	v_mov_b32_e32 v116, v0
	v_mov_b32_e32 v117, v0
	v_mov_b32_e32 v118, v0
	v_mov_b32_e32 v119, v0
	v_mov_b32_e32 v80, v0
	v_mov_b32_e32 v81, v0
	v_mov_b32_e32 v82, v0
	v_mov_b32_e32 v83, v0
	v_mov_b32_e32 v92, v0
	v_mov_b32_e32 v93, v0
	v_mov_b32_e32 v94, v0
	v_mov_b32_e32 v95, v0
	v_mov_b32_e32 v64, v0
	v_mov_b32_e32 v65, v0
	v_mov_b32_e32 v66, v0
	v_mov_b32_e32 v67, v0
	v_mov_b32_e32 v100, v0
	v_mov_b32_e32 v101, v0
	v_mov_b32_e32 v102, v0
	v_mov_b32_e32 v103, v0
	v_mov_b32_e32 v48, v0
	v_mov_b32_e32 v49, v0
	v_mov_b32_e32 v50, v0
	v_mov_b32_e32 v51, v0
	v_mov_b32_e32 v108, v0
	v_mov_b32_e32 v109, v0
	v_mov_b32_e32 v110, v0
	v_mov_b32_e32 v111, v0
	v_mov_b32_e32 v120, v0
	v_mov_b32_e32 v121, v0
	v_mov_b32_e32 v122, v0
	v_mov_b32_e32 v123, v0
	v_mov_b32_e32 v124, v0
	v_mov_b32_e32 v125, v0
	v_mov_b32_e32 v126, v0
	v_mov_b32_e32 v127, v0
	s_cmp_ge_u32 s33, 0x1000
	s_cbranch_scc1 .Lsprio_9
	s_setprio 1
.Lsprio_9:
.LBB0_1198:
	ds_read_b128 v[144:147], v153
	ds_read_b128 v[158:161], v153 offset:1024
	ds_read_b128 v[162:165], v153 offset:2048
	ds_read_b128 v[166:169], v153 offset:3072
	ds_read_b128 v[170:173], v154
	ds_read_b128 v[174:177], v154 offset:1024
	ds_read_b128 v[178:181], v154 offset:2048
	ds_read_b128 v[182:185], v154 offset:3072
	s_add_u32 s38, s34, 0xfff00080
	s_addc_u32 s39, s35, -1
	s_cmp_eq_u32 s65, 60
	s_cselect_b32 s41, s21, s39
	s_cselect_b32 s40, s27, s38
	s_cselect_b32 s39, s19, s64
	s_cselect_b32 s38, s62, s63
	s_add_i32 m0, s31, 0xc000
	ds_read_b128 v[186:189], v155
	ds_read_b128 v[190:193], v155 offset:1024
	ds_read_b128 v[194:197], v155 offset:2048
	ds_read_b128 v[198:201], v155 offset:3072
	ds_read_b128 v[202:205], v155 offset:4096
	ds_read_b128 v[206:209], v155 offset:5120
	ds_read_b128 v[210:213], v155 offset:6144
	ds_read_b128 v[214:217], v155 offset:7168
	global_load_lds_dwordx4 v136, s[34:35]
	s_add_i32 m0, s31, 0xe000
	s_nop 0
	global_load_lds_dwordx4 v138, s[34:35]
	s_waitcnt vmcnt(8)
	s_waitcnt lgkmcnt(0)
	s_barrier
; #define PG8_STAGE(bufoff, gbase, voff) do { _Pragma("unroll") for (int _i = 0; _i < 2; ++_i) \
;         __builtin_amdgcn_global_load_lds((const unsigned*)((const char*)(gbase) + (voff)[_i]), (PG8_LAS unsigned*)(lds + (bufoff) + ldsw + _i * 8192), 16, 0, 0); } while (0)
; #define PG8_LDA(dst, b, h) do { _Pragma("unroll") for (int m = 0; m < 4; ++m) _Pragma("unroll") for (int k = 0; k < 2; ++k) dst[m][k] = *(const PG8_LAS bf16x8*)(lds + PG8_SA(b, h) + aoff + m * 2048 + k * 1024); } while (0)
; #define PG8_MMA(ai, bj, At, Bt) do { __builtin_amdgcn_s_setprio(1); _Pragma("unroll") for (int m = 0; m < 4; ++m) _Pragma("unroll") for (int n = 0; n < 2; ++n) _Pragma("unroll") for (int k = 0; k < 2; ++k) \
;         acc[ai][bj][m][n] = __builtin_amdgcn_mfma_f32_16x16x32_bf16(Bt[n][k], At[m][k], acc[ai][bj][m][n], 0, 0, 0); __builtin_amdgcn_s_setprio(0); } while (0)
; #define PG8_WAIT_V(n) asm volatile("s_waitcnt vmcnt(" #n ")" ::: "memory")
; #define PG8_WAIT_L(n) asm volatile("s_waitcnt lgkmcnt(" #n ")" ::: "memory")
; #define PG8_BAR __builtin_amdgcn_s_barrier()
; #define PG8_SCHED __builtin_amdgcn_sched_barrier(0)
; template <class Epi, class Sched, bool ALIGN_EPI = false, bool SP2 = false>
; __device__ __forceinline__ void gemm_phase(PG8_LAS unsigned char* lds, const Gemm g, const Sched& S, const Epi& E) {
;     ...
;             PG8_WAIT_V(8); PG8_WAIT_L(0); PG8_BAR; PG8_MMA(0, 0, At, B0); PG8_MMA(0, 1, At, B1); PG8_BAR; PG8_SCHED;
;             PG8_LDA(At, 0, 1); PG8_STAGE(PG8_SB(0, 0), b2, voffB); PG8_STAGE(PG8_SB(0, 1), b2 + hstep, voffB); PG8_STAGE(PG8_SA(0, 0), a2, voffA);
;             PG8_WAIT_V(8); PG8_WAIT_L(0); PG8_BAR; PG8_MMA(1, 0, At, B0); PG8_MMA(1, 1, At, B1); PG8_BAR; PG8_SCHED;
	v_mfma_f32_16x16x32_bf16 v[124:127], v[144:147], v[186:189], v[124:127]
	v_mfma_f32_16x16x32_bf16 v[120:123], v[162:165], v[186:189], v[120:123]
	v_mfma_f32_16x16x32_bf16 v[108:111], v[144:147], v[194:197], v[108:111]
	v_mfma_f32_16x16x32_bf16 v[48:51], v[162:165], v[194:197], v[48:51]
	v_mfma_f32_16x16x32_bf16 v[100:103], v[144:147], v[202:205], v[100:103]
	v_mfma_f32_16x16x32_bf16 v[64:67], v[162:165], v[202:205], v[64:67]
	v_mfma_f32_16x16x32_bf16 v[92:95], v[144:147], v[210:213], v[92:95]
	v_mfma_f32_16x16x32_bf16 v[80:83], v[162:165], v[210:213], v[80:83]
	v_mfma_f32_16x16x32_bf16 v[124:127], v[158:161], v[190:193], v[124:127]
	v_mfma_f32_16x16x32_bf16 v[120:123], v[166:169], v[190:193], v[120:123]
	v_mfma_f32_16x16x32_bf16 v[108:111], v[158:161], v[198:201], v[108:111]
	v_mfma_f32_16x16x32_bf16 v[48:51], v[166:169], v[198:201], v[48:51]
	v_mfma_f32_16x16x32_bf16 v[100:103], v[158:161], v[206:209], v[100:103]
	v_mfma_f32_16x16x32_bf16 v[64:67], v[166:169], v[206:209], v[64:67]
	v_mfma_f32_16x16x32_bf16 v[92:95], v[158:161], v[214:217], v[92:95]
	v_mfma_f32_16x16x32_bf16 v[80:83], v[166:169], v[214:217], v[80:83]
	v_mfma_f32_16x16x32_bf16 v[116:119], v[170:173], v[186:189], v[116:119]
	v_mfma_f32_16x16x32_bf16 v[112:115], v[178:181], v[186:189], v[112:115]
	v_mfma_f32_16x16x32_bf16 v[104:107], v[170:173], v[194:197], v[104:107]
	v_mfma_f32_16x16x32_bf16 v[52:55], v[178:181], v[194:197], v[52:55]
	v_mfma_f32_16x16x32_bf16 v[96:99], v[170:173], v[202:205], v[96:99]
	v_mfma_f32_16x16x32_bf16 v[76:79], v[178:181], v[202:205], v[76:79]
	v_mfma_f32_16x16x32_bf16 v[88:91], v[170:173], v[210:213], v[88:91]
	v_mfma_f32_16x16x32_bf16 v[84:87], v[178:181], v[210:213], v[84:87]
	v_mfma_f32_16x16x32_bf16 v[116:119], v[174:177], v[190:193], v[116:119]
	v_mfma_f32_16x16x32_bf16 v[112:115], v[182:185], v[190:193], v[112:115]
	v_mfma_f32_16x16x32_bf16 v[104:107], v[174:177], v[198:201], v[104:107]
	v_mfma_f32_16x16x32_bf16 v[52:55], v[182:185], v[198:201], v[52:55]
	v_mfma_f32_16x16x32_bf16 v[96:99], v[174:177], v[206:209], v[96:99]
	v_mfma_f32_16x16x32_bf16 v[76:79], v[182:185], v[206:209], v[76:79]
	v_mfma_f32_16x16x32_bf16 v[88:91], v[174:177], v[214:217], v[88:91]
	v_mfma_f32_16x16x32_bf16 v[84:87], v[182:185], v[214:217], v[84:87]
	s_barrier
	s_add_u32 s98, s38, s14
	s_addc_u32 s99, s39, s15
	s_add_u32 s100, s40, s14
	s_addc_u32 s101, s41, s15
	s_add_i32 s66, s60, s33
	s_mov_b32 m0, s66
	ds_read_b128 v[186:189], v155 offset:16384
	ds_read_b128 v[190:193], v155 offset:17408
	ds_read_b128 v[194:197], v155 offset:18432
	ds_read_b128 v[198:201], v155 offset:19456
	ds_read_b128 v[202:205], v155 offset:20480
	ds_read_b128 v[206:209], v155 offset:21504
	ds_read_b128 v[210:213], v155 offset:22528
	ds_read_b128 v[214:217], v155 offset:23552
	global_load_lds_dwordx4 v130, s[38:39]
	s_add_i32 m0, s66, 0x2000
	s_add_u32 s66, s38, 0x100000
	s_addc_u32 s67, s39, 0
	s_add_i32 s68, s61, s33
	global_load_lds_dwordx4 v134, s[38:39]
	s_mov_b32 m0, s68
	s_nop 0
	global_load_lds_dwordx4 v130, s[66:67]
	s_add_i32 m0, s68, 0x2000
	s_nop 0
	global_load_lds_dwordx4 v134, s[66:67]
	s_mov_b32 m0, s31
	s_nop 0
	global_load_lds_dwordx4 v128, s[40:41]
	s_mov_b32 m0, s52
	s_nop 0
	global_load_lds_dwordx4 v132, s[40:41]
	s_waitcnt vmcnt(8)
	s_waitcnt lgkmcnt(0)
	s_barrier
	v_mfma_f32_16x16x32_bf16 v[72:75], v[144:147], v[186:189], v[72:75]
	v_mfma_f32_16x16x32_bf16 v[68:71], v[162:165], v[186:189], v[68:71]
	v_mfma_f32_16x16x32_bf16 v[44:47], v[144:147], v[194:197], v[44:47]
	v_mfma_f32_16x16x32_bf16 v[40:43], v[162:165], v[194:197], v[40:43]
	v_mfma_f32_16x16x32_bf16 v[28:31], v[144:147], v[202:205], v[28:31]
	v_mfma_f32_16x16x32_bf16 v[24:27], v[162:165], v[202:205], v[24:27]
	v_mfma_f32_16x16x32_bf16 v[12:15], v[144:147], v[210:213], v[12:15]
	v_mfma_f32_16x16x32_bf16 v[8:11], v[162:165], v[210:213], v[8:11]
	v_mfma_f32_16x16x32_bf16 v[72:75], v[158:161], v[190:193], v[72:75]
	v_mfma_f32_16x16x32_bf16 v[68:71], v[166:169], v[190:193], v[68:71]
	v_mfma_f32_16x16x32_bf16 v[44:47], v[158:161], v[198:201], v[44:47]
	v_mfma_f32_16x16x32_bf16 v[40:43], v[166:169], v[198:201], v[40:43]
	v_mfma_f32_16x16x32_bf16 v[28:31], v[158:161], v[206:209], v[28:31]
	v_mfma_f32_16x16x32_bf16 v[24:27], v[166:169], v[206:209], v[24:27]
	v_mfma_f32_16x16x32_bf16 v[12:15], v[158:161], v[214:217], v[12:15]
	v_mfma_f32_16x16x32_bf16 v[8:11], v[166:169], v[214:217], v[8:11]
	v_mfma_f32_16x16x32_bf16 v[60:63], v[170:173], v[186:189], v[60:63]
	v_mfma_f32_16x16x32_bf16 v[56:59], v[178:181], v[186:189], v[56:59]
	v_mfma_f32_16x16x32_bf16 v[36:39], v[170:173], v[194:197], v[36:39]
	v_mfma_f32_16x16x32_bf16 v[32:35], v[178:181], v[194:197], v[32:35]
	v_mfma_f32_16x16x32_bf16 v[20:23], v[170:173], v[202:205], v[20:23]
	v_mfma_f32_16x16x32_bf16 v[16:19], v[178:181], v[202:205], v[16:19]
	v_mfma_f32_16x16x32_bf16 v[4:7], v[170:173], v[210:213], v[4:7]
	v_mfma_f32_16x16x32_bf16 v[0:3], v[178:181], v[210:213], v[0:3]
	v_mfma_f32_16x16x32_bf16 v[60:63], v[174:177], v[190:193], v[60:63]
	v_mfma_f32_16x16x32_bf16 v[56:59], v[182:185], v[190:193], v[56:59]
	v_mfma_f32_16x16x32_bf16 v[36:39], v[174:177], v[198:201], v[36:39]
	v_mfma_f32_16x16x32_bf16 v[32:35], v[182:185], v[198:201], v[32:35]
	v_mfma_f32_16x16x32_bf16 v[20:23], v[174:177], v[206:209], v[20:23]
	v_mfma_f32_16x16x32_bf16 v[16:19], v[182:185], v[206:209], v[16:19]
	v_mfma_f32_16x16x32_bf16 v[4:7], v[174:177], v[214:217], v[4:7]
	v_mfma_f32_16x16x32_bf16 v[0:3], v[182:185], v[214:217], v[0:3]
	s_barrier
; #define PG8_STAGE(bufoff, gbase, voff) do { _Pragma("unroll") for (int _i = 0; _i < 2; ++_i) \
;         __builtin_amdgcn_global_load_lds((const unsigned*)((const char*)(gbase) + (voff)[_i]), (PG8_LAS unsigned*)(lds + (bufoff) + ldsw + _i * 8192), 16, 0, 0); } while (0)
; #define PG8_LDA(dst, b, h) do { _Pragma("unroll") for (int m = 0; m < 4; ++m) _Pragma("unroll") for (int k = 0; k < 2; ++k) dst[m][k] = *(const PG8_LAS bf16x8*)(lds + PG8_SA(b, h) + aoff + m * 2048 + k * 1024); } while (0)
; #define PG8_LDB(dst, b, h) do { _Pragma("unroll") for (int n = 0; n < 2; ++n) _Pragma("unroll") for (int k = 0; k < 2; ++k) dst[n][k] = *(const PG8_LAS bf16x8*)(lds + PG8_SB(b, h) + boff + n * 2048 + k * 1024); } while (0)
; #define PG8_MMA(ai, bj, At, Bt) do { __builtin_amdgcn_s_setprio(1); _Pragma("unroll") for (int m = 0; m < 4; ++m) _Pragma("unroll") for (int n = 0; n < 2; ++n) _Pragma("unroll") for (int k = 0; k < 2; ++k) \
;         acc[ai][bj][m][n] = __builtin_amdgcn_mfma_f32_16x16x32_bf16(Bt[n][k], At[m][k], acc[ai][bj][m][n], 0, 0, 0); __builtin_amdgcn_s_setprio(0); } while (0)
; #define PG8_WAIT_V(n) asm volatile("s_waitcnt vmcnt(" #n ")" ::: "memory")
; #define PG8_WAIT_L(n) asm volatile("s_waitcnt lgkmcnt(" #n ")" ::: "memory")
; #define PG8_BAR __builtin_amdgcn_s_barrier()
; #define PG8_SCHED __builtin_amdgcn_sched_barrier(0)
; template <class Epi, class Sched, bool ALIGN_EPI = false, bool SP2 = false>
; __device__ __forceinline__ void gemm_phase(PG8_LAS unsigned char* lds, const Gemm g, const Sched& S, const Epi& E) {
;     ...
;             PG8_LDB(B0, 1, 0); PG8_LDB(B1, 1, 1); PG8_SCHED; PG8_LDA(At, 1, 0); PG8_STAGE(PG8_SA(0, 1), a2 + hstepA, voffA);
;             PG8_WAIT_V(8); PG8_WAIT_L(0); PG8_BAR; PG8_MMA(0, 0, At, B0); PG8_MMA(0, 1, At, B1); PG8_BAR; PG8_SCHED;
;             PG8_LDA(At, 1, 1); PG8_STAGE(PG8_SB(1, 0), b3, voffB); PG8_STAGE(PG8_SB(1, 1), b3 + hstep, voffB); PG8_STAGE(PG8_SA(1, 0), a3, voffA);
;             PG8_WAIT_V(8); PG8_WAIT_L(0); PG8_BAR; PG8_MMA(1, 0, At, B0); PG8_MMA(1, 1, At, B1); PG8_BAR; PG8_SCHED;
;     ...
;         if constexpr (ALIGN_EPI) { if (wr == 0) PG8_BAR; }
	s_add_i32 s66, 0, 0x18000
	v_add_u32_e32 v157, s66, v151
	s_add_i32 s67, 0, 0x1c000
	ds_read_b128 v[144:147], v157
	ds_read_b128 v[158:161], v157 offset:1024
	ds_read_b128 v[162:165], v157 offset:2048
	ds_read_b128 v[166:169], v157 offset:3072
	v_add_u32_e32 v157, s67, v151
	ds_read_b128 v[170:173], v157
	ds_read_b128 v[174:177], v157 offset:1024
	ds_read_b128 v[178:181], v157 offset:2048
	ds_read_b128 v[182:185], v157 offset:3072
	s_add_u32 s40, s40, 0x100000
	s_addc_u32 s41, s41, 0
	s_mov_b32 m0, s53
	ds_read_b128 v[186:189], v155 offset:32768
	ds_read_b128 v[190:193], v155 offset:33792
	ds_read_b128 v[194:197], v155 offset:34816
	ds_read_b128 v[198:201], v155 offset:35840
	ds_read_b128 v[202:205], v155 offset:36864
	ds_read_b128 v[206:209], v155 offset:37888
	ds_read_b128 v[210:213], v155 offset:38912
	ds_read_b128 v[214:217], v155 offset:39936
	global_load_lds_dwordx4 v128, s[40:41]
	s_mov_b32 m0, s54
	s_nop 0
	global_load_lds_dwordx4 v132, s[40:41]
	s_waitcnt vmcnt(8)
	s_waitcnt lgkmcnt(0)
	s_barrier
	v_mfma_f32_16x16x32_bf16 v[124:127], v[144:147], v[186:189], v[124:127]
	v_mfma_f32_16x16x32_bf16 v[120:123], v[162:165], v[186:189], v[120:123]
	v_mfma_f32_16x16x32_bf16 v[108:111], v[144:147], v[194:197], v[108:111]
	v_mfma_f32_16x16x32_bf16 v[48:51], v[162:165], v[194:197], v[48:51]
	v_mfma_f32_16x16x32_bf16 v[100:103], v[144:147], v[202:205], v[100:103]
	v_mfma_f32_16x16x32_bf16 v[64:67], v[162:165], v[202:205], v[64:67]
	v_mfma_f32_16x16x32_bf16 v[92:95], v[144:147], v[210:213], v[92:95]
	v_mfma_f32_16x16x32_bf16 v[80:83], v[162:165], v[210:213], v[80:83]
	v_mfma_f32_16x16x32_bf16 v[124:127], v[158:161], v[190:193], v[124:127]
	v_mfma_f32_16x16x32_bf16 v[120:123], v[166:169], v[190:193], v[120:123]
	v_mfma_f32_16x16x32_bf16 v[108:111], v[158:161], v[198:201], v[108:111]
	v_mfma_f32_16x16x32_bf16 v[48:51], v[166:169], v[198:201], v[48:51]
	v_mfma_f32_16x16x32_bf16 v[100:103], v[158:161], v[206:209], v[100:103]
	v_mfma_f32_16x16x32_bf16 v[64:67], v[166:169], v[206:209], v[64:67]
	v_mfma_f32_16x16x32_bf16 v[92:95], v[158:161], v[214:217], v[92:95]
	v_mfma_f32_16x16x32_bf16 v[80:83], v[166:169], v[214:217], v[80:83]
	v_mfma_f32_16x16x32_bf16 v[116:119], v[170:173], v[186:189], v[116:119]
	v_mfma_f32_16x16x32_bf16 v[112:115], v[178:181], v[186:189], v[112:115]
	v_mfma_f32_16x16x32_bf16 v[104:107], v[170:173], v[194:197], v[104:107]
	v_mfma_f32_16x16x32_bf16 v[52:55], v[178:181], v[194:197], v[52:55]
	v_mfma_f32_16x16x32_bf16 v[96:99], v[170:173], v[202:205], v[96:99]
	v_mfma_f32_16x16x32_bf16 v[76:79], v[178:181], v[202:205], v[76:79]
	v_mfma_f32_16x16x32_bf16 v[88:91], v[170:173], v[210:213], v[88:91]
	v_mfma_f32_16x16x32_bf16 v[84:87], v[178:181], v[210:213], v[84:87]
	v_mfma_f32_16x16x32_bf16 v[116:119], v[174:177], v[190:193], v[116:119]
	v_mfma_f32_16x16x32_bf16 v[112:115], v[182:185], v[190:193], v[112:115]
	v_mfma_f32_16x16x32_bf16 v[104:107], v[174:177], v[198:201], v[104:107]
	v_mfma_f32_16x16x32_bf16 v[52:55], v[182:185], v[198:201], v[52:55]
	v_mfma_f32_16x16x32_bf16 v[96:99], v[174:177], v[206:209], v[96:99]
	v_mfma_f32_16x16x32_bf16 v[76:79], v[182:185], v[206:209], v[76:79]
	v_mfma_f32_16x16x32_bf16 v[88:91], v[174:177], v[214:217], v[88:91]
	v_mfma_f32_16x16x32_bf16 v[84:87], v[182:185], v[214:217], v[84:87]
	s_barrier
	s_add_i32 s40, s66, s33
	s_mov_b32 m0, s40
	ds_read_b128 v[186:189], v155 offset:49152
	ds_read_b128 v[190:193], v155 offset:50176
	ds_read_b128 v[194:197], v155 offset:51200
	ds_read_b128 v[198:201], v155 offset:52224
	ds_read_b128 v[202:205], v155 offset:53248
	ds_read_b128 v[206:209], v155 offset:54272
	ds_read_b128 v[210:213], v155 offset:55296
	ds_read_b128 v[214:217], v155 offset:56320
	global_load_lds_dwordx4 v130, s[98:99]
	s_add_i32 m0, s40, 0x2000
	s_add_u32 s38, s38, 0x100080
	s_addc_u32 s39, s39, 0
	s_add_i32 s40, s67, s33
	global_load_lds_dwordx4 v134, s[98:99]
	s_mov_b32 m0, s40
	s_nop 0
	global_load_lds_dwordx4 v130, s[38:39]
	s_add_i32 m0, s40, 0x2000
	s_nop 0
	global_load_lds_dwordx4 v134, s[38:39]
	s_mov_b32 m0, s56
	s_nop 0
	global_load_lds_dwordx4 v128, s[100:101]
	s_mov_b32 m0, s57
	s_nop 0
	global_load_lds_dwordx4 v132, s[100:101]
	s_waitcnt vmcnt(8)
	s_waitcnt lgkmcnt(0)
	s_barrier
	v_mfma_f32_16x16x32_bf16 v[72:75], v[144:147], v[186:189], v[72:75]
	v_mfma_f32_16x16x32_bf16 v[68:71], v[162:165], v[186:189], v[68:71]
	v_mfma_f32_16x16x32_bf16 v[44:47], v[144:147], v[194:197], v[44:47]
	v_mfma_f32_16x16x32_bf16 v[40:43], v[162:165], v[194:197], v[40:43]
	v_mfma_f32_16x16x32_bf16 v[28:31], v[144:147], v[202:205], v[28:31]
	v_mfma_f32_16x16x32_bf16 v[24:27], v[162:165], v[202:205], v[24:27]
	v_mfma_f32_16x16x32_bf16 v[12:15], v[144:147], v[210:213], v[12:15]
	v_mfma_f32_16x16x32_bf16 v[8:11], v[162:165], v[210:213], v[8:11]
	v_mfma_f32_16x16x32_bf16 v[72:75], v[158:161], v[190:193], v[72:75]
	v_mfma_f32_16x16x32_bf16 v[68:71], v[166:169], v[190:193], v[68:71]
	v_mfma_f32_16x16x32_bf16 v[44:47], v[158:161], v[198:201], v[44:47]
	v_mfma_f32_16x16x32_bf16 v[40:43], v[166:169], v[198:201], v[40:43]
	v_mfma_f32_16x16x32_bf16 v[28:31], v[158:161], v[206:209], v[28:31]
	v_mfma_f32_16x16x32_bf16 v[24:27], v[166:169], v[206:209], v[24:27]
	v_mfma_f32_16x16x32_bf16 v[12:15], v[158:161], v[214:217], v[12:15]
	v_mfma_f32_16x16x32_bf16 v[8:11], v[166:169], v[214:217], v[8:11]
	v_mfma_f32_16x16x32_bf16 v[60:63], v[170:173], v[186:189], v[60:63]
	v_mfma_f32_16x16x32_bf16 v[56:59], v[178:181], v[186:189], v[56:59]
	v_mfma_f32_16x16x32_bf16 v[36:39], v[170:173], v[194:197], v[36:39]
	v_mfma_f32_16x16x32_bf16 v[32:35], v[178:181], v[194:197], v[32:35]
	v_mfma_f32_16x16x32_bf16 v[20:23], v[170:173], v[202:205], v[20:23]
	v_mfma_f32_16x16x32_bf16 v[16:19], v[178:181], v[202:205], v[16:19]
	v_mfma_f32_16x16x32_bf16 v[4:7], v[170:173], v[210:213], v[4:7]
	v_mfma_f32_16x16x32_bf16 v[0:3], v[178:181], v[210:213], v[0:3]
	v_mfma_f32_16x16x32_bf16 v[60:63], v[174:177], v[190:193], v[60:63]
	v_mfma_f32_16x16x32_bf16 v[56:59], v[182:185], v[190:193], v[56:59]
	v_mfma_f32_16x16x32_bf16 v[36:39], v[174:177], v[198:201], v[36:39]
	v_mfma_f32_16x16x32_bf16 v[32:35], v[182:185], v[198:201], v[32:35]
	v_mfma_f32_16x16x32_bf16 v[20:23], v[174:177], v[206:209], v[20:23]
	v_mfma_f32_16x16x32_bf16 v[16:19], v[182:185], v[206:209], v[16:19]
	v_mfma_f32_16x16x32_bf16 v[4:7], v[174:177], v[214:217], v[4:7]
	v_mfma_f32_16x16x32_bf16 v[0:3], v[182:185], v[214:217], v[0:3]
	s_barrier
	s_add_i32 s65, s65, 2
	s_add_u32 s34, s34, 0x100
	s_addc_u32 s35, s35, 0
	s_add_u32 s63, s63, 0x100
	s_addc_u32 s64, s64, 0
	s_cmp_gt_u32 s65, 61
	s_cbranch_scc0 .LBB0_1198
	s_setprio 0
	s_and_b64 vcc, exec, s[16:17]
	s_cbranch_vccz .LBB0_1201
	s_barrier

; #define PG8_STAGE(bufoff, gbase, voff) do { _Pragma("unroll") for (int _i = 0; _i < 2; ++_i) \
;         __builtin_amdgcn_global_load_lds((const unsigned*)((const char*)(gbase) + (voff)[_i]), (PG8_LAS unsigned*)(lds + (bufoff) + ldsw + _i * 8192), 16, 0, 0); } while (0)
; #define PG8_LDA(dst, b, h) do { _Pragma("unroll") for (int m = 0; m < 4; ++m) _Pragma("unroll") for (int k = 0; k < 2; ++k) dst[m][k] = *(const PG8_LAS bf16x8*)(lds + PG8_SA(b, h) + aoff + m * 2048 + k * 1024); } while (0)
; #define PG8_LDB(dst, b, h) do { _Pragma("unroll") for (int n = 0; n < 2; ++n) _Pragma("unroll") for (int k = 0; k < 2; ++k) dst[n][k] = *(const PG8_LAS bf16x8*)(lds + PG8_SB(b, h) + boff + n * 2048 + k * 1024); } while (0)
; #define PG8_WAIT_V(n) asm volatile("s_waitcnt vmcnt(" #n ")" ::: "memory")
; #define PG8_WAIT_L(n) asm volatile("s_waitcnt lgkmcnt(" #n ")" ::: "memory")
; #define PG8_BAR __builtin_amdgcn_s_barrier()
; #define PG8_SCHED __builtin_amdgcn_sched_barrier(0)
; template <class Epi, class Sched, bool ALIGN_EPI = false, bool SP2 = false>
; __device__ __forceinline__ void gemm_phase(PG8_LAS unsigned char* lds, const Gemm g, const Sched& S, const Epi& E) {
;     ...
;     for (;;) {
;         const bool has_next = S.next(ui + 1, nxt);
;         const char* nA = has_next ? (const char*)g.A + (size_t)nxt.pm * tstep : cA; const char* nB = has_next ? (const char*)g.Bt + (size_t)nxt.pn * tstep : cB;
;         for (int t = 0; t < nt; t += 2) {
;             const bool last = (t == nt - 2);
;             const char* a1 = cA + (size_t)(t + 1) * kstepA;
;             const char* a2 = last ? nA : cA + (size_t)(t + 2) * kstepA; const char* b2 = last ? nB : cB + (size_t)(t + 2) * kstep;
;             const char* a3 = a2 + kstepA; const char* b3 = b2 + kstep;
;             if (last && has_next) S.a_ready(nxt);
;             if constexpr (SP2) {
;             PG8_LDB(B0, 0, 0); PG8_LDB(B1, 0, 1); PG8_SCHED; PG8_LDA(At, 0, 0); PG8_STAGE(PG8_SA(1, 1), a1 + hstepA, voffA);
;             PG8_WAIT_V(8); PG8_WAIT_L(0); PG8_BAR; PG8_MMA(0, 0, At, B0); PG8_MMA(0, 1, At, B1); PG8_BAR; PG8_SCHED;
;     ...
;         for (int a = 0; a < 2; ++a)
; #pragma unroll
;             for (int b = 0; b < 2; ++b)
; #pragma unroll
;                 for (int m = 0; m < 4; ++m)
; #pragma unroll
;                     for (int n = 0; n < 2; ++n) acc[a][b][m][n] = (f32x4){0.f, 0.f, 0.f, 0.f};
.LBB0_1309:
	s_ashr_i32 s41, s40, 31
	s_lshl_b64 s[6:7], s[40:41], 21
	s_add_u32 s84, s92, s6
	s_addc_u32 s85, s93, s7
	s_and_b64 s[6:7], s[4:5], exec
	s_cselect_b32 s41, s85, s95
	s_cselect_b32 s52, s84, s94
	s_ashr_i32 s39, s38, 31
	s_lshl_b64 s[6:7], s[38:39], 21
	s_add_u32 s86, s75, s6
	s_addc_u32 s87, s33, s7
	s_and_b64 s[6:7], s[4:5], exec
	s_cselect_b32 s39, s87, s97
	s_cselect_b32 s53, s86, s96
	s_add_u32 s69, s96, 0x100
	v_mov_b32_e32 v0, 0
	s_addc_u32 s70, s97, 0
	s_mov_b32 s71, -2
	v_mov_b32_e32 v1, v0
	v_mov_b32_e32 v2, v0
	v_mov_b32_e32 v3, v0
	v_mov_b32_e32 v4, v0
	v_mov_b32_e32 v5, v0
	v_mov_b32_e32 v6, v0
	v_mov_b32_e32 v7, v0
	v_mov_b32_e32 v16, v0
	v_mov_b32_e32 v17, v0
	v_mov_b32_e32 v18, v0
	v_mov_b32_e32 v19, v0
	v_mov_b32_e32 v20, v0
	v_mov_b32_e32 v21, v0
	v_mov_b32_e32 v22, v0
	v_mov_b32_e32 v23, v0
	v_mov_b32_e32 v32, v0
	v_mov_b32_e32 v33, v0
	v_mov_b32_e32 v34, v0
	v_mov_b32_e32 v35, v0
	s_waitcnt vmcnt(0)
	v_mov_b32_e32 v36, v0
	v_mov_b32_e32 v37, v0
	v_mov_b32_e32 v38, v0
	v_mov_b32_e32 v39, v0
	v_mov_b32_e32 v48, v0
	v_mov_b32_e32 v49, v0
	v_mov_b32_e32 v50, v0
	v_mov_b32_e32 v51, v0
	v_mov_b32_e32 v52, v0
	v_mov_b32_e32 v53, v0
	v_mov_b32_e32 v54, v0
	v_mov_b32_e32 v55, v0
	v_mov_b32_e32 v8, v0
	v_mov_b32_e32 v9, v0
	v_mov_b32_e32 v10, v0
	v_mov_b32_e32 v11, v0
	v_mov_b32_e32 v12, v0
	v_mov_b32_e32 v13, v0
	v_mov_b32_e32 v14, v0
	v_mov_b32_e32 v15, v0
	v_mov_b32_e32 v24, v0
	v_mov_b32_e32 v25, v0
	v_mov_b32_e32 v26, v0
	v_mov_b32_e32 v27, v0
	v_mov_b32_e32 v28, v0
	v_mov_b32_e32 v29, v0
	v_mov_b32_e32 v30, v0
	v_mov_b32_e32 v31, v0
	v_mov_b32_e32 v40, v0
	v_mov_b32_e32 v41, v0
	v_mov_b32_e32 v42, v0
	v_mov_b32_e32 v43, v0
	v_mov_b32_e32 v44, v0
	v_mov_b32_e32 v45, v0
	v_mov_b32_e32 v46, v0
	v_mov_b32_e32 v47, v0
	v_mov_b32_e32 v56, v0
	v_mov_b32_e32 v57, v0
	v_mov_b32_e32 v58, v0
	v_mov_b32_e32 v59, v0
	v_mov_b32_e32 v60, v0
	v_mov_b32_e32 v61, v0
	v_mov_b32_e32 v62, v0
	v_mov_b32_e32 v63, v0
	v_mov_b32_e32 v64, v0
	v_mov_b32_e32 v65, v0
	v_mov_b32_e32 v66, v0
	v_mov_b32_e32 v67, v0
	v_mov_b32_e32 v68, v0
	v_mov_b32_e32 v69, v0
	v_mov_b32_e32 v70, v0
	v_mov_b32_e32 v71, v0
	v_mov_b32_e32 v80, v0
	v_mov_b32_e32 v81, v0
	v_mov_b32_e32 v82, v0
	v_mov_b32_e32 v83, v0
	v_mov_b32_e32 v84, v0
	v_mov_b32_e32 v85, v0
	v_mov_b32_e32 v86, v0
	v_mov_b32_e32 v87, v0
	v_mov_b32_e32 v96, v0
	v_mov_b32_e32 v97, v0
	v_mov_b32_e32 v98, v0
	v_mov_b32_e32 v99, v0
	v_mov_b32_e32 v100, v0
	v_mov_b32_e32 v101, v0
	v_mov_b32_e32 v102, v0
	v_mov_b32_e32 v103, v0
	v_mov_b32_e32 v112, v0
	v_mov_b32_e32 v113, v0
	v_mov_b32_e32 v114, v0
	v_mov_b32_e32 v115, v0
	v_mov_b32_e32 v116, v0
	v_mov_b32_e32 v117, v0
	v_mov_b32_e32 v118, v0
	v_mov_b32_e32 v119, v0
	v_mov_b32_e32 v72, v0
	v_mov_b32_e32 v73, v0
	v_mov_b32_e32 v74, v0
	v_mov_b32_e32 v75, v0
	v_mov_b32_e32 v76, v0
	v_mov_b32_e32 v77, v0
	v_mov_b32_e32 v78, v0
	v_mov_b32_e32 v79, v0
	v_mov_b32_e32 v88, v0
	v_mov_b32_e32 v89, v0
	v_mov_b32_e32 v90, v0
	v_mov_b32_e32 v91, v0
	v_mov_b32_e32 v92, v0
	v_mov_b32_e32 v93, v0
	v_mov_b32_e32 v94, v0
	v_mov_b32_e32 v95, v0
	v_mov_b32_e32 v104, v0
	v_mov_b32_e32 v105, v0
	v_mov_b32_e32 v106, v0
	v_mov_b32_e32 v107, v0
	v_mov_b32_e32 v108, v0
	v_mov_b32_e32 v109, v0
	v_mov_b32_e32 v110, v0
	v_mov_b32_e32 v111, v0
	v_mov_b32_e32 v120, v0
	v_mov_b32_e32 v121, v0
	v_mov_b32_e32 v122, v0
	v_mov_b32_e32 v123, v0
	v_mov_b32_e32 v124, v0
	v_mov_b32_e32 v125, v0
	v_mov_b32_e32 v126, v0
	v_mov_b32_e32 v127, v0
	s_cmp_ge_u32 s55, 0x1000
	s_cbranch_scc1 .Lsprio_8
	s_setprio 1
.Lsprio_8:
.LBB0_1310:
	ds_read_b128 v[128:131], v236
	ds_read_b128 v[132:135], v236 offset:1024
	ds_read_b128 v[136:139], v236 offset:2048
	ds_read_b128 v[140:143], v236 offset:3072
	ds_read_b128 v[144:147], v237
	ds_read_b128 v[148:151], v237 offset:1024
	ds_read_b128 v[152:155], v237 offset:2048
	ds_read_b128 v[156:159], v237 offset:3072
	s_add_u32 s96, s94, 0x100
	s_addc_u32 s97, s95, 0
	s_cmp_eq_u32 s71, 60
	s_cselect_b32 s7, s41, s97
	s_cselect_b32 s6, s52, s96
	s_cselect_b32 vcc_hi, s39, s70
	s_cselect_b32 vcc_lo, s53, s69
	v_lshl_add_u64 v[164:165], s[94:95], 0, v[178:179]
	s_add_i32 m0, s56, 0xc000
	ds_read_b128 v[160:163], v238
	ds_read_b128 v[186:189], v238 offset:1024
	ds_read_b128 v[190:193], v238 offset:2048
	ds_read_b128 v[194:197], v238 offset:3072
	ds_read_b128 v[198:201], v238 offset:4096
	ds_read_b128 v[202:205], v238 offset:5120
	ds_read_b128 v[206:209], v238 offset:6144
	ds_read_b128 v[210:213], v238 offset:7168
	global_load_lds_dwordx4 v[164:165], off
	v_lshl_add_u64 v[164:165], s[94:95], 0, v[180:181]
	s_add_i32 m0, s56, 0xe000
	s_nop 0
	global_load_lds_dwordx4 v[164:165], off
	s_waitcnt vmcnt(8)
	s_waitcnt lgkmcnt(0)
	s_barrier
; #define PG8_STAGE(bufoff, gbase, voff) do { _Pragma("unroll") for (int _i = 0; _i < 2; ++_i) \
;         __builtin_amdgcn_global_load_lds((const unsigned*)((const char*)(gbase) + (voff)[_i]), (PG8_LAS unsigned*)(lds + (bufoff) + ldsw + _i * 8192), 16, 0, 0); } while (0)
; #define PG8_LDA(dst, b, h) do { _Pragma("unroll") for (int m = 0; m < 4; ++m) _Pragma("unroll") for (int k = 0; k < 2; ++k) dst[m][k] = *(const PG8_LAS bf16x8*)(lds + PG8_SA(b, h) + aoff + m * 2048 + k * 1024); } while (0)
; #define PG8_MMA(ai, bj, At, Bt) do { __builtin_amdgcn_s_setprio(1); _Pragma("unroll") for (int m = 0; m < 4; ++m) _Pragma("unroll") for (int n = 0; n < 2; ++n) _Pragma("unroll") for (int k = 0; k < 2; ++k) \
;         acc[ai][bj][m][n] = __builtin_amdgcn_mfma_f32_16x16x32_bf16(Bt[n][k], At[m][k], acc[ai][bj][m][n], 0, 0, 0); __builtin_amdgcn_s_setprio(0); } while (0)
; #define PG8_WAIT_V(n) asm volatile("s_waitcnt vmcnt(" #n ")" ::: "memory")
; #define PG8_WAIT_L(n) asm volatile("s_waitcnt lgkmcnt(" #n ")" ::: "memory")
; #define PG8_BAR __builtin_amdgcn_s_barrier()
; #define PG8_SCHED __builtin_amdgcn_sched_barrier(0)
; template <class Epi, class Sched, bool ALIGN_EPI = false, bool SP2 = false>
; __device__ __forceinline__ void gemm_phase(PG8_LAS unsigned char* lds, const Gemm g, const Sched& S, const Epi& E) {
;     ...
;             PG8_WAIT_V(8); PG8_WAIT_L(0); PG8_BAR; PG8_MMA(0, 0, At, B0); PG8_MMA(0, 1, At, B1); PG8_BAR; PG8_SCHED;
;             PG8_LDA(At, 0, 1); PG8_STAGE(PG8_SB(0, 0), b2, voffB); PG8_STAGE(PG8_SB(0, 1), b2 + hstep, voffB); PG8_STAGE(PG8_SA(0, 0), a2, voffA);
;             PG8_WAIT_V(8); PG8_WAIT_L(0); PG8_BAR; PG8_MMA(1, 0, At, B0); PG8_MMA(1, 1, At, B1); PG8_BAR; PG8_SCHED;
	v_mfma_f32_16x16x32_bf16 v[124:127], v[128:131], v[160:163], v[124:127]
	v_mfma_f32_16x16x32_bf16 v[120:123], v[136:139], v[160:163], v[120:123]
	v_mfma_f32_16x16x32_bf16 v[108:111], v[128:131], v[190:193], v[108:111]
	v_mfma_f32_16x16x32_bf16 v[104:107], v[136:139], v[190:193], v[104:107]
	v_mfma_f32_16x16x32_bf16 v[92:95], v[128:131], v[198:201], v[92:95]
	v_mfma_f32_16x16x32_bf16 v[88:91], v[136:139], v[198:201], v[88:91]
	v_mfma_f32_16x16x32_bf16 v[76:79], v[128:131], v[206:209], v[76:79]
	v_mfma_f32_16x16x32_bf16 v[72:75], v[136:139], v[206:209], v[72:75]
	v_mfma_f32_16x16x32_bf16 v[124:127], v[132:135], v[186:189], v[124:127]
	v_mfma_f32_16x16x32_bf16 v[120:123], v[140:143], v[186:189], v[120:123]
	v_mfma_f32_16x16x32_bf16 v[108:111], v[132:135], v[194:197], v[108:111]
	v_mfma_f32_16x16x32_bf16 v[104:107], v[140:143], v[194:197], v[104:107]
	v_mfma_f32_16x16x32_bf16 v[92:95], v[132:135], v[202:205], v[92:95]
	v_mfma_f32_16x16x32_bf16 v[88:91], v[140:143], v[202:205], v[88:91]
	v_mfma_f32_16x16x32_bf16 v[76:79], v[132:135], v[210:213], v[76:79]
	v_mfma_f32_16x16x32_bf16 v[72:75], v[140:143], v[210:213], v[72:75]
	v_mfma_f32_16x16x32_bf16 v[116:119], v[144:147], v[160:163], v[116:119]
	v_mfma_f32_16x16x32_bf16 v[112:115], v[152:155], v[160:163], v[112:115]
	v_mfma_f32_16x16x32_bf16 v[100:103], v[144:147], v[190:193], v[100:103]
	v_mfma_f32_16x16x32_bf16 v[96:99], v[152:155], v[190:193], v[96:99]
	v_mfma_f32_16x16x32_bf16 v[84:87], v[144:147], v[198:201], v[84:87]
	v_mfma_f32_16x16x32_bf16 v[80:83], v[152:155], v[198:201], v[80:83]
	v_mfma_f32_16x16x32_bf16 v[68:71], v[144:147], v[206:209], v[68:71]
	v_mfma_f32_16x16x32_bf16 v[64:67], v[152:155], v[206:209], v[64:67]
	v_mfma_f32_16x16x32_bf16 v[116:119], v[148:151], v[186:189], v[116:119]
	v_mfma_f32_16x16x32_bf16 v[112:115], v[156:159], v[186:189], v[112:115]
	v_mfma_f32_16x16x32_bf16 v[100:103], v[148:151], v[194:197], v[100:103]
	v_mfma_f32_16x16x32_bf16 v[96:99], v[156:159], v[194:197], v[96:99]
	v_mfma_f32_16x16x32_bf16 v[84:87], v[148:151], v[202:205], v[84:87]
	v_mfma_f32_16x16x32_bf16 v[80:83], v[156:159], v[202:205], v[80:83]
	v_mfma_f32_16x16x32_bf16 v[68:71], v[148:151], v[210:213], v[68:71]
	v_mfma_f32_16x16x32_bf16 v[64:67], v[156:159], v[210:213], v[64:67]
	s_barrier
	s_add_u32 s98, vcc_lo, s10
	s_addc_u32 s99, vcc_hi, s11
	s_add_u32 s100, s6, s10
	s_addc_u32 s101, s7, s11
	s_add_i32 s72, s65, s55
	s_mov_b32 m0, s72
	ds_read_b128 v[160:163], v238 offset:16384
	ds_read_b128 v[186:189], v238 offset:17408
	ds_read_b128 v[190:193], v238 offset:18432
	ds_read_b128 v[194:197], v238 offset:19456
	ds_read_b128 v[198:201], v238 offset:20480
	ds_read_b128 v[202:205], v238 offset:21504
	ds_read_b128 v[206:209], v238 offset:22528
	ds_read_b128 v[210:213], v238 offset:23552
	global_load_lds_dwordx4 v168, vcc
	s_add_i32 m0, s72, 0x2000
	s_add_u32 s72, vcc_lo, 0x100000
	s_addc_u32 s73, vcc_hi, 0
	s_add_i32 s74, s66, s55
	global_load_lds_dwordx4 v172, vcc
	s_mov_b32 m0, s74
	s_nop 0
	global_load_lds_dwordx4 v168, s[72:73]
	s_add_i32 m0, s74, 0x2000
	s_nop 0
	global_load_lds_dwordx4 v172, s[72:73]
	s_mov_b32 m0, s56
	s_nop 0
	global_load_lds_dwordx4 v166, s[6:7]
	s_mov_b32 m0, s57
	s_nop 0
	global_load_lds_dwordx4 v170, s[6:7]
	s_waitcnt vmcnt(8)
	s_waitcnt lgkmcnt(0)
	s_barrier
	v_mfma_f32_16x16x32_bf16 v[60:63], v[128:131], v[160:163], v[60:63]
	v_mfma_f32_16x16x32_bf16 v[56:59], v[136:139], v[160:163], v[56:59]
	v_mfma_f32_16x16x32_bf16 v[44:47], v[128:131], v[190:193], v[44:47]
	v_mfma_f32_16x16x32_bf16 v[40:43], v[136:139], v[190:193], v[40:43]
	v_mfma_f32_16x16x32_bf16 v[28:31], v[128:131], v[198:201], v[28:31]
	v_mfma_f32_16x16x32_bf16 v[24:27], v[136:139], v[198:201], v[24:27]
	v_mfma_f32_16x16x32_bf16 v[12:15], v[128:131], v[206:209], v[12:15]
	v_mfma_f32_16x16x32_bf16 v[8:11], v[136:139], v[206:209], v[8:11]
	v_mfma_f32_16x16x32_bf16 v[60:63], v[132:135], v[186:189], v[60:63]
	v_mfma_f32_16x16x32_bf16 v[56:59], v[140:143], v[186:189], v[56:59]
	v_mfma_f32_16x16x32_bf16 v[44:47], v[132:135], v[194:197], v[44:47]
	v_mfma_f32_16x16x32_bf16 v[40:43], v[140:143], v[194:197], v[40:43]
	v_mfma_f32_16x16x32_bf16 v[28:31], v[132:135], v[202:205], v[28:31]
	v_mfma_f32_16x16x32_bf16 v[24:27], v[140:143], v[202:205], v[24:27]
	v_mfma_f32_16x16x32_bf16 v[12:15], v[132:135], v[210:213], v[12:15]
	v_mfma_f32_16x16x32_bf16 v[8:11], v[140:143], v[210:213], v[8:11]
	v_mfma_f32_16x16x32_bf16 v[52:55], v[144:147], v[160:163], v[52:55]
	v_mfma_f32_16x16x32_bf16 v[48:51], v[152:155], v[160:163], v[48:51]
	v_mfma_f32_16x16x32_bf16 v[36:39], v[144:147], v[190:193], v[36:39]
	v_mfma_f32_16x16x32_bf16 v[32:35], v[152:155], v[190:193], v[32:35]
	v_mfma_f32_16x16x32_bf16 v[20:23], v[144:147], v[198:201], v[20:23]
	v_mfma_f32_16x16x32_bf16 v[16:19], v[152:155], v[198:201], v[16:19]
	v_mfma_f32_16x16x32_bf16 v[4:7], v[144:147], v[206:209], v[4:7]
	v_mfma_f32_16x16x32_bf16 v[0:3], v[152:155], v[206:209], v[0:3]
	v_mfma_f32_16x16x32_bf16 v[52:55], v[148:151], v[186:189], v[52:55]
	v_mfma_f32_16x16x32_bf16 v[48:51], v[156:159], v[186:189], v[48:51]
	v_mfma_f32_16x16x32_bf16 v[36:39], v[148:151], v[194:197], v[36:39]
	v_mfma_f32_16x16x32_bf16 v[32:35], v[156:159], v[194:197], v[32:35]
	v_mfma_f32_16x16x32_bf16 v[20:23], v[148:151], v[202:205], v[20:23]
	v_mfma_f32_16x16x32_bf16 v[16:19], v[156:159], v[202:205], v[16:19]
	v_mfma_f32_16x16x32_bf16 v[4:7], v[148:151], v[210:213], v[4:7]
	v_mfma_f32_16x16x32_bf16 v[0:3], v[156:159], v[210:213], v[0:3]
	s_barrier
; #define PG8_STAGE(bufoff, gbase, voff) do { _Pragma("unroll") for (int _i = 0; _i < 2; ++_i) \
;         __builtin_amdgcn_global_load_lds((const unsigned*)((const char*)(gbase) + (voff)[_i]), (PG8_LAS unsigned*)(lds + (bufoff) + ldsw + _i * 8192), 16, 0, 0); } while (0)
; #define PG8_LDA(dst, b, h) do { _Pragma("unroll") for (int m = 0; m < 4; ++m) _Pragma("unroll") for (int k = 0; k < 2; ++k) dst[m][k] = *(const PG8_LAS bf16x8*)(lds + PG8_SA(b, h) + aoff + m * 2048 + k * 1024); } while (0)
; #define PG8_LDB(dst, b, h) do { _Pragma("unroll") for (int n = 0; n < 2; ++n) _Pragma("unroll") for (int k = 0; k < 2; ++k) dst[n][k] = *(const PG8_LAS bf16x8*)(lds + PG8_SB(b, h) + boff + n * 2048 + k * 1024); } while (0)
; #define PG8_MMA(ai, bj, At, Bt) do { __builtin_amdgcn_s_setprio(1); _Pragma("unroll") for (int m = 0; m < 4; ++m) _Pragma("unroll") for (int n = 0; n < 2; ++n) _Pragma("unroll") for (int k = 0; k < 2; ++k) \
;         acc[ai][bj][m][n] = __builtin_amdgcn_mfma_f32_16x16x32_bf16(Bt[n][k], At[m][k], acc[ai][bj][m][n], 0, 0, 0); __builtin_amdgcn_s_setprio(0); } while (0)
; #define PG8_WAIT_V(n) asm volatile("s_waitcnt vmcnt(" #n ")" ::: "memory")
; #define PG8_WAIT_L(n) asm volatile("s_waitcnt lgkmcnt(" #n ")" ::: "memory")
; #define PG8_BAR __builtin_amdgcn_s_barrier()
; #define PG8_SCHED __builtin_amdgcn_sched_barrier(0)
; template <class Epi, class Sched, bool ALIGN_EPI = false, bool SP2 = false>
; __device__ __forceinline__ void gemm_phase(PG8_LAS unsigned char* lds, const Gemm g, const Sched& S, const Epi& E) {
;     ...
;             PG8_LDB(B0, 1, 0); PG8_LDB(B1, 1, 1); PG8_SCHED; PG8_LDA(At, 1, 0); PG8_STAGE(PG8_SA(0, 1), a2 + hstepA, voffA);
;             PG8_WAIT_V(8); PG8_WAIT_L(0); PG8_BAR; PG8_MMA(0, 0, At, B0); PG8_MMA(0, 1, At, B1); PG8_BAR; PG8_SCHED;
;             PG8_LDA(At, 1, 1); PG8_STAGE(PG8_SB(1, 0), b3, voffB); PG8_STAGE(PG8_SB(1, 1), b3 + hstep, voffB); PG8_STAGE(PG8_SA(1, 0), a3, voffA);
;             PG8_WAIT_V(8); PG8_WAIT_L(0); PG8_BAR; PG8_MMA(1, 0, At, B0); PG8_MMA(1, 1, At, B1); PG8_BAR; PG8_SCHED;
;     ...
;         if constexpr (ALIGN_EPI) { if (wr == 0) PG8_BAR; }
	s_add_i32 s72, 0, 0x18000
	s_add_i32 s73, 0, 0x1c000
	v_add_u32_e32 v140, s72, v234
	v_add_u32_e32 v156, s73, v234
	ds_read_b128 v[128:131], v140
	ds_read_b128 v[132:135], v140 offset:1024
	ds_read_b128 v[136:139], v140 offset:2048
	ds_read_b128 v[140:143], v140 offset:3072
	ds_read_b128 v[144:147], v156
	ds_read_b128 v[148:151], v156 offset:1024
	ds_read_b128 v[152:155], v156 offset:2048
	ds_read_b128 v[156:159], v156 offset:3072
	s_add_u32 s6, s6, 0x100000
	s_addc_u32 s7, s7, 0
	s_mov_b32 m0, s58
	ds_read_b128 v[160:163], v238 offset:32768
	ds_read_b128 v[186:189], v238 offset:33792
	ds_read_b128 v[190:193], v238 offset:34816
	ds_read_b128 v[194:197], v238 offset:35840
	ds_read_b128 v[198:201], v238 offset:36864
	ds_read_b128 v[202:205], v238 offset:37888
	ds_read_b128 v[206:209], v238 offset:38912
	ds_read_b128 v[210:213], v238 offset:39936
	global_load_lds_dwordx4 v166, s[6:7]
	s_mov_b32 m0, s59
	s_nop 0
	global_load_lds_dwordx4 v170, s[6:7]
	s_waitcnt vmcnt(8)
	s_waitcnt lgkmcnt(0)
	s_barrier
	v_mfma_f32_16x16x32_bf16 v[124:127], v[128:131], v[160:163], v[124:127]
	v_mfma_f32_16x16x32_bf16 v[120:123], v[136:139], v[160:163], v[120:123]
	v_mfma_f32_16x16x32_bf16 v[108:111], v[128:131], v[190:193], v[108:111]
	v_mfma_f32_16x16x32_bf16 v[104:107], v[136:139], v[190:193], v[104:107]
	v_mfma_f32_16x16x32_bf16 v[92:95], v[128:131], v[198:201], v[92:95]
	v_mfma_f32_16x16x32_bf16 v[88:91], v[136:139], v[198:201], v[88:91]
	v_mfma_f32_16x16x32_bf16 v[76:79], v[128:131], v[206:209], v[76:79]
	v_mfma_f32_16x16x32_bf16 v[72:75], v[136:139], v[206:209], v[72:75]
	v_mfma_f32_16x16x32_bf16 v[124:127], v[132:135], v[186:189], v[124:127]
	v_mfma_f32_16x16x32_bf16 v[120:123], v[140:143], v[186:189], v[120:123]
	v_mfma_f32_16x16x32_bf16 v[108:111], v[132:135], v[194:197], v[108:111]
	v_mfma_f32_16x16x32_bf16 v[104:107], v[140:143], v[194:197], v[104:107]
	v_mfma_f32_16x16x32_bf16 v[92:95], v[132:135], v[202:205], v[92:95]
	v_mfma_f32_16x16x32_bf16 v[88:91], v[140:143], v[202:205], v[88:91]
	v_mfma_f32_16x16x32_bf16 v[76:79], v[132:135], v[210:213], v[76:79]
	v_mfma_f32_16x16x32_bf16 v[72:75], v[140:143], v[210:213], v[72:75]
	v_mfma_f32_16x16x32_bf16 v[116:119], v[144:147], v[160:163], v[116:119]
	v_mfma_f32_16x16x32_bf16 v[112:115], v[152:155], v[160:163], v[112:115]
	v_mfma_f32_16x16x32_bf16 v[100:103], v[144:147], v[190:193], v[100:103]
	v_mfma_f32_16x16x32_bf16 v[96:99], v[152:155], v[190:193], v[96:99]
	v_mfma_f32_16x16x32_bf16 v[84:87], v[144:147], v[198:201], v[84:87]
	v_mfma_f32_16x16x32_bf16 v[80:83], v[152:155], v[198:201], v[80:83]
	v_mfma_f32_16x16x32_bf16 v[68:71], v[144:147], v[206:209], v[68:71]
	v_mfma_f32_16x16x32_bf16 v[64:67], v[152:155], v[206:209], v[64:67]
	v_mfma_f32_16x16x32_bf16 v[116:119], v[148:151], v[186:189], v[116:119]
	v_mfma_f32_16x16x32_bf16 v[112:115], v[156:159], v[186:189], v[112:115]
	v_mfma_f32_16x16x32_bf16 v[100:103], v[148:151], v[194:197], v[100:103]
	v_mfma_f32_16x16x32_bf16 v[96:99], v[156:159], v[194:197], v[96:99]
	v_mfma_f32_16x16x32_bf16 v[84:87], v[148:151], v[202:205], v[84:87]
	v_mfma_f32_16x16x32_bf16 v[80:83], v[156:159], v[202:205], v[80:83]
	v_mfma_f32_16x16x32_bf16 v[68:71], v[148:151], v[210:213], v[68:71]
	v_mfma_f32_16x16x32_bf16 v[64:67], v[156:159], v[210:213], v[64:67]
	s_barrier
	s_add_i32 s6, s72, s55
	s_mov_b32 m0, s6
	ds_read_b128 v[160:163], v238 offset:49152
	ds_read_b128 v[186:189], v238 offset:50176
	ds_read_b128 v[190:193], v238 offset:51200
	ds_read_b128 v[194:197], v238 offset:52224
	ds_read_b128 v[198:201], v238 offset:53248
	ds_read_b128 v[202:205], v238 offset:54272
	ds_read_b128 v[206:209], v238 offset:55296
	ds_read_b128 v[210:213], v238 offset:56320
	global_load_lds_dwordx4 v168, s[98:99]
	s_add_i32 m0, s6, 0x2000
	s_add_u32 s6, vcc_lo, 0x100080
	s_addc_u32 s7, vcc_hi, 0
	s_add_i32 s72, s73, s55
	global_load_lds_dwordx4 v172, s[98:99]
	s_mov_b32 m0, s72
	s_nop 0
	global_load_lds_dwordx4 v168, s[6:7]
	s_add_i32 m0, s72, 0x2000
	s_nop 0
	global_load_lds_dwordx4 v172, s[6:7]
	s_mov_b32 m0, s63
	s_nop 0
	global_load_lds_dwordx4 v166, s[100:101]
	s_mov_b32 m0, s64
	s_nop 0
	global_load_lds_dwordx4 v170, s[100:101]
	s_waitcnt vmcnt(8)
	s_waitcnt lgkmcnt(0)
	s_barrier
	v_mfma_f32_16x16x32_bf16 v[60:63], v[128:131], v[160:163], v[60:63]
	v_mfma_f32_16x16x32_bf16 v[56:59], v[136:139], v[160:163], v[56:59]
	v_mfma_f32_16x16x32_bf16 v[44:47], v[128:131], v[190:193], v[44:47]
	v_mfma_f32_16x16x32_bf16 v[40:43], v[136:139], v[190:193], v[40:43]
	v_mfma_f32_16x16x32_bf16 v[28:31], v[128:131], v[198:201], v[28:31]
	v_mfma_f32_16x16x32_bf16 v[24:27], v[136:139], v[198:201], v[24:27]
	v_mfma_f32_16x16x32_bf16 v[12:15], v[128:131], v[206:209], v[12:15]
	v_mfma_f32_16x16x32_bf16 v[8:11], v[136:139], v[206:209], v[8:11]
	v_mfma_f32_16x16x32_bf16 v[60:63], v[132:135], v[186:189], v[60:63]
	v_mfma_f32_16x16x32_bf16 v[56:59], v[140:143], v[186:189], v[56:59]
	v_mfma_f32_16x16x32_bf16 v[44:47], v[132:135], v[194:197], v[44:47]
	v_mfma_f32_16x16x32_bf16 v[40:43], v[140:143], v[194:197], v[40:43]
	v_mfma_f32_16x16x32_bf16 v[28:31], v[132:135], v[202:205], v[28:31]
	v_mfma_f32_16x16x32_bf16 v[24:27], v[140:143], v[202:205], v[24:27]
	v_mfma_f32_16x16x32_bf16 v[12:15], v[132:135], v[210:213], v[12:15]
	v_mfma_f32_16x16x32_bf16 v[8:11], v[140:143], v[210:213], v[8:11]
	v_mfma_f32_16x16x32_bf16 v[52:55], v[144:147], v[160:163], v[52:55]
	v_mfma_f32_16x16x32_bf16 v[48:51], v[152:155], v[160:163], v[48:51]
	v_mfma_f32_16x16x32_bf16 v[36:39], v[144:147], v[190:193], v[36:39]
	v_mfma_f32_16x16x32_bf16 v[32:35], v[152:155], v[190:193], v[32:35]
	v_mfma_f32_16x16x32_bf16 v[20:23], v[144:147], v[198:201], v[20:23]
	v_mfma_f32_16x16x32_bf16 v[16:19], v[152:155], v[198:201], v[16:19]
	v_mfma_f32_16x16x32_bf16 v[4:7], v[144:147], v[206:209], v[4:7]
	v_mfma_f32_16x16x32_bf16 v[0:3], v[152:155], v[206:209], v[0:3]
	v_mfma_f32_16x16x32_bf16 v[52:55], v[148:151], v[186:189], v[52:55]
	v_mfma_f32_16x16x32_bf16 v[48:51], v[156:159], v[186:189], v[48:51]
	v_mfma_f32_16x16x32_bf16 v[36:39], v[148:151], v[194:197], v[36:39]
	v_mfma_f32_16x16x32_bf16 v[32:35], v[156:159], v[194:197], v[32:35]
	v_mfma_f32_16x16x32_bf16 v[20:23], v[148:151], v[202:205], v[20:23]
	v_mfma_f32_16x16x32_bf16 v[16:19], v[156:159], v[202:205], v[16:19]
	v_mfma_f32_16x16x32_bf16 v[4:7], v[148:151], v[210:213], v[4:7]
	v_mfma_f32_16x16x32_bf16 v[0:3], v[156:159], v[210:213], v[0:3]
	s_barrier
	s_add_i32 s71, s71, 2
	s_add_u32 s69, s69, 0x100
	s_addc_u32 s70, s70, 0
	s_cmp_gt_u32 s71, 61
	s_mov_b64 s[94:95], s[96:97]
	s_cbranch_scc0 .LBB0_1310
	s_setprio 0
	s_and_b64 vcc, exec, s[12:13]
	s_cbranch_vccz .LBB0_1313
	s_barrier

; #define PG8_STAGE(bufoff, gbase, voff) do { _Pragma("unroll") for (int _i = 0; _i < 2; ++_i) \
;         __builtin_amdgcn_global_load_lds((const unsigned*)((const char*)(gbase) + (voff)[_i]), (PG8_LAS unsigned*)(lds + (bufoff) + ldsw + _i * 8192), 16, 0, 0); } while (0)
; #define PG8_LDA(dst, b, h) do { _Pragma("unroll") for (int m = 0; m < 4; ++m) _Pragma("unroll") for (int k = 0; k < 2; ++k) dst[m][k] = *(const PG8_LAS bf16x8*)(lds + PG8_SA(b, h) + aoff + m * 2048 + k * 1024); } while (0)
; #define PG8_LDB(dst, b, h) do { _Pragma("unroll") for (int n = 0; n < 2; ++n) _Pragma("unroll") for (int k = 0; k < 2; ++k) dst[n][k] = *(const PG8_LAS bf16x8*)(lds + PG8_SB(b, h) + boff + n * 2048 + k * 1024); } while (0)
; template <class Epi, class Sched, bool ALIGN_EPI = false, bool SP2 = false>
; __device__ __forceinline__ void gemm_phase(PG8_LAS unsigned char* lds, const Gemm g, const Sched& S, const Epi& E) {
;     ...
;     for (;;) {
;         const bool has_next = S.next(ui + 1, nxt);
;         const char* nA = has_next ? (const char*)g.A + (size_t)nxt.pm * tstep : cA; const char* nB = has_next ? (const char*)g.Bt + (size_t)nxt.pn * tstep : cB;
;         for (int t = 0; t < nt; t += 2) {
;             const bool last = (t == nt - 2);
;             const char* a1 = cA + (size_t)(t + 1) * kstepA;
;             const char* a2 = last ? nA : cA + (size_t)(t + 2) * kstepA; const char* b2 = last ? nB : cB + (size_t)(t + 2) * kstep;
;             const char* a3 = a2 + kstepA; const char* b3 = b2 + kstep;
;             if (last && has_next) S.a_ready(nxt);
;             if constexpr (SP2) {
;             PG8_LDB(B0, 0, 0); PG8_LDB(B1, 0, 1); PG8_SCHED; PG8_LDA(At, 0, 0); PG8_STAGE(PG8_SA(1, 1), a1 + hstepA, voffA);
;             PG8_WAIT_V(8); PG8_WAIT_L(0); PG8_BAR; PG8_MMA(0, 0, At, B0); PG8_MMA(0, 1, At, B1); PG8_BAR; PG8_SCHED;
;             PG8_LDA(At, 0, 1); PG8_STAGE(PG8_SB(0, 0), b2, voffB); PG8_STAGE(PG8_SB(0, 1), b2 + hstep, voffB); PG8_STAGE(PG8_SA(0, 0), a2, voffA);
;             PG8_WAIT_V(8); PG8_WAIT_L(0); PG8_BAR; PG8_MMA(1, 0, At, B0); PG8_MMA(1, 1, At, B1); PG8_BAR; PG8_SCHED;
;     ...
;         for (int a = 0; a < 2; ++a)
; #pragma unroll
;             for (int b = 0; b < 2; ++b)
; #pragma unroll
;                 for (int m = 0; m < 4; ++m)
; #pragma unroll
;                     for (int n = 0; n < 2; ++n) acc[a][b][m][n] = (f32x4){0.f, 0.f, 0.f, 0.f};
.LBB0_1514:
	s_add_u32 s61, s22, 0x100
	s_addc_u32 s62, s23, 0
	s_add_u32 s22, s24, 0xc000
	v_mov_b32_e32 v0, 0
	s_addc_u32 s23, s25, 0
	s_mov_b32 s63, -2
	s_waitcnt lgkmcnt(0)
	v_mov_b32_e32 v1, v0
	v_mov_b32_e32 v2, v0
	v_mov_b32_e32 v3, v0
	v_mov_b32_e32 v4, v0
	v_mov_b32_e32 v5, v0
	v_mov_b32_e32 v6, v0
	v_mov_b32_e32 v7, v0
	v_mov_b32_e32 v16, v0
	v_mov_b32_e32 v17, v0
	v_mov_b32_e32 v18, v0
	v_mov_b32_e32 v19, v0
	v_mov_b32_e32 v20, v0
	v_mov_b32_e32 v21, v0
	v_mov_b32_e32 v22, v0
	v_mov_b32_e32 v23, v0
	v_mov_b32_e32 v32, v0
	v_mov_b32_e32 v33, v0
	v_mov_b32_e32 v34, v0
	v_mov_b32_e32 v35, v0
	s_waitcnt vmcnt(0)
	v_mov_b32_e32 v36, v0
	v_mov_b32_e32 v37, v0
	v_mov_b32_e32 v38, v0
	v_mov_b32_e32 v39, v0
	v_mov_b32_e32 v56, v0
	v_mov_b32_e32 v57, v0
	v_mov_b32_e32 v58, v0
	v_mov_b32_e32 v59, v0
	v_mov_b32_e32 v60, v0
	v_mov_b32_e32 v61, v0
	v_mov_b32_e32 v62, v0
	v_mov_b32_e32 v63, v0
	v_mov_b32_e32 v8, v0
	v_mov_b32_e32 v9, v0
	v_mov_b32_e32 v10, v0
	v_mov_b32_e32 v11, v0
	v_mov_b32_e32 v12, v0
	v_mov_b32_e32 v13, v0
	v_mov_b32_e32 v14, v0
	v_mov_b32_e32 v15, v0
	v_mov_b32_e32 v24, v0
	v_mov_b32_e32 v25, v0
	v_mov_b32_e32 v26, v0
	v_mov_b32_e32 v27, v0
	v_mov_b32_e32 v28, v0
	v_mov_b32_e32 v29, v0
	v_mov_b32_e32 v30, v0
	v_mov_b32_e32 v31, v0
	v_mov_b32_e32 v40, v0
	v_mov_b32_e32 v41, v0
	v_mov_b32_e32 v42, v0
	v_mov_b32_e32 v43, v0
	v_mov_b32_e32 v44, v0
	v_mov_b32_e32 v45, v0
	v_mov_b32_e32 v46, v0
	v_mov_b32_e32 v47, v0
	v_mov_b32_e32 v68, v0
	v_mov_b32_e32 v69, v0
	v_mov_b32_e32 v70, v0
	v_mov_b32_e32 v71, v0
	v_mov_b32_e32 v72, v0
	v_mov_b32_e32 v73, v0
	v_mov_b32_e32 v74, v0
	v_mov_b32_e32 v75, v0
	v_mov_b32_e32 v84, v0
	v_mov_b32_e32 v85, v0
	v_mov_b32_e32 v86, v0
	v_mov_b32_e32 v87, v0
	v_mov_b32_e32 v88, v0
	v_mov_b32_e32 v89, v0
	v_mov_b32_e32 v90, v0
	v_mov_b32_e32 v91, v0
	v_mov_b32_e32 v76, v0
	v_mov_b32_e32 v77, v0
	v_mov_b32_e32 v78, v0
	v_mov_b32_e32 v79, v0
	v_mov_b32_e32 v96, v0
	v_mov_b32_e32 v97, v0
	v_mov_b32_e32 v98, v0
	v_mov_b32_e32 v99, v0
	v_mov_b32_e32 v52, v0
	v_mov_b32_e32 v53, v0
	v_mov_b32_e32 v54, v0
	v_mov_b32_e32 v55, v0
	v_mov_b32_e32 v104, v0
	v_mov_b32_e32 v105, v0
	v_mov_b32_e32 v106, v0
	v_mov_b32_e32 v107, v0
	v_mov_b32_e32 v112, v0
	v_mov_b32_e32 v113, v0
	v_mov_b32_e32 v114, v0
	v_mov_b32_e32 v115, v0
	v_mov_b32_e32 v116, v0
	v_mov_b32_e32 v117, v0
	v_mov_b32_e32 v118, v0
	v_mov_b32_e32 v119, v0
	v_mov_b32_e32 v80, v0
	v_mov_b32_e32 v81, v0
	v_mov_b32_e32 v82, v0
	v_mov_b32_e32 v83, v0
	v_mov_b32_e32 v92, v0
	v_mov_b32_e32 v93, v0
	v_mov_b32_e32 v94, v0
	v_mov_b32_e32 v95, v0
	v_mov_b32_e32 v64, v0
	v_mov_b32_e32 v65, v0
	v_mov_b32_e32 v66, v0
	v_mov_b32_e32 v67, v0
	v_mov_b32_e32 v100, v0
	v_mov_b32_e32 v101, v0
	v_mov_b32_e32 v102, v0
	v_mov_b32_e32 v103, v0
	v_mov_b32_e32 v48, v0
	v_mov_b32_e32 v49, v0
	v_mov_b32_e32 v50, v0
	v_mov_b32_e32 v51, v0
	v_mov_b32_e32 v108, v0
	v_mov_b32_e32 v109, v0
	v_mov_b32_e32 v110, v0
	v_mov_b32_e32 v111, v0
	v_mov_b32_e32 v120, v0
	v_mov_b32_e32 v121, v0
	v_mov_b32_e32 v122, v0
	v_mov_b32_e32 v123, v0
	v_mov_b32_e32 v124, v0
	v_mov_b32_e32 v125, v0
	v_mov_b32_e32 v126, v0
	v_mov_b32_e32 v127, v0
	s_cmp_ge_u32 s33, 0x1000
	s_cbranch_scc1 .Lsprio_7
	s_setprio 1
.Lsprio_7:
.LBB0_1515:
	ds_read_b128 v[144:147], v153
	ds_read_b128 v[158:161], v153 offset:1024
	ds_read_b128 v[162:165], v153 offset:2048
	ds_read_b128 v[166:169], v153 offset:3072
	ds_read_b128 v[170:173], v154
	ds_read_b128 v[174:177], v154 offset:1024
	ds_read_b128 v[178:181], v154 offset:2048
	ds_read_b128 v[182:185], v154 offset:3072
	s_add_u32 s24, s22, 0x4000
	s_addc_u32 s25, s23, 0
	s_cmpk_eq_i32 s63, 0xa8
	s_cselect_b32 s30, s6, s24
	s_cselect_b32 s31, s7, s25
	s_cselect_b32 s26, s20, s61
	s_cselect_b32 s27, s21, s62
	s_add_u32 s24, s30, 0x8000
	s_addc_u32 s25, s31, 0
	s_add_i32 m0, s34, 0xc000
	ds_read_b128 v[186:189], v155
	ds_read_b128 v[190:193], v155 offset:1024
	ds_read_b128 v[194:197], v155 offset:2048
	ds_read_b128 v[198:201], v155 offset:3072
	ds_read_b128 v[202:205], v155 offset:4096
	ds_read_b128 v[206:209], v155 offset:5120
	ds_read_b128 v[210:213], v155 offset:6144
	ds_read_b128 v[214:217], v155 offset:7168
	global_load_lds_dwordx4 v136, s[22:23]
	s_add_i32 m0, s34, 0xe000
	s_nop 0
	global_load_lds_dwordx4 v138, s[22:23]
	s_waitcnt vmcnt(8)
	s_waitcnt lgkmcnt(0)
	s_barrier
	v_mfma_f32_16x16x32_bf16 v[124:127], v[144:147], v[186:189], v[124:127]
	v_mfma_f32_16x16x32_bf16 v[120:123], v[162:165], v[186:189], v[120:123]
	v_mfma_f32_16x16x32_bf16 v[108:111], v[144:147], v[194:197], v[108:111]
	v_mfma_f32_16x16x32_bf16 v[48:51], v[162:165], v[194:197], v[48:51]
	v_mfma_f32_16x16x32_bf16 v[100:103], v[144:147], v[202:205], v[100:103]
	v_mfma_f32_16x16x32_bf16 v[64:67], v[162:165], v[202:205], v[64:67]
	v_mfma_f32_16x16x32_bf16 v[92:95], v[144:147], v[210:213], v[92:95]
	v_mfma_f32_16x16x32_bf16 v[80:83], v[162:165], v[210:213], v[80:83]
	v_mfma_f32_16x16x32_bf16 v[124:127], v[158:161], v[190:193], v[124:127]
	v_mfma_f32_16x16x32_bf16 v[120:123], v[166:169], v[190:193], v[120:123]
	v_mfma_f32_16x16x32_bf16 v[108:111], v[158:161], v[198:201], v[108:111]
	v_mfma_f32_16x16x32_bf16 v[48:51], v[166:169], v[198:201], v[48:51]
	v_mfma_f32_16x16x32_bf16 v[100:103], v[158:161], v[206:209], v[100:103]
	v_mfma_f32_16x16x32_bf16 v[64:67], v[166:169], v[206:209], v[64:67]
	v_mfma_f32_16x16x32_bf16 v[92:95], v[158:161], v[214:217], v[92:95]
	v_mfma_f32_16x16x32_bf16 v[80:83], v[166:169], v[214:217], v[80:83]
	v_mfma_f32_16x16x32_bf16 v[116:119], v[170:173], v[186:189], v[116:119]
	v_mfma_f32_16x16x32_bf16 v[112:115], v[178:181], v[186:189], v[112:115]
	v_mfma_f32_16x16x32_bf16 v[104:107], v[170:173], v[194:197], v[104:107]
	v_mfma_f32_16x16x32_bf16 v[52:55], v[178:181], v[194:197], v[52:55]
	v_mfma_f32_16x16x32_bf16 v[96:99], v[170:173], v[202:205], v[96:99]
	v_mfma_f32_16x16x32_bf16 v[76:79], v[178:181], v[202:205], v[76:79]
	v_mfma_f32_16x16x32_bf16 v[88:91], v[170:173], v[210:213], v[88:91]
	v_mfma_f32_16x16x32_bf16 v[84:87], v[178:181], v[210:213], v[84:87]
	v_mfma_f32_16x16x32_bf16 v[116:119], v[174:177], v[190:193], v[116:119]
	v_mfma_f32_16x16x32_bf16 v[112:115], v[182:185], v[190:193], v[112:115]
	v_mfma_f32_16x16x32_bf16 v[104:107], v[174:177], v[198:201], v[104:107]
	v_mfma_f32_16x16x32_bf16 v[52:55], v[182:185], v[198:201], v[52:55]
	v_mfma_f32_16x16x32_bf16 v[96:99], v[174:177], v[206:209], v[96:99]
	v_mfma_f32_16x16x32_bf16 v[76:79], v[182:185], v[206:209], v[76:79]
	v_mfma_f32_16x16x32_bf16 v[88:91], v[174:177], v[214:217], v[88:91]
	v_mfma_f32_16x16x32_bf16 v[84:87], v[182:185], v[214:217], v[84:87]
	s_barrier
; #define PG8_STAGE(bufoff, gbase, voff) do { _Pragma("unroll") for (int _i = 0; _i < 2; ++_i) \
;         __builtin_amdgcn_global_load_lds((const unsigned*)((const char*)(gbase) + (voff)[_i]), (PG8_LAS unsigned*)(lds + (bufoff) + ldsw + _i * 8192), 16, 0, 0); } while (0)
; #define PG8_LDA(dst, b, h) do { _Pragma("unroll") for (int m = 0; m < 4; ++m) _Pragma("unroll") for (int k = 0; k < 2; ++k) dst[m][k] = *(const PG8_LAS bf16x8*)(lds + PG8_SA(b, h) + aoff + m * 2048 + k * 1024); } while (0)
; #define PG8_LDB(dst, b, h) do { _Pragma("unroll") for (int n = 0; n < 2; ++n) _Pragma("unroll") for (int k = 0; k < 2; ++k) dst[n][k] = *(const PG8_LAS bf16x8*)(lds + PG8_SB(b, h) + boff + n * 2048 + k * 1024); } while (0)
; #define PG8_MMA(ai, bj, At, Bt) do { __builtin_amdgcn_s_setprio(1); _Pragma("unroll") for (int m = 0; m < 4; ++m) _Pragma("unroll") for (int n = 0; n < 2; ++n) _Pragma("unroll") for (int k = 0; k < 2; ++k) \
;         acc[ai][bj][m][n] = __builtin_amdgcn_mfma_f32_16x16x32_bf16(Bt[n][k], At[m][k], acc[ai][bj][m][n], 0, 0, 0); __builtin_amdgcn_s_setprio(0); } while (0)
; #define PG8_WAIT_V(n) asm volatile("s_waitcnt vmcnt(" #n ")" ::: "memory")
; #define PG8_WAIT_L(n) asm volatile("s_waitcnt lgkmcnt(" #n ")" ::: "memory")
; #define PG8_BAR __builtin_amdgcn_s_barrier()
; #define PG8_SCHED __builtin_amdgcn_sched_barrier(0)
; template <class Epi, class Sched, bool ALIGN_EPI = false, bool SP2 = false>
; __device__ __forceinline__ void gemm_phase(PG8_LAS unsigned char* lds, const Gemm g, const Sched& S, const Epi& E) {
;     ...
;             PG8_LDA(At, 0, 1); PG8_STAGE(PG8_SB(0, 0), b2, voffB); PG8_STAGE(PG8_SB(0, 1), b2 + hstep, voffB); PG8_STAGE(PG8_SA(0, 0), a2, voffA);
;             PG8_WAIT_V(8); PG8_WAIT_L(0); PG8_BAR; PG8_MMA(1, 0, At, B0); PG8_MMA(1, 1, At, B1); PG8_BAR; PG8_SCHED;
;             PG8_LDB(B0, 1, 0); PG8_LDB(B1, 1, 1); PG8_SCHED; PG8_LDA(At, 1, 0); PG8_STAGE(PG8_SA(0, 1), a2 + hstepA, voffA);
	s_add_u32 s98, s26, s16
	s_addc_u32 s99, s27, s17
	s_add_i32 s64, s55, s33
	s_mov_b32 m0, s64
	ds_read_b128 v[186:189], v155 offset:16384
	ds_read_b128 v[190:193], v155 offset:17408
	ds_read_b128 v[194:197], v155 offset:18432
	ds_read_b128 v[198:201], v155 offset:19456
	ds_read_b128 v[202:205], v155 offset:20480
	ds_read_b128 v[206:209], v155 offset:21504
	ds_read_b128 v[210:213], v155 offset:22528
	ds_read_b128 v[214:217], v155 offset:23552
	global_load_lds_dwordx4 v130, s[26:27]
	s_add_i32 m0, s64, 0x2000
	s_add_u32 s64, s26, 0x2b0000
	s_addc_u32 s65, s27, 0
	s_add_i32 s66, s56, s33
	global_load_lds_dwordx4 v134, s[26:27]
	s_mov_b32 m0, s66
	s_nop 0
	global_load_lds_dwordx4 v130, s[64:65]
	s_add_i32 m0, s66, 0x2000
	s_nop 0
	global_load_lds_dwordx4 v134, s[64:65]
	s_mov_b32 m0, s34
	s_nop 0
	global_load_lds_dwordx4 v128, s[30:31]
	s_mov_b32 m0, s35
	s_nop 0
	global_load_lds_dwordx4 v132, s[30:31]
	s_waitcnt vmcnt(8)
	s_waitcnt lgkmcnt(0)
	s_barrier
	v_mfma_f32_16x16x32_bf16 v[72:75], v[144:147], v[186:189], v[72:75]
	v_mfma_f32_16x16x32_bf16 v[68:71], v[162:165], v[186:189], v[68:71]
	v_mfma_f32_16x16x32_bf16 v[44:47], v[144:147], v[194:197], v[44:47]
	v_mfma_f32_16x16x32_bf16 v[40:43], v[162:165], v[194:197], v[40:43]
	v_mfma_f32_16x16x32_bf16 v[28:31], v[144:147], v[202:205], v[28:31]
	v_mfma_f32_16x16x32_bf16 v[24:27], v[162:165], v[202:205], v[24:27]
	v_mfma_f32_16x16x32_bf16 v[12:15], v[144:147], v[210:213], v[12:15]
	v_mfma_f32_16x16x32_bf16 v[8:11], v[162:165], v[210:213], v[8:11]
	v_mfma_f32_16x16x32_bf16 v[72:75], v[158:161], v[190:193], v[72:75]
	v_mfma_f32_16x16x32_bf16 v[68:71], v[166:169], v[190:193], v[68:71]
	v_mfma_f32_16x16x32_bf16 v[44:47], v[158:161], v[198:201], v[44:47]
	v_mfma_f32_16x16x32_bf16 v[40:43], v[166:169], v[198:201], v[40:43]
	v_mfma_f32_16x16x32_bf16 v[28:31], v[158:161], v[206:209], v[28:31]
	v_mfma_f32_16x16x32_bf16 v[24:27], v[166:169], v[206:209], v[24:27]
	v_mfma_f32_16x16x32_bf16 v[12:15], v[158:161], v[214:217], v[12:15]
	v_mfma_f32_16x16x32_bf16 v[8:11], v[166:169], v[214:217], v[8:11]
	v_mfma_f32_16x16x32_bf16 v[60:63], v[170:173], v[186:189], v[60:63]
	v_mfma_f32_16x16x32_bf16 v[56:59], v[178:181], v[186:189], v[56:59]
	v_mfma_f32_16x16x32_bf16 v[36:39], v[170:173], v[194:197], v[36:39]
	v_mfma_f32_16x16x32_bf16 v[32:35], v[178:181], v[194:197], v[32:35]
	v_mfma_f32_16x16x32_bf16 v[20:23], v[170:173], v[202:205], v[20:23]
	v_mfma_f32_16x16x32_bf16 v[16:19], v[178:181], v[202:205], v[16:19]
	v_mfma_f32_16x16x32_bf16 v[4:7], v[170:173], v[210:213], v[4:7]
	v_mfma_f32_16x16x32_bf16 v[0:3], v[178:181], v[210:213], v[0:3]
	v_mfma_f32_16x16x32_bf16 v[60:63], v[174:177], v[190:193], v[60:63]
	v_mfma_f32_16x16x32_bf16 v[56:59], v[182:185], v[190:193], v[56:59]
	v_mfma_f32_16x16x32_bf16 v[36:39], v[174:177], v[198:201], v[36:39]
	v_mfma_f32_16x16x32_bf16 v[32:35], v[182:185], v[198:201], v[32:35]
	v_mfma_f32_16x16x32_bf16 v[20:23], v[174:177], v[206:209], v[20:23]
	v_mfma_f32_16x16x32_bf16 v[16:19], v[182:185], v[206:209], v[16:19]
	v_mfma_f32_16x16x32_bf16 v[4:7], v[174:177], v[214:217], v[4:7]
	v_mfma_f32_16x16x32_bf16 v[0:3], v[182:185], v[214:217], v[0:3]
	s_barrier
	s_add_i32 s64, 0, 0x18000
	v_add_u32_e32 v157, s64, v151
	s_add_i32 s65, 0, 0x1c000
	ds_read_b128 v[144:147], v157
	ds_read_b128 v[158:161], v157 offset:1024
	ds_read_b128 v[162:165], v157 offset:2048
	ds_read_b128 v[166:169], v157 offset:3072
	v_add_u32_e32 v157, s65, v151
	ds_read_b128 v[170:173], v157
	ds_read_b128 v[174:177], v157 offset:1024
	ds_read_b128 v[178:181], v157 offset:2048
	ds_read_b128 v[182:185], v157 offset:3072
	s_add_u32 s30, s30, 0x4000
	s_addc_u32 s31, s31, 0
	s_mov_b32 m0, s38
	ds_read_b128 v[186:189], v155 offset:32768
	ds_read_b128 v[190:193], v155 offset:33792
	ds_read_b128 v[194:197], v155 offset:34816
	ds_read_b128 v[198:201], v155 offset:35840
	ds_read_b128 v[202:205], v155 offset:36864
	ds_read_b128 v[206:209], v155 offset:37888
	ds_read_b128 v[210:213], v155 offset:38912
	ds_read_b128 v[214:217], v155 offset:39936
	global_load_lds_dwordx4 v128, s[30:31]
	s_mov_b32 m0, s39
	s_nop 0
	global_load_lds_dwordx4 v132, s[30:31]
	s_waitcnt vmcnt(8)
	s_waitcnt lgkmcnt(0)
	s_barrier
; #define PG8_STAGE(bufoff, gbase, voff) do { _Pragma("unroll") for (int _i = 0; _i < 2; ++_i) \
;         __builtin_amdgcn_global_load_lds((const unsigned*)((const char*)(gbase) + (voff)[_i]), (PG8_LAS unsigned*)(lds + (bufoff) + ldsw + _i * 8192), 16, 0, 0); } while (0)
; #define PG8_LDA(dst, b, h) do { _Pragma("unroll") for (int m = 0; m < 4; ++m) _Pragma("unroll") for (int k = 0; k < 2; ++k) dst[m][k] = *(const PG8_LAS bf16x8*)(lds + PG8_SA(b, h) + aoff + m * 2048 + k * 1024); } while (0)
; #define PG8_MMA(ai, bj, At, Bt) do { __builtin_amdgcn_s_setprio(1); _Pragma("unroll") for (int m = 0; m < 4; ++m) _Pragma("unroll") for (int n = 0; n < 2; ++n) _Pragma("unroll") for (int k = 0; k < 2; ++k) \
;         acc[ai][bj][m][n] = __builtin_amdgcn_mfma_f32_16x16x32_bf16(Bt[n][k], At[m][k], acc[ai][bj][m][n], 0, 0, 0); __builtin_amdgcn_s_setprio(0); } while (0)
; #define PG8_WAIT_V(n) asm volatile("s_waitcnt vmcnt(" #n ")" ::: "memory")
; #define PG8_WAIT_L(n) asm volatile("s_waitcnt lgkmcnt(" #n ")" ::: "memory")
; #define PG8_BAR __builtin_amdgcn_s_barrier()
; #define PG8_SCHED __builtin_amdgcn_sched_barrier(0)
; template <class Epi, class Sched, bool ALIGN_EPI = false, bool SP2 = false>
; __device__ __forceinline__ void gemm_phase(PG8_LAS unsigned char* lds, const Gemm g, const Sched& S, const Epi& E) {
;     ...
;             PG8_WAIT_V(8); PG8_WAIT_L(0); PG8_BAR; PG8_MMA(0, 0, At, B0); PG8_MMA(0, 1, At, B1); PG8_BAR; PG8_SCHED;
;             PG8_LDA(At, 1, 1); PG8_STAGE(PG8_SB(1, 0), b3, voffB); PG8_STAGE(PG8_SB(1, 1), b3 + hstep, voffB); PG8_STAGE(PG8_SA(1, 0), a3, voffA);
;             PG8_WAIT_V(8); PG8_WAIT_L(0); PG8_BAR; PG8_MMA(1, 0, At, B0); PG8_MMA(1, 1, At, B1); PG8_BAR; PG8_SCHED;
;     ...
;         if constexpr (ALIGN_EPI) { if (wr == 0) PG8_BAR; }
	v_mfma_f32_16x16x32_bf16 v[124:127], v[144:147], v[186:189], v[124:127]
	v_mfma_f32_16x16x32_bf16 v[120:123], v[162:165], v[186:189], v[120:123]
	v_mfma_f32_16x16x32_bf16 v[108:111], v[144:147], v[194:197], v[108:111]
	v_mfma_f32_16x16x32_bf16 v[48:51], v[162:165], v[194:197], v[48:51]
	v_mfma_f32_16x16x32_bf16 v[100:103], v[144:147], v[202:205], v[100:103]
	v_mfma_f32_16x16x32_bf16 v[64:67], v[162:165], v[202:205], v[64:67]
	v_mfma_f32_16x16x32_bf16 v[92:95], v[144:147], v[210:213], v[92:95]
	v_mfma_f32_16x16x32_bf16 v[80:83], v[162:165], v[210:213], v[80:83]
	v_mfma_f32_16x16x32_bf16 v[124:127], v[158:161], v[190:193], v[124:127]
	v_mfma_f32_16x16x32_bf16 v[120:123], v[166:169], v[190:193], v[120:123]
	v_mfma_f32_16x16x32_bf16 v[108:111], v[158:161], v[198:201], v[108:111]
	v_mfma_f32_16x16x32_bf16 v[48:51], v[166:169], v[198:201], v[48:51]
	v_mfma_f32_16x16x32_bf16 v[100:103], v[158:161], v[206:209], v[100:103]
	v_mfma_f32_16x16x32_bf16 v[64:67], v[166:169], v[206:209], v[64:67]
	v_mfma_f32_16x16x32_bf16 v[92:95], v[158:161], v[214:217], v[92:95]
	v_mfma_f32_16x16x32_bf16 v[80:83], v[166:169], v[214:217], v[80:83]
	v_mfma_f32_16x16x32_bf16 v[116:119], v[170:173], v[186:189], v[116:119]
	v_mfma_f32_16x16x32_bf16 v[112:115], v[178:181], v[186:189], v[112:115]
	v_mfma_f32_16x16x32_bf16 v[104:107], v[170:173], v[194:197], v[104:107]
	v_mfma_f32_16x16x32_bf16 v[52:55], v[178:181], v[194:197], v[52:55]
	v_mfma_f32_16x16x32_bf16 v[96:99], v[170:173], v[202:205], v[96:99]
	v_mfma_f32_16x16x32_bf16 v[76:79], v[178:181], v[202:205], v[76:79]
	v_mfma_f32_16x16x32_bf16 v[88:91], v[170:173], v[210:213], v[88:91]
	v_mfma_f32_16x16x32_bf16 v[84:87], v[178:181], v[210:213], v[84:87]
	v_mfma_f32_16x16x32_bf16 v[116:119], v[174:177], v[190:193], v[116:119]
	v_mfma_f32_16x16x32_bf16 v[112:115], v[182:185], v[190:193], v[112:115]
	v_mfma_f32_16x16x32_bf16 v[104:107], v[174:177], v[198:201], v[104:107]
	v_mfma_f32_16x16x32_bf16 v[52:55], v[182:185], v[198:201], v[52:55]
	v_mfma_f32_16x16x32_bf16 v[96:99], v[174:177], v[206:209], v[96:99]
	v_mfma_f32_16x16x32_bf16 v[76:79], v[182:185], v[206:209], v[76:79]
	v_mfma_f32_16x16x32_bf16 v[88:91], v[174:177], v[214:217], v[88:91]
	v_mfma_f32_16x16x32_bf16 v[84:87], v[182:185], v[214:217], v[84:87]
	s_barrier
	s_add_i32 s30, s64, s33
	s_mov_b32 m0, s30
	ds_read_b128 v[186:189], v155 offset:49152
	ds_read_b128 v[190:193], v155 offset:50176
	ds_read_b128 v[194:197], v155 offset:51200
	ds_read_b128 v[198:201], v155 offset:52224
	ds_read_b128 v[202:205], v155 offset:53248
	ds_read_b128 v[206:209], v155 offset:54272
	ds_read_b128 v[210:213], v155 offset:55296
	ds_read_b128 v[214:217], v155 offset:56320
	global_load_lds_dwordx4 v130, s[98:99]
	s_add_i32 m0, s30, 0x2000
	s_add_u32 s26, s26, 0x2b0080
	s_addc_u32 s27, s27, 0
	s_add_i32 s30, s65, s33
	global_load_lds_dwordx4 v134, s[98:99]
	s_mov_b32 m0, s30
	s_nop 0
	global_load_lds_dwordx4 v130, s[26:27]
	s_add_i32 m0, s30, 0x2000
	s_nop 0
	global_load_lds_dwordx4 v134, s[26:27]
	s_mov_b32 m0, s41
	s_nop 0
	global_load_lds_dwordx4 v128, s[24:25]
	s_mov_b32 m0, s52
	s_nop 0
	global_load_lds_dwordx4 v132, s[24:25]
	s_waitcnt vmcnt(8)
	s_waitcnt lgkmcnt(0)
	s_barrier
	v_mfma_f32_16x16x32_bf16 v[72:75], v[144:147], v[186:189], v[72:75]
	v_mfma_f32_16x16x32_bf16 v[68:71], v[162:165], v[186:189], v[68:71]
	v_mfma_f32_16x16x32_bf16 v[44:47], v[144:147], v[194:197], v[44:47]
	v_mfma_f32_16x16x32_bf16 v[40:43], v[162:165], v[194:197], v[40:43]
	v_mfma_f32_16x16x32_bf16 v[28:31], v[144:147], v[202:205], v[28:31]
	v_mfma_f32_16x16x32_bf16 v[24:27], v[162:165], v[202:205], v[24:27]
	v_mfma_f32_16x16x32_bf16 v[12:15], v[144:147], v[210:213], v[12:15]
	v_mfma_f32_16x16x32_bf16 v[8:11], v[162:165], v[210:213], v[8:11]
	v_mfma_f32_16x16x32_bf16 v[72:75], v[158:161], v[190:193], v[72:75]
	v_mfma_f32_16x16x32_bf16 v[68:71], v[166:169], v[190:193], v[68:71]
	v_mfma_f32_16x16x32_bf16 v[44:47], v[158:161], v[198:201], v[44:47]
	v_mfma_f32_16x16x32_bf16 v[40:43], v[166:169], v[198:201], v[40:43]
	v_mfma_f32_16x16x32_bf16 v[28:31], v[158:161], v[206:209], v[28:31]
	v_mfma_f32_16x16x32_bf16 v[24:27], v[166:169], v[206:209], v[24:27]
	v_mfma_f32_16x16x32_bf16 v[12:15], v[158:161], v[214:217], v[12:15]
	v_mfma_f32_16x16x32_bf16 v[8:11], v[166:169], v[214:217], v[8:11]
	v_mfma_f32_16x16x32_bf16 v[60:63], v[170:173], v[186:189], v[60:63]
	v_mfma_f32_16x16x32_bf16 v[56:59], v[178:181], v[186:189], v[56:59]
	v_mfma_f32_16x16x32_bf16 v[36:39], v[170:173], v[194:197], v[36:39]
	v_mfma_f32_16x16x32_bf16 v[32:35], v[178:181], v[194:197], v[32:35]
	v_mfma_f32_16x16x32_bf16 v[20:23], v[170:173], v[202:205], v[20:23]
	v_mfma_f32_16x16x32_bf16 v[16:19], v[178:181], v[202:205], v[16:19]
	v_mfma_f32_16x16x32_bf16 v[4:7], v[170:173], v[210:213], v[4:7]
	v_mfma_f32_16x16x32_bf16 v[0:3], v[178:181], v[210:213], v[0:3]
	v_mfma_f32_16x16x32_bf16 v[60:63], v[174:177], v[190:193], v[60:63]
	v_mfma_f32_16x16x32_bf16 v[56:59], v[182:185], v[190:193], v[56:59]
	v_mfma_f32_16x16x32_bf16 v[36:39], v[174:177], v[198:201], v[36:39]
	v_mfma_f32_16x16x32_bf16 v[32:35], v[182:185], v[198:201], v[32:35]
	v_mfma_f32_16x16x32_bf16 v[20:23], v[174:177], v[206:209], v[20:23]
	v_mfma_f32_16x16x32_bf16 v[16:19], v[182:185], v[206:209], v[16:19]
	v_mfma_f32_16x16x32_bf16 v[4:7], v[174:177], v[214:217], v[4:7]
	v_mfma_f32_16x16x32_bf16 v[0:3], v[182:185], v[214:217], v[0:3]
	s_barrier
	s_add_i32 s63, s63, 2
	s_add_u32 s61, s61, 0x100
	s_addc_u32 s62, s62, 0
	s_add_u32 s22, s22, 0x10000
	s_addc_u32 s23, s23, 0
	s_cmpk_gt_u32 s63, 0xa9
	s_cbranch_scc0 .LBB0_1515
	s_setprio 0
	s_and_b64 vcc, exec, s[18:19]
	s_cbranch_vccz .LBB0_1518
	s_barrier

; #define PG8_STAGE(bufoff, gbase, voff) do { _Pragma("unroll") for (int _i = 0; _i < 2; ++_i) \
;         __builtin_amdgcn_global_load_lds((const unsigned*)((const char*)(gbase) + (voff)[_i]), (PG8_LAS unsigned*)(lds + (bufoff) + ldsw + _i * 8192), 16, 0, 0); } while (0)
; #define PG8_LDA(dst, b, h) do { _Pragma("unroll") for (int m = 0; m < 4; ++m) _Pragma("unroll") for (int k = 0; k < 2; ++k) dst[m][k] = *(const PG8_LAS bf16x8*)(lds + PG8_SA(b, h) + aoff + m * 2048 + k * 1024); } while (0)
; #define PG8_LDB(dst, b, h) do { _Pragma("unroll") for (int n = 0; n < 2; ++n) _Pragma("unroll") for (int k = 0; k < 2; ++k) dst[n][k] = *(const PG8_LAS bf16x8*)(lds + PG8_SB(b, h) + boff + n * 2048 + k * 1024); } while (0)
; #define PG8_WAIT_V(n) asm volatile("s_waitcnt vmcnt(" #n ")" ::: "memory")
; #define PG8_WAIT_L(n) asm volatile("s_waitcnt lgkmcnt(" #n ")" ::: "memory")
; #define PG8_BAR __builtin_amdgcn_s_barrier()
; #define PG8_SCHED __builtin_amdgcn_sched_barrier(0)
; template <class Epi, class Sched, bool ALIGN_EPI = false, bool SP2 = false>
; __device__ __forceinline__ void gemm_phase(PG8_LAS unsigned char* lds, const Gemm g, const Sched& S, const Epi& E) {
;     ...
;     for (;;) {
;         const bool has_next = S.next(ui + 1, nxt);
;         const char* nA = has_next ? (const char*)g.A + (size_t)nxt.pm * tstep : cA; const char* nB = has_next ? (const char*)g.Bt + (size_t)nxt.pn * tstep : cB;
;         for (int t = 0; t < nt; t += 2) {
;             const bool last = (t == nt - 2);
;             const char* a1 = cA + (size_t)(t + 1) * kstepA;
;             const char* a2 = last ? nA : cA + (size_t)(t + 2) * kstepA; const char* b2 = last ? nB : cB + (size_t)(t + 2) * kstep;
;             const char* a3 = a2 + kstepA; const char* b3 = b2 + kstep;
;             if (last && has_next) S.a_ready(nxt);
;             if constexpr (SP2) {
;             PG8_LDB(B0, 0, 0); PG8_LDB(B1, 0, 1); PG8_SCHED; PG8_LDA(At, 0, 0); PG8_STAGE(PG8_SA(1, 1), a1 + hstepA, voffA);
;             PG8_WAIT_V(8); PG8_WAIT_L(0); PG8_BAR; PG8_MMA(0, 0, At, B0); PG8_MMA(0, 1, At, B1); PG8_BAR; PG8_SCHED;
;     ...
;         for (int a = 0; a < 2; ++a)
; #pragma unroll
;             for (int b = 0; b < 2; ++b)
; #pragma unroll
;                 for (int m = 0; m < 4; ++m)
; #pragma unroll
;                     for (int n = 0; n < 2; ++n) acc[a][b][m][n] = (f32x4){0.f, 0.f, 0.f, 0.f};
.LBB0_1630:
	s_ashr_i32 s25, s24, 31
	s_lshl_b64 s[26:27], s[24:25], 21
	s_add_u32 s26, s92, s26
	s_addc_u32 s27, s93, s27
	s_and_b64 s[30:31], s[4:5], exec
	s_cselect_b32 s25, s27, s85
	s_cselect_b32 s35, s26, s84
	s_ashr_i32 s23, s22, 31
	s_lshl_b64 s[30:31], s[22:23], 21
	s_add_u32 s30, s14, s30
	s_addc_u32 s31, s15, s31
	s_and_b64 s[62:63], s[4:5], exec
	s_cselect_b32 s23, s31, s87
	s_cselect_b32 s61, s30, s86
	s_add_u32 s84, s84, 0x100080
	s_addc_u32 s85, s85, 0
	s_add_u32 s62, s86, 0x100
	v_mov_b32_e32 v0, 0
	s_addc_u32 s63, s87, 0
	s_mov_b32 s64, -2
	s_waitcnt lgkmcnt(0)
	v_mov_b32_e32 v1, v0
	v_mov_b32_e32 v2, v0
	v_mov_b32_e32 v3, v0
	v_mov_b32_e32 v4, v0
	v_mov_b32_e32 v5, v0
	v_mov_b32_e32 v6, v0
	v_mov_b32_e32 v7, v0
	v_mov_b32_e32 v16, v0
	v_mov_b32_e32 v17, v0
	v_mov_b32_e32 v18, v0
	v_mov_b32_e32 v19, v0
	v_mov_b32_e32 v20, v0
	v_mov_b32_e32 v21, v0
	v_mov_b32_e32 v22, v0
	v_mov_b32_e32 v23, v0
	s_waitcnt vmcnt(0)
	v_mov_b32_e32 v36, v0
	v_mov_b32_e32 v37, v0
	v_mov_b32_e32 v38, v0
	v_mov_b32_e32 v39, v0
	v_mov_b32_e32 v40, v0
	v_mov_b32_e32 v41, v0
	v_mov_b32_e32 v42, v0
	v_mov_b32_e32 v43, v0
	v_mov_b32_e32 v60, v0
	v_mov_b32_e32 v61, v0
	v_mov_b32_e32 v62, v0
	v_mov_b32_e32 v63, v0
	v_mov_b32_e32 v64, v0
	v_mov_b32_e32 v65, v0
	v_mov_b32_e32 v66, v0
	v_mov_b32_e32 v67, v0
	v_mov_b32_e32 v8, v0
	v_mov_b32_e32 v9, v0
	v_mov_b32_e32 v10, v0
	v_mov_b32_e32 v11, v0
	v_mov_b32_e32 v12, v0
	v_mov_b32_e32 v13, v0
	v_mov_b32_e32 v14, v0
	v_mov_b32_e32 v15, v0
	v_mov_b32_e32 v24, v0
	v_mov_b32_e32 v25, v0
	v_mov_b32_e32 v26, v0
	v_mov_b32_e32 v27, v0
	v_mov_b32_e32 v28, v0
	v_mov_b32_e32 v29, v0
	v_mov_b32_e32 v30, v0
	v_mov_b32_e32 v31, v0
	v_mov_b32_e32 v48, v0
	v_mov_b32_e32 v49, v0
	v_mov_b32_e32 v50, v0
	v_mov_b32_e32 v51, v0
	v_mov_b32_e32 v56, v0
	v_mov_b32_e32 v57, v0
	v_mov_b32_e32 v58, v0
	v_mov_b32_e32 v59, v0
	v_mov_b32_e32 v76, v0
	v_mov_b32_e32 v77, v0
	v_mov_b32_e32 v78, v0
	v_mov_b32_e32 v79, v0
	v_mov_b32_e32 v80, v0
	v_mov_b32_e32 v81, v0
	v_mov_b32_e32 v82, v0
	v_mov_b32_e32 v83, v0
	v_mov_b32_e32 v84, v0
	v_mov_b32_e32 v85, v0
	v_mov_b32_e32 v86, v0
	v_mov_b32_e32 v87, v0
	v_mov_b32_e32 v88, v0
	v_mov_b32_e32 v89, v0
	v_mov_b32_e32 v90, v0
	v_mov_b32_e32 v91, v0
	v_mov_b32_e32 v68, v0
	v_mov_b32_e32 v69, v0
	v_mov_b32_e32 v70, v0
	v_mov_b32_e32 v71, v0
	v_mov_b32_e32 v96, v0
	v_mov_b32_e32 v97, v0
	v_mov_b32_e32 v98, v0
	v_mov_b32_e32 v99, v0
	v_mov_b32_e32 v44, v0
	v_mov_b32_e32 v45, v0
	v_mov_b32_e32 v46, v0
	v_mov_b32_e32 v47, v0
	v_mov_b32_e32 v104, v0
	v_mov_b32_e32 v105, v0
	v_mov_b32_e32 v106, v0
	v_mov_b32_e32 v107, v0
	v_mov_b32_e32 v112, v0
	v_mov_b32_e32 v113, v0
	v_mov_b32_e32 v114, v0
	v_mov_b32_e32 v115, v0
	v_mov_b32_e32 v116, v0
	v_mov_b32_e32 v117, v0
	v_mov_b32_e32 v118, v0
	v_mov_b32_e32 v119, v0
	v_mov_b32_e32 v72, v0
	v_mov_b32_e32 v73, v0
	v_mov_b32_e32 v74, v0
	v_mov_b32_e32 v75, v0
	v_mov_b32_e32 v92, v0
	v_mov_b32_e32 v93, v0
	v_mov_b32_e32 v94, v0
	v_mov_b32_e32 v95, v0
	v_mov_b32_e32 v52, v0
	v_mov_b32_e32 v53, v0
	v_mov_b32_e32 v54, v0
	v_mov_b32_e32 v55, v0
	v_mov_b32_e32 v100, v0
	v_mov_b32_e32 v101, v0
	v_mov_b32_e32 v102, v0
	v_mov_b32_e32 v103, v0
	v_mov_b32_e32 v32, v0
	v_mov_b32_e32 v33, v0
	v_mov_b32_e32 v34, v0
	v_mov_b32_e32 v35, v0
	v_mov_b32_e32 v108, v0
	v_mov_b32_e32 v109, v0
	v_mov_b32_e32 v110, v0
	v_mov_b32_e32 v111, v0
	v_mov_b32_e32 v120, v0
	v_mov_b32_e32 v121, v0
	v_mov_b32_e32 v122, v0
	v_mov_b32_e32 v123, v0
	v_mov_b32_e32 v124, v0
	v_mov_b32_e32 v125, v0
	v_mov_b32_e32 v126, v0
	v_mov_b32_e32 v127, v0
	s_cmp_ge_u32 s3, 0x1000
	s_cbranch_scc1 .Lsprio_6
	s_setprio 1
.Lsprio_6:
.LBB0_1631:
	ds_read_b128 v[144:147], v155
	ds_read_b128 v[148:151], v155 offset:1024
	ds_read_b128 v[160:163], v155 offset:2048
	ds_read_b128 v[164:167], v155 offset:3072
	ds_read_b128 v[168:171], v156
	ds_read_b128 v[172:175], v156 offset:1024
	ds_read_b128 v[176:179], v156 offset:2048
	ds_read_b128 v[180:183], v156 offset:3072
	s_add_u32 s65, s84, 0xfff00080
	s_addc_u32 s66, s85, -1
	s_cmp_eq_u32 s64, 60
	s_cselect_b32 s89, s25, s66
	s_cselect_b32 s88, s35, s65
	s_cselect_b32 s87, s23, s63
	s_cselect_b32 s86, s61, s62
	s_add_i32 m0, s29, 0xc000
	ds_read_b128 v[184:187], v157
	ds_read_b128 v[188:191], v157 offset:1024
	ds_read_b128 v[192:195], v157 offset:2048
	ds_read_b128 v[196:199], v157 offset:3072
	ds_read_b128 v[200:203], v157 offset:4096
	ds_read_b128 v[204:207], v157 offset:5120
	ds_read_b128 v[208:211], v157 offset:6144
	ds_read_b128 v[212:215], v157 offset:7168
	global_load_lds_dwordx4 v136, s[84:85]
	s_add_i32 m0, s29, 0xe000
	s_nop 0
	global_load_lds_dwordx4 v138, s[84:85]
	s_waitcnt vmcnt(8)
	s_waitcnt lgkmcnt(0)
	s_barrier
; #define PG8_STAGE(bufoff, gbase, voff) do { _Pragma("unroll") for (int _i = 0; _i < 2; ++_i) \
;         __builtin_amdgcn_global_load_lds((const unsigned*)((const char*)(gbase) + (voff)[_i]), (PG8_LAS unsigned*)(lds + (bufoff) + ldsw + _i * 8192), 16, 0, 0); } while (0)
; #define PG8_LDA(dst, b, h) do { _Pragma("unroll") for (int m = 0; m < 4; ++m) _Pragma("unroll") for (int k = 0; k < 2; ++k) dst[m][k] = *(const PG8_LAS bf16x8*)(lds + PG8_SA(b, h) + aoff + m * 2048 + k * 1024); } while (0)
; #define PG8_MMA(ai, bj, At, Bt) do { __builtin_amdgcn_s_setprio(1); _Pragma("unroll") for (int m = 0; m < 4; ++m) _Pragma("unroll") for (int n = 0; n < 2; ++n) _Pragma("unroll") for (int k = 0; k < 2; ++k) \
;         acc[ai][bj][m][n] = __builtin_amdgcn_mfma_f32_16x16x32_bf16(Bt[n][k], At[m][k], acc[ai][bj][m][n], 0, 0, 0); __builtin_amdgcn_s_setprio(0); } while (0)
; #define PG8_WAIT_V(n) asm volatile("s_waitcnt vmcnt(" #n ")" ::: "memory")
; #define PG8_WAIT_L(n) asm volatile("s_waitcnt lgkmcnt(" #n ")" ::: "memory")
; #define PG8_BAR __builtin_amdgcn_s_barrier()
; #define PG8_SCHED __builtin_amdgcn_sched_barrier(0)
; template <class Epi, class Sched, bool ALIGN_EPI = false, bool SP2 = false>
; __device__ __forceinline__ void gemm_phase(PG8_LAS unsigned char* lds, const Gemm g, const Sched& S, const Epi& E) {
;     ...
;             PG8_WAIT_V(8); PG8_WAIT_L(0); PG8_BAR; PG8_MMA(0, 0, At, B0); PG8_MMA(0, 1, At, B1); PG8_BAR; PG8_SCHED;
;             PG8_LDA(At, 0, 1); PG8_STAGE(PG8_SB(0, 0), b2, voffB); PG8_STAGE(PG8_SB(0, 1), b2 + hstep, voffB); PG8_STAGE(PG8_SA(0, 0), a2, voffA);
;             PG8_WAIT_V(8); PG8_WAIT_L(0); PG8_BAR; PG8_MMA(1, 0, At, B0); PG8_MMA(1, 1, At, B1); PG8_BAR; PG8_SCHED;
	v_mfma_f32_16x16x32_bf16 v[124:127], v[144:147], v[184:187], v[124:127]
	v_mfma_f32_16x16x32_bf16 v[120:123], v[160:163], v[184:187], v[120:123]
	v_mfma_f32_16x16x32_bf16 v[108:111], v[144:147], v[192:195], v[108:111]
	v_mfma_f32_16x16x32_bf16 v[32:35], v[160:163], v[192:195], v[32:35]
	v_mfma_f32_16x16x32_bf16 v[100:103], v[144:147], v[200:203], v[100:103]
	v_mfma_f32_16x16x32_bf16 v[52:55], v[160:163], v[200:203], v[52:55]
	v_mfma_f32_16x16x32_bf16 v[92:95], v[144:147], v[208:211], v[92:95]
	v_mfma_f32_16x16x32_bf16 v[72:75], v[160:163], v[208:211], v[72:75]
	v_mfma_f32_16x16x32_bf16 v[124:127], v[148:151], v[188:191], v[124:127]
	v_mfma_f32_16x16x32_bf16 v[120:123], v[164:167], v[188:191], v[120:123]
	v_mfma_f32_16x16x32_bf16 v[108:111], v[148:151], v[196:199], v[108:111]
	v_mfma_f32_16x16x32_bf16 v[32:35], v[164:167], v[196:199], v[32:35]
	v_mfma_f32_16x16x32_bf16 v[100:103], v[148:151], v[204:207], v[100:103]
	v_mfma_f32_16x16x32_bf16 v[52:55], v[164:167], v[204:207], v[52:55]
	v_mfma_f32_16x16x32_bf16 v[92:95], v[148:151], v[212:215], v[92:95]
	v_mfma_f32_16x16x32_bf16 v[72:75], v[164:167], v[212:215], v[72:75]
	v_mfma_f32_16x16x32_bf16 v[116:119], v[168:171], v[184:187], v[116:119]
	v_mfma_f32_16x16x32_bf16 v[112:115], v[176:179], v[184:187], v[112:115]
	v_mfma_f32_16x16x32_bf16 v[104:107], v[168:171], v[192:195], v[104:107]
	v_mfma_f32_16x16x32_bf16 v[44:47], v[176:179], v[192:195], v[44:47]
	v_mfma_f32_16x16x32_bf16 v[96:99], v[168:171], v[200:203], v[96:99]
	v_mfma_f32_16x16x32_bf16 v[68:71], v[176:179], v[200:203], v[68:71]
	v_mfma_f32_16x16x32_bf16 v[88:91], v[168:171], v[208:211], v[88:91]
	v_mfma_f32_16x16x32_bf16 v[84:87], v[176:179], v[208:211], v[84:87]
	v_mfma_f32_16x16x32_bf16 v[116:119], v[172:175], v[188:191], v[116:119]
	v_mfma_f32_16x16x32_bf16 v[112:115], v[180:183], v[188:191], v[112:115]
	v_mfma_f32_16x16x32_bf16 v[104:107], v[172:175], v[196:199], v[104:107]
	v_mfma_f32_16x16x32_bf16 v[44:47], v[180:183], v[196:199], v[44:47]
	v_mfma_f32_16x16x32_bf16 v[96:99], v[172:175], v[204:207], v[96:99]
	v_mfma_f32_16x16x32_bf16 v[68:71], v[180:183], v[204:207], v[68:71]
	v_mfma_f32_16x16x32_bf16 v[88:91], v[172:175], v[212:215], v[88:91]
	v_mfma_f32_16x16x32_bf16 v[84:87], v[180:183], v[212:215], v[84:87]
	s_barrier
	s_add_u32 s98, s86, s18
	s_addc_u32 s99, s87, s19
	s_add_u32 s100, s88, s18
	s_addc_u32 s101, s89, s19
	s_add_i32 s65, s58, s3
	s_mov_b32 m0, s65
	ds_read_b128 v[184:187], v157 offset:16384
	ds_read_b128 v[188:191], v157 offset:17408
	ds_read_b128 v[192:195], v157 offset:18432
	ds_read_b128 v[196:199], v157 offset:19456
	ds_read_b128 v[200:203], v157 offset:20480
	ds_read_b128 v[204:207], v157 offset:21504
	ds_read_b128 v[208:211], v157 offset:22528
	ds_read_b128 v[212:215], v157 offset:23552
	global_load_lds_dwordx4 v130, s[86:87]
	s_add_i32 m0, s65, 0x2000
	s_add_u32 s66, s86, 0x100000
	s_addc_u32 s67, s87, 0
	s_add_i32 s65, s59, s3
	global_load_lds_dwordx4 v134, s[86:87]
	s_mov_b32 m0, s65
	s_nop 0
	global_load_lds_dwordx4 v130, s[66:67]
	s_add_i32 m0, s65, 0x2000
	s_nop 0
	global_load_lds_dwordx4 v134, s[66:67]
	s_mov_b32 m0, s29
	s_nop 0
	global_load_lds_dwordx4 v128, s[88:89]
	s_mov_b32 m0, s33
	s_nop 0
	global_load_lds_dwordx4 v132, s[88:89]
	s_waitcnt vmcnt(8)
	s_waitcnt lgkmcnt(0)
	s_barrier
	v_mfma_f32_16x16x32_bf16 v[80:83], v[144:147], v[184:187], v[80:83]
	v_mfma_f32_16x16x32_bf16 v[76:79], v[160:163], v[184:187], v[76:79]
	v_mfma_f32_16x16x32_bf16 v[56:59], v[144:147], v[192:195], v[56:59]
	v_mfma_f32_16x16x32_bf16 v[48:51], v[160:163], v[192:195], v[48:51]
	v_mfma_f32_16x16x32_bf16 v[28:31], v[144:147], v[200:203], v[28:31]
	v_mfma_f32_16x16x32_bf16 v[24:27], v[160:163], v[200:203], v[24:27]
	v_mfma_f32_16x16x32_bf16 v[12:15], v[144:147], v[208:211], v[12:15]
	v_mfma_f32_16x16x32_bf16 v[8:11], v[160:163], v[208:211], v[8:11]
	v_mfma_f32_16x16x32_bf16 v[80:83], v[148:151], v[188:191], v[80:83]
	v_mfma_f32_16x16x32_bf16 v[76:79], v[164:167], v[188:191], v[76:79]
	v_mfma_f32_16x16x32_bf16 v[56:59], v[148:151], v[196:199], v[56:59]
	v_mfma_f32_16x16x32_bf16 v[48:51], v[164:167], v[196:199], v[48:51]
	v_mfma_f32_16x16x32_bf16 v[28:31], v[148:151], v[204:207], v[28:31]
	v_mfma_f32_16x16x32_bf16 v[24:27], v[164:167], v[204:207], v[24:27]
	v_mfma_f32_16x16x32_bf16 v[12:15], v[148:151], v[212:215], v[12:15]
	v_mfma_f32_16x16x32_bf16 v[8:11], v[164:167], v[212:215], v[8:11]
	v_mfma_f32_16x16x32_bf16 v[64:67], v[168:171], v[184:187], v[64:67]
	v_mfma_f32_16x16x32_bf16 v[60:63], v[176:179], v[184:187], v[60:63]
	v_mfma_f32_16x16x32_bf16 v[40:43], v[168:171], v[192:195], v[40:43]
	v_mfma_f32_16x16x32_bf16 v[36:39], v[176:179], v[192:195], v[36:39]
	v_mfma_f32_16x16x32_bf16 v[20:23], v[168:171], v[200:203], v[20:23]
	v_mfma_f32_16x16x32_bf16 v[16:19], v[176:179], v[200:203], v[16:19]
	v_mfma_f32_16x16x32_bf16 v[4:7], v[168:171], v[208:211], v[4:7]
	v_mfma_f32_16x16x32_bf16 v[0:3], v[176:179], v[208:211], v[0:3]
	v_mfma_f32_16x16x32_bf16 v[64:67], v[172:175], v[188:191], v[64:67]
	v_mfma_f32_16x16x32_bf16 v[60:63], v[180:183], v[188:191], v[60:63]
	v_mfma_f32_16x16x32_bf16 v[40:43], v[172:175], v[196:199], v[40:43]
	v_mfma_f32_16x16x32_bf16 v[36:39], v[180:183], v[196:199], v[36:39]
	v_mfma_f32_16x16x32_bf16 v[20:23], v[172:175], v[204:207], v[20:23]
	v_mfma_f32_16x16x32_bf16 v[16:19], v[180:183], v[204:207], v[16:19]
	v_mfma_f32_16x16x32_bf16 v[4:7], v[172:175], v[212:215], v[4:7]
	v_mfma_f32_16x16x32_bf16 v[0:3], v[180:183], v[212:215], v[0:3]
	s_barrier
; #define PG8_STAGE(bufoff, gbase, voff) do { _Pragma("unroll") for (int _i = 0; _i < 2; ++_i) \
;         __builtin_amdgcn_global_load_lds((const unsigned*)((const char*)(gbase) + (voff)[_i]), (PG8_LAS unsigned*)(lds + (bufoff) + ldsw + _i * 8192), 16, 0, 0); } while (0)
; #define PG8_LDA(dst, b, h) do { _Pragma("unroll") for (int m = 0; m < 4; ++m) _Pragma("unroll") for (int k = 0; k < 2; ++k) dst[m][k] = *(const PG8_LAS bf16x8*)(lds + PG8_SA(b, h) + aoff + m * 2048 + k * 1024); } while (0)
; #define PG8_LDB(dst, b, h) do { _Pragma("unroll") for (int n = 0; n < 2; ++n) _Pragma("unroll") for (int k = 0; k < 2; ++k) dst[n][k] = *(const PG8_LAS bf16x8*)(lds + PG8_SB(b, h) + boff + n * 2048 + k * 1024); } while (0)
; #define PG8_MMA(ai, bj, At, Bt) do { __builtin_amdgcn_s_setprio(1); _Pragma("unroll") for (int m = 0; m < 4; ++m) _Pragma("unroll") for (int n = 0; n < 2; ++n) _Pragma("unroll") for (int k = 0; k < 2; ++k) \
;         acc[ai][bj][m][n] = __builtin_amdgcn_mfma_f32_16x16x32_bf16(Bt[n][k], At[m][k], acc[ai][bj][m][n], 0, 0, 0); __builtin_amdgcn_s_setprio(0); } while (0)
; #define PG8_WAIT_V(n) asm volatile("s_waitcnt vmcnt(" #n ")" ::: "memory")
; #define PG8_WAIT_L(n) asm volatile("s_waitcnt lgkmcnt(" #n ")" ::: "memory")
; #define PG8_BAR __builtin_amdgcn_s_barrier()
; #define PG8_SCHED __builtin_amdgcn_sched_barrier(0)
; template <class Epi, class Sched, bool ALIGN_EPI = false, bool SP2 = false>
; __device__ __forceinline__ void gemm_phase(PG8_LAS unsigned char* lds, const Gemm g, const Sched& S, const Epi& E) {
;     ...
;             PG8_LDB(B0, 1, 0); PG8_LDB(B1, 1, 1); PG8_SCHED; PG8_LDA(At, 1, 0); PG8_STAGE(PG8_SA(0, 1), a2 + hstepA, voffA);
;             PG8_WAIT_V(8); PG8_WAIT_L(0); PG8_BAR; PG8_MMA(0, 0, At, B0); PG8_MMA(0, 1, At, B1); PG8_BAR; PG8_SCHED;
;             PG8_LDA(At, 1, 1); PG8_STAGE(PG8_SB(1, 0), b3, voffB); PG8_STAGE(PG8_SB(1, 1), b3 + hstep, voffB); PG8_STAGE(PG8_SA(1, 0), a3, voffA);
;             PG8_WAIT_V(8); PG8_WAIT_L(0); PG8_BAR; PG8_MMA(1, 0, At, B0); PG8_MMA(1, 1, At, B1); PG8_BAR; PG8_SCHED;
;     ...
;         if constexpr (ALIGN_EPI) { if (wr == 0) PG8_BAR; }
	s_add_i32 s65, 0, 0x18000
	s_add_i32 s68, 0, 0x1c000
	v_add_u32_e32 v164, s65, v153
	v_add_u32_e32 v180, s68, v153
	ds_read_b128 v[144:147], v164
	ds_read_b128 v[148:151], v164 offset:1024
	ds_read_b128 v[160:163], v164 offset:2048
	ds_read_b128 v[164:167], v164 offset:3072
	ds_read_b128 v[168:171], v180
	ds_read_b128 v[172:175], v180 offset:1024
	ds_read_b128 v[176:179], v180 offset:2048
	ds_read_b128 v[180:183], v180 offset:3072
	s_add_u32 s66, s88, 0x100000
	s_addc_u32 s67, s89, 0
	s_mov_b32 m0, s41
	ds_read_b128 v[184:187], v157 offset:32768
	ds_read_b128 v[188:191], v157 offset:33792
	ds_read_b128 v[192:195], v157 offset:34816
	ds_read_b128 v[196:199], v157 offset:35840
	ds_read_b128 v[200:203], v157 offset:36864
	ds_read_b128 v[204:207], v157 offset:37888
	ds_read_b128 v[208:211], v157 offset:38912
	ds_read_b128 v[212:215], v157 offset:39936
	global_load_lds_dwordx4 v128, s[66:67]
	s_mov_b32 m0, s52
	s_nop 0
	global_load_lds_dwordx4 v132, s[66:67]
	s_waitcnt vmcnt(8)
	s_waitcnt lgkmcnt(0)
	s_barrier
	v_mfma_f32_16x16x32_bf16 v[124:127], v[144:147], v[184:187], v[124:127]
	v_mfma_f32_16x16x32_bf16 v[120:123], v[160:163], v[184:187], v[120:123]
	v_mfma_f32_16x16x32_bf16 v[108:111], v[144:147], v[192:195], v[108:111]
	v_mfma_f32_16x16x32_bf16 v[32:35], v[160:163], v[192:195], v[32:35]
	v_mfma_f32_16x16x32_bf16 v[100:103], v[144:147], v[200:203], v[100:103]
	v_mfma_f32_16x16x32_bf16 v[52:55], v[160:163], v[200:203], v[52:55]
	v_mfma_f32_16x16x32_bf16 v[92:95], v[144:147], v[208:211], v[92:95]
	v_mfma_f32_16x16x32_bf16 v[72:75], v[160:163], v[208:211], v[72:75]
	v_mfma_f32_16x16x32_bf16 v[124:127], v[148:151], v[188:191], v[124:127]
	v_mfma_f32_16x16x32_bf16 v[120:123], v[164:167], v[188:191], v[120:123]
	v_mfma_f32_16x16x32_bf16 v[108:111], v[148:151], v[196:199], v[108:111]
	v_mfma_f32_16x16x32_bf16 v[32:35], v[164:167], v[196:199], v[32:35]
	v_mfma_f32_16x16x32_bf16 v[100:103], v[148:151], v[204:207], v[100:103]
	v_mfma_f32_16x16x32_bf16 v[52:55], v[164:167], v[204:207], v[52:55]
	v_mfma_f32_16x16x32_bf16 v[92:95], v[148:151], v[212:215], v[92:95]
	v_mfma_f32_16x16x32_bf16 v[72:75], v[164:167], v[212:215], v[72:75]
	v_mfma_f32_16x16x32_bf16 v[116:119], v[168:171], v[184:187], v[116:119]
	v_mfma_f32_16x16x32_bf16 v[112:115], v[176:179], v[184:187], v[112:115]
	v_mfma_f32_16x16x32_bf16 v[104:107], v[168:171], v[192:195], v[104:107]
	v_mfma_f32_16x16x32_bf16 v[44:47], v[176:179], v[192:195], v[44:47]
	v_mfma_f32_16x16x32_bf16 v[96:99], v[168:171], v[200:203], v[96:99]
	v_mfma_f32_16x16x32_bf16 v[68:71], v[176:179], v[200:203], v[68:71]
	v_mfma_f32_16x16x32_bf16 v[88:91], v[168:171], v[208:211], v[88:91]
	v_mfma_f32_16x16x32_bf16 v[84:87], v[176:179], v[208:211], v[84:87]
	v_mfma_f32_16x16x32_bf16 v[116:119], v[172:175], v[188:191], v[116:119]
	v_mfma_f32_16x16x32_bf16 v[112:115], v[180:183], v[188:191], v[112:115]
	v_mfma_f32_16x16x32_bf16 v[104:107], v[172:175], v[196:199], v[104:107]
	v_mfma_f32_16x16x32_bf16 v[44:47], v[180:183], v[196:199], v[44:47]
	v_mfma_f32_16x16x32_bf16 v[96:99], v[172:175], v[204:207], v[96:99]
	v_mfma_f32_16x16x32_bf16 v[68:71], v[180:183], v[204:207], v[68:71]
	v_mfma_f32_16x16x32_bf16 v[88:91], v[172:175], v[212:215], v[88:91]
	v_mfma_f32_16x16x32_bf16 v[84:87], v[180:183], v[212:215], v[84:87]
	s_barrier
	s_add_i32 s65, s65, s3
	s_mov_b32 m0, s65
	ds_read_b128 v[184:187], v157 offset:49152
	ds_read_b128 v[188:191], v157 offset:50176
	ds_read_b128 v[192:195], v157 offset:51200
	ds_read_b128 v[196:199], v157 offset:52224
	ds_read_b128 v[200:203], v157 offset:53248
	ds_read_b128 v[204:207], v157 offset:54272
	ds_read_b128 v[208:211], v157 offset:55296
	ds_read_b128 v[212:215], v157 offset:56320
	global_load_lds_dwordx4 v130, s[98:99]
	s_add_i32 m0, s65, 0x2000
	s_add_u32 s66, s86, 0x100080
	s_addc_u32 s67, s87, 0
	s_add_i32 s65, s68, s3
	global_load_lds_dwordx4 v134, s[98:99]
	s_mov_b32 m0, s65
	s_nop 0
	global_load_lds_dwordx4 v130, s[66:67]
	s_add_i32 m0, s65, 0x2000
	s_nop 0
	global_load_lds_dwordx4 v134, s[66:67]
	s_mov_b32 m0, s54
	s_nop 0
	global_load_lds_dwordx4 v128, s[100:101]
	s_mov_b32 m0, s55
	s_nop 0
	global_load_lds_dwordx4 v132, s[100:101]
	s_waitcnt vmcnt(8)
	s_waitcnt lgkmcnt(0)
	s_barrier
	v_mfma_f32_16x16x32_bf16 v[80:83], v[144:147], v[184:187], v[80:83]
	v_mfma_f32_16x16x32_bf16 v[76:79], v[160:163], v[184:187], v[76:79]
	v_mfma_f32_16x16x32_bf16 v[56:59], v[144:147], v[192:195], v[56:59]
	v_mfma_f32_16x16x32_bf16 v[48:51], v[160:163], v[192:195], v[48:51]
	v_mfma_f32_16x16x32_bf16 v[28:31], v[144:147], v[200:203], v[28:31]
	v_mfma_f32_16x16x32_bf16 v[24:27], v[160:163], v[200:203], v[24:27]
	v_mfma_f32_16x16x32_bf16 v[12:15], v[144:147], v[208:211], v[12:15]
	v_mfma_f32_16x16x32_bf16 v[8:11], v[160:163], v[208:211], v[8:11]
	v_mfma_f32_16x16x32_bf16 v[80:83], v[148:151], v[188:191], v[80:83]
	v_mfma_f32_16x16x32_bf16 v[76:79], v[164:167], v[188:191], v[76:79]
	v_mfma_f32_16x16x32_bf16 v[56:59], v[148:151], v[196:199], v[56:59]
	v_mfma_f32_16x16x32_bf16 v[48:51], v[164:167], v[196:199], v[48:51]
	v_mfma_f32_16x16x32_bf16 v[28:31], v[148:151], v[204:207], v[28:31]
	v_mfma_f32_16x16x32_bf16 v[24:27], v[164:167], v[204:207], v[24:27]
	v_mfma_f32_16x16x32_bf16 v[12:15], v[148:151], v[212:215], v[12:15]
	v_mfma_f32_16x16x32_bf16 v[8:11], v[164:167], v[212:215], v[8:11]
	v_mfma_f32_16x16x32_bf16 v[64:67], v[168:171], v[184:187], v[64:67]
	v_mfma_f32_16x16x32_bf16 v[60:63], v[176:179], v[184:187], v[60:63]
	v_mfma_f32_16x16x32_bf16 v[40:43], v[168:171], v[192:195], v[40:43]
	v_mfma_f32_16x16x32_bf16 v[36:39], v[176:179], v[192:195], v[36:39]
	v_mfma_f32_16x16x32_bf16 v[20:23], v[168:171], v[200:203], v[20:23]
	v_mfma_f32_16x16x32_bf16 v[16:19], v[176:179], v[200:203], v[16:19]
	v_mfma_f32_16x16x32_bf16 v[4:7], v[168:171], v[208:211], v[4:7]
	v_mfma_f32_16x16x32_bf16 v[0:3], v[176:179], v[208:211], v[0:3]
	v_mfma_f32_16x16x32_bf16 v[64:67], v[172:175], v[188:191], v[64:67]
	v_mfma_f32_16x16x32_bf16 v[60:63], v[180:183], v[188:191], v[60:63]
	v_mfma_f32_16x16x32_bf16 v[40:43], v[172:175], v[196:199], v[40:43]
	v_mfma_f32_16x16x32_bf16 v[36:39], v[180:183], v[196:199], v[36:39]
	v_mfma_f32_16x16x32_bf16 v[20:23], v[172:175], v[204:207], v[20:23]
	v_mfma_f32_16x16x32_bf16 v[16:19], v[180:183], v[204:207], v[16:19]
	v_mfma_f32_16x16x32_bf16 v[4:7], v[172:175], v[212:215], v[4:7]
	v_mfma_f32_16x16x32_bf16 v[0:3], v[180:183], v[212:215], v[0:3]
	s_barrier
	s_add_i32 s64, s64, 2
	s_add_u32 s84, s84, 0x100
	s_addc_u32 s85, s85, 0
	s_add_u32 s62, s62, 0x100
	s_addc_u32 s63, s63, 0
	s_cmp_gt_u32 s64, 61
	s_cbranch_scc0 .LBB0_1631
	s_setprio 0
	s_and_b64 vcc, exec, s[20:21]
	s_cbranch_vccz .LBB0_1634
	s_barrier

; #define PG8_STAGE(bufoff, gbase, voff) do { _Pragma("unroll") for (int _i = 0; _i < 2; ++_i) \
;         __builtin_amdgcn_global_load_lds((const unsigned*)((const char*)(gbase) + (voff)[_i]), (PG8_LAS unsigned*)(lds + (bufoff) + ldsw + _i * 8192), 16, 0, 0); } while (0)
; #define PG8_LDA(dst, b, h) do { _Pragma("unroll") for (int m = 0; m < 4; ++m) _Pragma("unroll") for (int k = 0; k < 2; ++k) dst[m][k] = *(const PG8_LAS bf16x8*)(lds + PG8_SA(b, h) + aoff + m * 2048 + k * 1024); } while (0)
; #define PG8_LDB(dst, b, h) do { _Pragma("unroll") for (int n = 0; n < 2; ++n) _Pragma("unroll") for (int k = 0; k < 2; ++k) dst[n][k] = *(const PG8_LAS bf16x8*)(lds + PG8_SB(b, h) + boff + n * 2048 + k * 1024); } while (0)
; #define PG8_WAIT_V(n) asm volatile("s_waitcnt vmcnt(" #n ")" ::: "memory")
; #define PG8_WAIT_L(n) asm volatile("s_waitcnt lgkmcnt(" #n ")" ::: "memory")
; #define PG8_BAR __builtin_amdgcn_s_barrier()
; #define PG8_SCHED __builtin_amdgcn_sched_barrier(0)
; template <class Epi, class Sched, bool ALIGN_EPI = false, bool SP2 = false>
; __device__ __forceinline__ void gemm_phase(PG8_LAS unsigned char* lds, const Gemm g, const Sched& S, const Epi& E) {
;     ...
;     for (;;) {
;         const bool has_next = S.next(ui + 1, nxt);
;         const char* nA = has_next ? (const char*)g.A + (size_t)nxt.pm * tstep : cA; const char* nB = has_next ? (const char*)g.Bt + (size_t)nxt.pn * tstep : cB;
;         for (int t = 0; t < nt; t += 2) {
;             const bool last = (t == nt - 2);
;             const char* a1 = cA + (size_t)(t + 1) * kstepA;
;             const char* a2 = last ? nA : cA + (size_t)(t + 2) * kstepA; const char* b2 = last ? nB : cB + (size_t)(t + 2) * kstep;
;             const char* a3 = a2 + kstepA; const char* b3 = b2 + kstep;
;             if (last && has_next) S.a_ready(nxt);
;             if constexpr (SP2) {
;             PG8_LDB(B0, 0, 0); PG8_LDB(B1, 0, 1); PG8_SCHED; PG8_LDA(At, 0, 0); PG8_STAGE(PG8_SA(1, 1), a1 + hstepA, voffA);
;             PG8_WAIT_V(8); PG8_WAIT_L(0); PG8_BAR; PG8_MMA(0, 0, At, B0); PG8_MMA(0, 1, At, B1); PG8_BAR; PG8_SCHED;
;     ...
;         for (int a = 0; a < 2; ++a)
; #pragma unroll
;             for (int b = 0; b < 2; ++b)
; #pragma unroll
;                 for (int m = 0; m < 4; ++m)
; #pragma unroll
;                     for (int n = 0; n < 2; ++n) acc[a][b][m][n] = (f32x4){0.f, 0.f, 0.f, 0.f};
.LBB0_1740:
	s_ashr_i32 s21, s20, 31
	s_lshl_b64 s[22:23], s[20:21], 21
	s_add_u32 s22, s96, s22
	s_addc_u32 s23, s97, s23
	s_and_b64 s[24:25], s[0:1], exec
	s_cselect_b32 s21, s23, s35
	s_cselect_b32 s27, s22, s34
	s_ashr_i32 s19, s18, 31
	s_lshl_b64 s[24:25], s[18:19], 21
	s_add_u32 s24, s3, s24
	s_addc_u32 s25, s29, s25
	s_and_b64 s[66:67], s[0:1], exec
	s_cselect_b32 s19, s25, s41
	s_cselect_b32 s31, s24, s40
	s_add_u32 s34, s34, 0x100080
	s_addc_u32 s35, s35, 0
	s_add_u32 s65, s40, 0x100
	v_mov_b32_e32 v0, 0
	s_addc_u32 s66, s41, 0
	s_mov_b32 s67, -2
	v_mov_b32_e32 v1, v0
	v_mov_b32_e32 v2, v0
	v_mov_b32_e32 v3, v0
	v_mov_b32_e32 v4, v0
	v_mov_b32_e32 v5, v0
	v_mov_b32_e32 v6, v0
	v_mov_b32_e32 v7, v0
	v_mov_b32_e32 v16, v0
	v_mov_b32_e32 v17, v0
	v_mov_b32_e32 v18, v0
	v_mov_b32_e32 v19, v0
	v_mov_b32_e32 v20, v0
	v_mov_b32_e32 v21, v0
	v_mov_b32_e32 v22, v0
	v_mov_b32_e32 v23, v0
	v_mov_b32_e32 v32, v0
	v_mov_b32_e32 v33, v0
	v_mov_b32_e32 v34, v0
	v_mov_b32_e32 v35, v0
	s_waitcnt vmcnt(0)
	v_mov_b32_e32 v36, v0
	v_mov_b32_e32 v37, v0
	v_mov_b32_e32 v38, v0
	v_mov_b32_e32 v39, v0
	v_mov_b32_e32 v48, v0
	v_mov_b32_e32 v49, v0
	v_mov_b32_e32 v50, v0
	v_mov_b32_e32 v51, v0
	v_mov_b32_e32 v52, v0
	v_mov_b32_e32 v53, v0
	v_mov_b32_e32 v54, v0
	v_mov_b32_e32 v55, v0
	v_mov_b32_e32 v8, v0
	v_mov_b32_e32 v9, v0
	v_mov_b32_e32 v10, v0
	v_mov_b32_e32 v11, v0
	v_mov_b32_e32 v12, v0
	v_mov_b32_e32 v13, v0
	v_mov_b32_e32 v14, v0
	v_mov_b32_e32 v15, v0
	v_mov_b32_e32 v24, v0
	v_mov_b32_e32 v25, v0
	v_mov_b32_e32 v26, v0
	v_mov_b32_e32 v27, v0
	v_mov_b32_e32 v28, v0
	v_mov_b32_e32 v29, v0
	v_mov_b32_e32 v30, v0
	v_mov_b32_e32 v31, v0
	v_mov_b32_e32 v40, v0
	v_mov_b32_e32 v41, v0
	v_mov_b32_e32 v42, v0
	v_mov_b32_e32 v43, v0
	v_mov_b32_e32 v44, v0
	v_mov_b32_e32 v45, v0
	v_mov_b32_e32 v46, v0
	v_mov_b32_e32 v47, v0
	v_mov_b32_e32 v56, v0
	v_mov_b32_e32 v57, v0
	v_mov_b32_e32 v58, v0
	v_mov_b32_e32 v59, v0
	v_mov_b32_e32 v60, v0
	v_mov_b32_e32 v61, v0
	v_mov_b32_e32 v62, v0
	v_mov_b32_e32 v63, v0
	v_mov_b32_e32 v64, v0
	v_mov_b32_e32 v65, v0
	v_mov_b32_e32 v66, v0
	v_mov_b32_e32 v67, v0
	v_mov_b32_e32 v68, v0
	v_mov_b32_e32 v69, v0
	v_mov_b32_e32 v70, v0
	v_mov_b32_e32 v71, v0
	v_mov_b32_e32 v80, v0
	v_mov_b32_e32 v81, v0
	v_mov_b32_e32 v82, v0
	v_mov_b32_e32 v83, v0
	v_mov_b32_e32 v84, v0
	v_mov_b32_e32 v85, v0
	v_mov_b32_e32 v86, v0
	v_mov_b32_e32 v87, v0
	v_mov_b32_e32 v96, v0
	v_mov_b32_e32 v97, v0
	v_mov_b32_e32 v98, v0
	v_mov_b32_e32 v99, v0
	v_mov_b32_e32 v100, v0
	v_mov_b32_e32 v101, v0
	v_mov_b32_e32 v102, v0
	v_mov_b32_e32 v103, v0
	v_mov_b32_e32 v112, v0
	v_mov_b32_e32 v113, v0
	v_mov_b32_e32 v114, v0
	v_mov_b32_e32 v115, v0
	v_mov_b32_e32 v116, v0
	v_mov_b32_e32 v117, v0
	v_mov_b32_e32 v118, v0
	v_mov_b32_e32 v119, v0
	v_mov_b32_e32 v72, v0
	v_mov_b32_e32 v73, v0
	v_mov_b32_e32 v74, v0
	v_mov_b32_e32 v75, v0
	v_mov_b32_e32 v76, v0
	v_mov_b32_e32 v77, v0
	v_mov_b32_e32 v78, v0
	v_mov_b32_e32 v79, v0
	v_mov_b32_e32 v88, v0
	v_mov_b32_e32 v89, v0
	v_mov_b32_e32 v90, v0
	v_mov_b32_e32 v91, v0
	v_mov_b32_e32 v92, v0
	v_mov_b32_e32 v93, v0
	v_mov_b32_e32 v94, v0
	v_mov_b32_e32 v95, v0
	v_mov_b32_e32 v104, v0
	v_mov_b32_e32 v105, v0
	v_mov_b32_e32 v106, v0
	v_mov_b32_e32 v107, v0
	v_mov_b32_e32 v108, v0
	v_mov_b32_e32 v109, v0
	v_mov_b32_e32 v110, v0
	v_mov_b32_e32 v111, v0
	v_mov_b32_e32 v120, v0
	v_mov_b32_e32 v121, v0
	v_mov_b32_e32 v122, v0
	v_mov_b32_e32 v123, v0
	v_mov_b32_e32 v124, v0
	v_mov_b32_e32 v125, v0
	v_mov_b32_e32 v126, v0
	v_mov_b32_e32 v127, v0
	s_cmp_ge_u32 s33, 0x1000
	s_cbranch_scc1 .Lsprio_5
	s_setprio 1
.Lsprio_5:
.LBB0_1741:
	ds_read_b128 v[150:153], v158
	ds_read_b128 v[162:165], v158 offset:1024
	ds_read_b128 v[166:169], v158 offset:2048
	ds_read_b128 v[170:173], v158 offset:3072
	ds_read_b128 v[174:177], v159
	ds_read_b128 v[178:181], v159 offset:1024
	ds_read_b128 v[182:185], v159 offset:2048
	ds_read_b128 v[186:189], v159 offset:3072
	s_add_u32 s40, s34, 0xfff00080
	s_addc_u32 s41, s35, -1
	s_cmp_eq_u32 s67, 60
	s_cselect_b32 s85, s21, s41
	s_cselect_b32 s84, s27, s40
	s_cselect_b32 s41, s19, s66
	s_cselect_b32 s40, s31, s65
	s_add_i32 m0, s53, 0xc000
	ds_read_b128 v[190:193], v160
	ds_read_b128 v[194:197], v160 offset:1024
	ds_read_b128 v[198:201], v160 offset:2048
	ds_read_b128 v[202:205], v160 offset:3072
	ds_read_b128 v[206:209], v160 offset:4096
	ds_read_b128 v[210:213], v160 offset:5120
	ds_read_b128 v[214:217], v160 offset:6144
	ds_read_b128 v[218:221], v160 offset:7168
	global_load_lds_dwordx4 v140, s[34:35]
	s_add_i32 m0, s53, 0xe000
	s_nop 0
	global_load_lds_dwordx4 v142, s[34:35]
	s_waitcnt vmcnt(8)
	s_waitcnt lgkmcnt(0)
	s_barrier
; #define PG8_STAGE(bufoff, gbase, voff) do { _Pragma("unroll") for (int _i = 0; _i < 2; ++_i) \
;         __builtin_amdgcn_global_load_lds((const unsigned*)((const char*)(gbase) + (voff)[_i]), (PG8_LAS unsigned*)(lds + (bufoff) + ldsw + _i * 8192), 16, 0, 0); } while (0)
; #define PG8_LDA(dst, b, h) do { _Pragma("unroll") for (int m = 0; m < 4; ++m) _Pragma("unroll") for (int k = 0; k < 2; ++k) dst[m][k] = *(const PG8_LAS bf16x8*)(lds + PG8_SA(b, h) + aoff + m * 2048 + k * 1024); } while (0)
; #define PG8_MMA(ai, bj, At, Bt) do { __builtin_amdgcn_s_setprio(1); _Pragma("unroll") for (int m = 0; m < 4; ++m) _Pragma("unroll") for (int n = 0; n < 2; ++n) _Pragma("unroll") for (int k = 0; k < 2; ++k) \
;         acc[ai][bj][m][n] = __builtin_amdgcn_mfma_f32_16x16x32_bf16(Bt[n][k], At[m][k], acc[ai][bj][m][n], 0, 0, 0); __builtin_amdgcn_s_setprio(0); } while (0)
; #define PG8_WAIT_V(n) asm volatile("s_waitcnt vmcnt(" #n ")" ::: "memory")
; #define PG8_WAIT_L(n) asm volatile("s_waitcnt lgkmcnt(" #n ")" ::: "memory")
; #define PG8_BAR __builtin_amdgcn_s_barrier()
; #define PG8_SCHED __builtin_amdgcn_sched_barrier(0)
; template <class Epi, class Sched, bool ALIGN_EPI = false, bool SP2 = false>
; __device__ __forceinline__ void gemm_phase(PG8_LAS unsigned char* lds, const Gemm g, const Sched& S, const Epi& E) {
;     ...
;             PG8_WAIT_V(8); PG8_WAIT_L(0); PG8_BAR; PG8_MMA(0, 0, At, B0); PG8_MMA(0, 1, At, B1); PG8_BAR; PG8_SCHED;
;             PG8_LDA(At, 0, 1); PG8_STAGE(PG8_SB(0, 0), b2, voffB); PG8_STAGE(PG8_SB(0, 1), b2 + hstep, voffB); PG8_STAGE(PG8_SA(0, 0), a2, voffA);
;             PG8_WAIT_V(8); PG8_WAIT_L(0); PG8_BAR; PG8_MMA(1, 0, At, B0); PG8_MMA(1, 1, At, B1); PG8_BAR; PG8_SCHED;
	v_mfma_f32_16x16x32_bf16 v[124:127], v[150:153], v[190:193], v[124:127]
	v_mfma_f32_16x16x32_bf16 v[120:123], v[166:169], v[190:193], v[120:123]
	v_mfma_f32_16x16x32_bf16 v[108:111], v[150:153], v[198:201], v[108:111]
	v_mfma_f32_16x16x32_bf16 v[104:107], v[166:169], v[198:201], v[104:107]
	v_mfma_f32_16x16x32_bf16 v[92:95], v[150:153], v[206:209], v[92:95]
	v_mfma_f32_16x16x32_bf16 v[88:91], v[166:169], v[206:209], v[88:91]
	v_mfma_f32_16x16x32_bf16 v[76:79], v[150:153], v[214:217], v[76:79]
	v_mfma_f32_16x16x32_bf16 v[72:75], v[166:169], v[214:217], v[72:75]
	v_mfma_f32_16x16x32_bf16 v[124:127], v[162:165], v[194:197], v[124:127]
	v_mfma_f32_16x16x32_bf16 v[120:123], v[170:173], v[194:197], v[120:123]
	v_mfma_f32_16x16x32_bf16 v[108:111], v[162:165], v[202:205], v[108:111]
	v_mfma_f32_16x16x32_bf16 v[104:107], v[170:173], v[202:205], v[104:107]
	v_mfma_f32_16x16x32_bf16 v[92:95], v[162:165], v[210:213], v[92:95]
	v_mfma_f32_16x16x32_bf16 v[88:91], v[170:173], v[210:213], v[88:91]
	v_mfma_f32_16x16x32_bf16 v[76:79], v[162:165], v[218:221], v[76:79]
	v_mfma_f32_16x16x32_bf16 v[72:75], v[170:173], v[218:221], v[72:75]
	v_mfma_f32_16x16x32_bf16 v[116:119], v[174:177], v[190:193], v[116:119]
	v_mfma_f32_16x16x32_bf16 v[112:115], v[182:185], v[190:193], v[112:115]
	v_mfma_f32_16x16x32_bf16 v[100:103], v[174:177], v[198:201], v[100:103]
	v_mfma_f32_16x16x32_bf16 v[96:99], v[182:185], v[198:201], v[96:99]
	v_mfma_f32_16x16x32_bf16 v[84:87], v[174:177], v[206:209], v[84:87]
	v_mfma_f32_16x16x32_bf16 v[80:83], v[182:185], v[206:209], v[80:83]
	v_mfma_f32_16x16x32_bf16 v[68:71], v[174:177], v[214:217], v[68:71]
	v_mfma_f32_16x16x32_bf16 v[64:67], v[182:185], v[214:217], v[64:67]
	v_mfma_f32_16x16x32_bf16 v[116:119], v[178:181], v[194:197], v[116:119]
	v_mfma_f32_16x16x32_bf16 v[112:115], v[186:189], v[194:197], v[112:115]
	v_mfma_f32_16x16x32_bf16 v[100:103], v[178:181], v[202:205], v[100:103]
	v_mfma_f32_16x16x32_bf16 v[96:99], v[186:189], v[202:205], v[96:99]
	v_mfma_f32_16x16x32_bf16 v[84:87], v[178:181], v[210:213], v[84:87]
	v_mfma_f32_16x16x32_bf16 v[80:83], v[186:189], v[210:213], v[80:83]
	v_mfma_f32_16x16x32_bf16 v[68:71], v[178:181], v[218:221], v[68:71]
	v_mfma_f32_16x16x32_bf16 v[64:67], v[186:189], v[218:221], v[64:67]
	s_barrier
	s_add_u32 s98, s40, s12
	s_addc_u32 s99, s41, s13
	s_add_u32 s100, s84, s12
	s_addc_u32 s101, s85, s13
	s_add_i32 s68, s62, s33
	s_mov_b32 m0, s68
	ds_read_b128 v[190:193], v160 offset:16384
	ds_read_b128 v[194:197], v160 offset:17408
	ds_read_b128 v[198:201], v160 offset:18432
	ds_read_b128 v[202:205], v160 offset:19456
	ds_read_b128 v[206:209], v160 offset:20480
	ds_read_b128 v[210:213], v160 offset:21504
	ds_read_b128 v[214:217], v160 offset:22528
	ds_read_b128 v[218:221], v160 offset:23552
	global_load_lds_dwordx4 v132, s[40:41]
	s_add_i32 m0, s68, 0x2000
	s_add_u32 s68, s40, 0x100000
	s_addc_u32 s69, s41, 0
	s_add_i32 s70, s63, s33
	global_load_lds_dwordx4 v128, s[40:41]
	s_mov_b32 m0, s70
	s_nop 0
	global_load_lds_dwordx4 v132, s[68:69]
	s_add_i32 m0, s70, 0x2000
	s_nop 0
	global_load_lds_dwordx4 v128, s[68:69]
	s_mov_b32 m0, s53
	s_nop 0
	global_load_lds_dwordx4 v134, s[84:85]
	s_mov_b32 m0, s54
	s_nop 0
	global_load_lds_dwordx4 v130, s[84:85]
	s_waitcnt vmcnt(8)
	s_waitcnt lgkmcnt(0)
	s_barrier
	v_mfma_f32_16x16x32_bf16 v[60:63], v[150:153], v[190:193], v[60:63]
	v_mfma_f32_16x16x32_bf16 v[56:59], v[166:169], v[190:193], v[56:59]
	v_mfma_f32_16x16x32_bf16 v[44:47], v[150:153], v[198:201], v[44:47]
	v_mfma_f32_16x16x32_bf16 v[40:43], v[166:169], v[198:201], v[40:43]
	v_mfma_f32_16x16x32_bf16 v[28:31], v[150:153], v[206:209], v[28:31]
	v_mfma_f32_16x16x32_bf16 v[24:27], v[166:169], v[206:209], v[24:27]
	v_mfma_f32_16x16x32_bf16 v[12:15], v[150:153], v[214:217], v[12:15]
	v_mfma_f32_16x16x32_bf16 v[8:11], v[166:169], v[214:217], v[8:11]
	v_mfma_f32_16x16x32_bf16 v[60:63], v[162:165], v[194:197], v[60:63]
	v_mfma_f32_16x16x32_bf16 v[56:59], v[170:173], v[194:197], v[56:59]
	v_mfma_f32_16x16x32_bf16 v[44:47], v[162:165], v[202:205], v[44:47]
	v_mfma_f32_16x16x32_bf16 v[40:43], v[170:173], v[202:205], v[40:43]
	v_mfma_f32_16x16x32_bf16 v[28:31], v[162:165], v[210:213], v[28:31]
	v_mfma_f32_16x16x32_bf16 v[24:27], v[170:173], v[210:213], v[24:27]
	v_mfma_f32_16x16x32_bf16 v[12:15], v[162:165], v[218:221], v[12:15]
	v_mfma_f32_16x16x32_bf16 v[8:11], v[170:173], v[218:221], v[8:11]
	v_mfma_f32_16x16x32_bf16 v[52:55], v[174:177], v[190:193], v[52:55]
	v_mfma_f32_16x16x32_bf16 v[48:51], v[182:185], v[190:193], v[48:51]
	v_mfma_f32_16x16x32_bf16 v[36:39], v[174:177], v[198:201], v[36:39]
	v_mfma_f32_16x16x32_bf16 v[32:35], v[182:185], v[198:201], v[32:35]
	v_mfma_f32_16x16x32_bf16 v[20:23], v[174:177], v[206:209], v[20:23]
	v_mfma_f32_16x16x32_bf16 v[16:19], v[182:185], v[206:209], v[16:19]
	v_mfma_f32_16x16x32_bf16 v[4:7], v[174:177], v[214:217], v[4:7]
	v_mfma_f32_16x16x32_bf16 v[0:3], v[182:185], v[214:217], v[0:3]
	v_mfma_f32_16x16x32_bf16 v[52:55], v[178:181], v[194:197], v[52:55]
	v_mfma_f32_16x16x32_bf16 v[48:51], v[186:189], v[194:197], v[48:51]
	v_mfma_f32_16x16x32_bf16 v[36:39], v[178:181], v[202:205], v[36:39]
	v_mfma_f32_16x16x32_bf16 v[32:35], v[186:189], v[202:205], v[32:35]
	v_mfma_f32_16x16x32_bf16 v[20:23], v[178:181], v[210:213], v[20:23]
	v_mfma_f32_16x16x32_bf16 v[16:19], v[186:189], v[210:213], v[16:19]
	v_mfma_f32_16x16x32_bf16 v[4:7], v[178:181], v[218:221], v[4:7]
	v_mfma_f32_16x16x32_bf16 v[0:3], v[186:189], v[218:221], v[0:3]
	s_barrier
; #define PG8_STAGE(bufoff, gbase, voff) do { _Pragma("unroll") for (int _i = 0; _i < 2; ++_i) \
;         __builtin_amdgcn_global_load_lds((const unsigned*)((const char*)(gbase) + (voff)[_i]), (PG8_LAS unsigned*)(lds + (bufoff) + ldsw + _i * 8192), 16, 0, 0); } while (0)
; #define PG8_LDA(dst, b, h) do { _Pragma("unroll") for (int m = 0; m < 4; ++m) _Pragma("unroll") for (int k = 0; k < 2; ++k) dst[m][k] = *(const PG8_LAS bf16x8*)(lds + PG8_SA(b, h) + aoff + m * 2048 + k * 1024); } while (0)
; #define PG8_LDB(dst, b, h) do { _Pragma("unroll") for (int n = 0; n < 2; ++n) _Pragma("unroll") for (int k = 0; k < 2; ++k) dst[n][k] = *(const PG8_LAS bf16x8*)(lds + PG8_SB(b, h) + boff + n * 2048 + k * 1024); } while (0)
; #define PG8_MMA(ai, bj, At, Bt) do { __builtin_amdgcn_s_setprio(1); _Pragma("unroll") for (int m = 0; m < 4; ++m) _Pragma("unroll") for (int n = 0; n < 2; ++n) _Pragma("unroll") for (int k = 0; k < 2; ++k) \
;         acc[ai][bj][m][n] = __builtin_amdgcn_mfma_f32_16x16x32_bf16(Bt[n][k], At[m][k], acc[ai][bj][m][n], 0, 0, 0); __builtin_amdgcn_s_setprio(0); } while (0)
; #define PG8_WAIT_V(n) asm volatile("s_waitcnt vmcnt(" #n ")" ::: "memory")
; #define PG8_WAIT_L(n) asm volatile("s_waitcnt lgkmcnt(" #n ")" ::: "memory")
; #define PG8_BAR __builtin_amdgcn_s_barrier()
; #define PG8_SCHED __builtin_amdgcn_sched_barrier(0)
; template <class Epi, class Sched, bool ALIGN_EPI = false, bool SP2 = false>
; __device__ __forceinline__ void gemm_phase(PG8_LAS unsigned char* lds, const Gemm g, const Sched& S, const Epi& E) {
;     ...
;         for (int t = 0; t < nt; t += 2) {
;     ...
;             PG8_LDB(B0, 1, 0); PG8_LDB(B1, 1, 1); PG8_SCHED; PG8_LDA(At, 1, 0); PG8_STAGE(PG8_SA(0, 1), a2 + hstepA, voffA);
;             PG8_WAIT_V(8); PG8_WAIT_L(0); PG8_BAR; PG8_MMA(0, 0, At, B0); PG8_MMA(0, 1, At, B1); PG8_BAR; PG8_SCHED;
;             PG8_LDA(At, 1, 1); PG8_STAGE(PG8_SB(1, 0), b3, voffB); PG8_STAGE(PG8_SB(1, 1), b3 + hstep, voffB); PG8_STAGE(PG8_SA(1, 0), a3, voffA);
;             PG8_WAIT_V(8); PG8_WAIT_L(0); PG8_BAR; PG8_MMA(1, 0, At, B0); PG8_MMA(1, 1, At, B1); PG8_BAR; PG8_SCHED;
	s_add_i32 s70, 0, 0x18000
	v_add_u32_e32 v136, s70, v157
	s_add_i32 s71, 0, 0x1c000
	ds_read_b128 v[150:153], v136
	ds_read_b128 v[162:165], v136 offset:1024
	ds_read_b128 v[166:169], v136 offset:2048
	ds_read_b128 v[170:173], v136 offset:3072
	v_add_u32_e32 v136, s71, v157
	ds_read_b128 v[174:177], v136
	ds_read_b128 v[178:181], v136 offset:1024
	ds_read_b128 v[182:185], v136 offset:2048
	ds_read_b128 v[186:189], v136 offset:3072
	s_add_u32 s68, s84, 0x100000
	s_addc_u32 s69, s85, 0
	s_mov_b32 m0, s55
	ds_read_b128 v[190:193], v160 offset:32768
	ds_read_b128 v[194:197], v160 offset:33792
	ds_read_b128 v[198:201], v160 offset:34816
	ds_read_b128 v[202:205], v160 offset:35840
	ds_read_b128 v[206:209], v160 offset:36864
	ds_read_b128 v[210:213], v160 offset:37888
	ds_read_b128 v[214:217], v160 offset:38912
	ds_read_b128 v[218:221], v160 offset:39936
	global_load_lds_dwordx4 v134, s[68:69]
	s_mov_b32 m0, s56
	s_nop 0
	global_load_lds_dwordx4 v130, s[68:69]
	s_waitcnt vmcnt(8)
	s_waitcnt lgkmcnt(0)
	s_barrier
	v_mfma_f32_16x16x32_bf16 v[124:127], v[150:153], v[190:193], v[124:127]
	v_mfma_f32_16x16x32_bf16 v[120:123], v[166:169], v[190:193], v[120:123]
	v_mfma_f32_16x16x32_bf16 v[108:111], v[150:153], v[198:201], v[108:111]
	v_mfma_f32_16x16x32_bf16 v[104:107], v[166:169], v[198:201], v[104:107]
	v_mfma_f32_16x16x32_bf16 v[92:95], v[150:153], v[206:209], v[92:95]
	v_mfma_f32_16x16x32_bf16 v[88:91], v[166:169], v[206:209], v[88:91]
	v_mfma_f32_16x16x32_bf16 v[76:79], v[150:153], v[214:217], v[76:79]
	v_mfma_f32_16x16x32_bf16 v[72:75], v[166:169], v[214:217], v[72:75]
	v_mfma_f32_16x16x32_bf16 v[124:127], v[162:165], v[194:197], v[124:127]
	v_mfma_f32_16x16x32_bf16 v[120:123], v[170:173], v[194:197], v[120:123]
	v_mfma_f32_16x16x32_bf16 v[108:111], v[162:165], v[202:205], v[108:111]
	v_mfma_f32_16x16x32_bf16 v[104:107], v[170:173], v[202:205], v[104:107]
	v_mfma_f32_16x16x32_bf16 v[92:95], v[162:165], v[210:213], v[92:95]
	v_mfma_f32_16x16x32_bf16 v[88:91], v[170:173], v[210:213], v[88:91]
	v_mfma_f32_16x16x32_bf16 v[76:79], v[162:165], v[218:221], v[76:79]
	v_mfma_f32_16x16x32_bf16 v[72:75], v[170:173], v[218:221], v[72:75]
	v_mfma_f32_16x16x32_bf16 v[116:119], v[174:177], v[190:193], v[116:119]
	v_mfma_f32_16x16x32_bf16 v[112:115], v[182:185], v[190:193], v[112:115]
	v_mfma_f32_16x16x32_bf16 v[100:103], v[174:177], v[198:201], v[100:103]
	v_mfma_f32_16x16x32_bf16 v[96:99], v[182:185], v[198:201], v[96:99]
	v_mfma_f32_16x16x32_bf16 v[84:87], v[174:177], v[206:209], v[84:87]
	v_mfma_f32_16x16x32_bf16 v[80:83], v[182:185], v[206:209], v[80:83]
	v_mfma_f32_16x16x32_bf16 v[68:71], v[174:177], v[214:217], v[68:71]
	v_mfma_f32_16x16x32_bf16 v[64:67], v[182:185], v[214:217], v[64:67]
	v_mfma_f32_16x16x32_bf16 v[116:119], v[178:181], v[194:197], v[116:119]
	v_mfma_f32_16x16x32_bf16 v[112:115], v[186:189], v[194:197], v[112:115]
	v_mfma_f32_16x16x32_bf16 v[100:103], v[178:181], v[202:205], v[100:103]
	v_mfma_f32_16x16x32_bf16 v[96:99], v[186:189], v[202:205], v[96:99]
	v_mfma_f32_16x16x32_bf16 v[84:87], v[178:181], v[210:213], v[84:87]
	v_mfma_f32_16x16x32_bf16 v[80:83], v[186:189], v[210:213], v[80:83]
	v_mfma_f32_16x16x32_bf16 v[68:71], v[178:181], v[218:221], v[68:71]
	v_mfma_f32_16x16x32_bf16 v[64:67], v[186:189], v[218:221], v[64:67]
	s_barrier
	s_add_i32 s68, s70, s33
	s_mov_b32 m0, s68
	ds_read_b128 v[190:193], v160 offset:49152
	ds_read_b128 v[194:197], v160 offset:50176
	ds_read_b128 v[198:201], v160 offset:51200
	ds_read_b128 v[202:205], v160 offset:52224
	ds_read_b128 v[206:209], v160 offset:53248
	ds_read_b128 v[210:213], v160 offset:54272
	ds_read_b128 v[214:217], v160 offset:55296
	ds_read_b128 v[218:221], v160 offset:56320
	global_load_lds_dwordx4 v132, s[98:99]
	s_add_i32 m0, s68, 0x2000
	s_add_u32 s40, s40, 0x100080
	s_addc_u32 s41, s41, 0
	s_add_i32 s68, s71, s33
	global_load_lds_dwordx4 v128, s[98:99]
	s_mov_b32 m0, s68
	s_nop 0
	global_load_lds_dwordx4 v132, s[40:41]
	s_add_i32 m0, s68, 0x2000
	s_nop 0
	global_load_lds_dwordx4 v128, s[40:41]
	s_mov_b32 m0, s60
	s_nop 0
	global_load_lds_dwordx4 v134, s[100:101]
	s_mov_b32 m0, s61
	s_nop 0
	global_load_lds_dwordx4 v130, s[100:101]
	s_waitcnt vmcnt(8)
	s_waitcnt lgkmcnt(0)
	s_barrier
	v_mfma_f32_16x16x32_bf16 v[60:63], v[150:153], v[190:193], v[60:63]
	v_mfma_f32_16x16x32_bf16 v[56:59], v[166:169], v[190:193], v[56:59]
	v_mfma_f32_16x16x32_bf16 v[44:47], v[150:153], v[198:201], v[44:47]
	v_mfma_f32_16x16x32_bf16 v[40:43], v[166:169], v[198:201], v[40:43]
	v_mfma_f32_16x16x32_bf16 v[28:31], v[150:153], v[206:209], v[28:31]
	v_mfma_f32_16x16x32_bf16 v[24:27], v[166:169], v[206:209], v[24:27]
	v_mfma_f32_16x16x32_bf16 v[12:15], v[150:153], v[214:217], v[12:15]
	v_mfma_f32_16x16x32_bf16 v[8:11], v[166:169], v[214:217], v[8:11]
	v_mfma_f32_16x16x32_bf16 v[60:63], v[162:165], v[194:197], v[60:63]
	v_mfma_f32_16x16x32_bf16 v[56:59], v[170:173], v[194:197], v[56:59]
	v_mfma_f32_16x16x32_bf16 v[44:47], v[162:165], v[202:205], v[44:47]
	v_mfma_f32_16x16x32_bf16 v[40:43], v[170:173], v[202:205], v[40:43]
	v_mfma_f32_16x16x32_bf16 v[28:31], v[162:165], v[210:213], v[28:31]
	v_mfma_f32_16x16x32_bf16 v[24:27], v[170:173], v[210:213], v[24:27]
	v_mfma_f32_16x16x32_bf16 v[12:15], v[162:165], v[218:221], v[12:15]
	v_mfma_f32_16x16x32_bf16 v[8:11], v[170:173], v[218:221], v[8:11]
	v_mfma_f32_16x16x32_bf16 v[52:55], v[174:177], v[190:193], v[52:55]
	v_mfma_f32_16x16x32_bf16 v[48:51], v[182:185], v[190:193], v[48:51]
	v_mfma_f32_16x16x32_bf16 v[36:39], v[174:177], v[198:201], v[36:39]
	v_mfma_f32_16x16x32_bf16 v[32:35], v[182:185], v[198:201], v[32:35]
	v_mfma_f32_16x16x32_bf16 v[20:23], v[174:177], v[206:209], v[20:23]
	v_mfma_f32_16x16x32_bf16 v[16:19], v[182:185], v[206:209], v[16:19]
	v_mfma_f32_16x16x32_bf16 v[4:7], v[174:177], v[214:217], v[4:7]
	v_mfma_f32_16x16x32_bf16 v[0:3], v[182:185], v[214:217], v[0:3]
	v_mfma_f32_16x16x32_bf16 v[52:55], v[178:181], v[194:197], v[52:55]
	v_mfma_f32_16x16x32_bf16 v[48:51], v[186:189], v[194:197], v[48:51]
	v_mfma_f32_16x16x32_bf16 v[36:39], v[178:181], v[202:205], v[36:39]
	v_mfma_f32_16x16x32_bf16 v[32:35], v[186:189], v[202:205], v[32:35]
	v_mfma_f32_16x16x32_bf16 v[20:23], v[178:181], v[210:213], v[20:23]
	v_mfma_f32_16x16x32_bf16 v[16:19], v[186:189], v[210:213], v[16:19]
	v_mfma_f32_16x16x32_bf16 v[4:7], v[178:181], v[218:221], v[4:7]
	v_mfma_f32_16x16x32_bf16 v[0:3], v[186:189], v[218:221], v[0:3]
	s_barrier
	s_add_i32 s67, s67, 2
	s_add_u32 s34, s34, 0x100
	s_addc_u32 s35, s35, 0
	s_add_u32 s65, s65, 0x100
	s_addc_u32 s66, s66, 0
	s_cmp_gt_u32 s67, 61
	s_cbranch_scc0 .LBB0_1741
	s_setprio 0
	s_and_b64 vcc, exec, s[14:15]
	s_cbranch_vccz .LBB0_1744
	s_barrier

; #define PG8_STAGE(bufoff, gbase, voff) do { _Pragma("unroll") for (int _i = 0; _i < 2; ++_i) \
;         __builtin_amdgcn_global_load_lds((const unsigned*)((const char*)(gbase) + (voff)[_i]), (PG8_LAS unsigned*)(lds + (bufoff) + ldsw + _i * 8192), 16, 0, 0); } while (0)
; #define PG8_LDA(dst, b, h) do { _Pragma("unroll") for (int m = 0; m < 4; ++m) _Pragma("unroll") for (int k = 0; k < 2; ++k) dst[m][k] = *(const PG8_LAS bf16x8*)(lds + PG8_SA(b, h) + aoff + m * 2048 + k * 1024); } while (0)
; #define PG8_LDB(dst, b, h) do { _Pragma("unroll") for (int n = 0; n < 2; ++n) _Pragma("unroll") for (int k = 0; k < 2; ++k) dst[n][k] = *(const PG8_LAS bf16x8*)(lds + PG8_SB(b, h) + boff + n * 2048 + k * 1024); } while (0)
; #define PG8_WAIT_V(n) asm volatile("s_waitcnt vmcnt(" #n ")" ::: "memory")
; #define PG8_WAIT_L(n) asm volatile("s_waitcnt lgkmcnt(" #n ")" ::: "memory")
; #define PG8_BAR __builtin_amdgcn_s_barrier()
; template <class Epi, class Sched, bool ALIGN_EPI = false, bool SP2 = false>
; __device__ __forceinline__ void gemm_phase(PG8_LAS unsigned char* lds, const Gemm g, const Sched& S, const Epi& E) {
;     ...
;         const bool has_next = S.next(ui + 1, nxt);
;         const char* nA = has_next ? (const char*)g.A + (size_t)nxt.pm * tstep : cA; const char* nB = has_next ? (const char*)g.Bt + (size_t)nxt.pn * tstep : cB;
;         for (int t = 0; t < nt; t += 2) {
;             const bool last = (t == nt - 2);
;             const char* a1 = cA + (size_t)(t + 1) * kstepA;
;             const char* a2 = last ? nA : cA + (size_t)(t + 2) * kstepA; const char* b2 = last ? nB : cB + (size_t)(t + 2) * kstep;
;             const char* a3 = a2 + kstepA; const char* b3 = b2 + kstep;
;             if (last && has_next) S.a_ready(nxt);
;             if constexpr (SP2) {
;             PG8_LDB(B0, 0, 0); PG8_LDB(B1, 0, 1); PG8_SCHED; PG8_LDA(At, 0, 0); PG8_STAGE(PG8_SA(1, 1), a1 + hstepA, voffA);
;             PG8_WAIT_V(8); PG8_WAIT_L(0); PG8_BAR; PG8_MMA(0, 0, At, B0); PG8_MMA(0, 1, At, B1); PG8_BAR; PG8_SCHED;
;     ...
; #pragma unroll
;         for (int a = 0; a < 2; ++a)
; #pragma unroll
;             for (int b = 0; b < 2; ++b)
; #pragma unroll
;                 for (int m = 0; m < 4; ++m)
; #pragma unroll
;                     for (int n = 0; n < 2; ++n) acc[a][b][m][n] = (f32x4){0.f, 0.f, 0.f, 0.f};
;         cur = nxt; cA = nA; cB = nB; ++ui;
.LBB0_2769:
	s_ashr_i32 s31, s30, 31
	s_lshl_b64 s[34:35], s[30:31], 21
	s_add_u32 s34, s3, s34
	s_addc_u32 s35, s29, s35
	s_and_b64 s[40:41], s[4:5], exec
	s_cselect_b32 s31, s35, s47
	s_cselect_b32 s43, s34, s46
	s_ashr_i32 s27, s26, 31
	s_lshl_b64 s[40:41], s[26:27], 21
	s_add_u32 s40, s10, s40
	s_addc_u32 s41, s11, s41
	s_and_b64 s[50:51], s[4:5], exec
	s_cselect_b32 s27, s41, s49
	s_cselect_b32 s66, s40, s48
	s_add_u32 s46, s46, 0x100080
	s_addc_u32 s47, s47, 0
	s_add_u32 s67, s48, 0x100
	v_mov_b32_e32 v0, 0
	s_addc_u32 s68, s49, 0
	s_mov_b32 s69, -2
	s_waitcnt lgkmcnt(0)
	v_mov_b32_e32 v1, v0
	v_mov_b32_e32 v2, v0
	v_mov_b32_e32 v3, v0
	v_mov_b32_e32 v4, v0
	v_mov_b32_e32 v5, v0
	v_mov_b32_e32 v6, v0
	v_mov_b32_e32 v7, v0
	v_mov_b32_e32 v16, v0
	v_mov_b32_e32 v17, v0
	v_mov_b32_e32 v18, v0
	v_mov_b32_e32 v19, v0
	v_mov_b32_e32 v20, v0
	v_mov_b32_e32 v21, v0
	v_mov_b32_e32 v22, v0
	v_mov_b32_e32 v23, v0
	v_mov_b32_e32 v32, v0
	v_mov_b32_e32 v33, v0
	v_mov_b32_e32 v34, v0
	v_mov_b32_e32 v35, v0
	s_waitcnt vmcnt(0)
	v_mov_b32_e32 v36, v0
	v_mov_b32_e32 v37, v0
	v_mov_b32_e32 v38, v0
	v_mov_b32_e32 v39, v0
	v_mov_b32_e32 v48, v0
	v_mov_b32_e32 v49, v0
	v_mov_b32_e32 v50, v0
	v_mov_b32_e32 v51, v0
	v_mov_b32_e32 v52, v0
	v_mov_b32_e32 v53, v0
	v_mov_b32_e32 v54, v0
	v_mov_b32_e32 v55, v0
	v_mov_b32_e32 v8, v0
	v_mov_b32_e32 v9, v0
	v_mov_b32_e32 v10, v0
	v_mov_b32_e32 v11, v0
	v_mov_b32_e32 v12, v0
	v_mov_b32_e32 v13, v0
	v_mov_b32_e32 v14, v0
	v_mov_b32_e32 v15, v0
	v_mov_b32_e32 v24, v0
	v_mov_b32_e32 v25, v0
	v_mov_b32_e32 v26, v0
	v_mov_b32_e32 v27, v0
	v_mov_b32_e32 v28, v0
	v_mov_b32_e32 v29, v0
	v_mov_b32_e32 v30, v0
	v_mov_b32_e32 v31, v0
	v_mov_b32_e32 v40, v0
	v_mov_b32_e32 v41, v0
	v_mov_b32_e32 v42, v0
	v_mov_b32_e32 v43, v0
	v_mov_b32_e32 v44, v0
	v_mov_b32_e32 v45, v0
	v_mov_b32_e32 v46, v0
	v_mov_b32_e32 v47, v0
	v_mov_b32_e32 v56, v0
	v_mov_b32_e32 v57, v0
	v_mov_b32_e32 v58, v0
	v_mov_b32_e32 v59, v0
	v_mov_b32_e32 v60, v0
	v_mov_b32_e32 v61, v0
	v_mov_b32_e32 v62, v0
	v_mov_b32_e32 v63, v0
	v_mov_b32_e32 v64, v0
	v_mov_b32_e32 v65, v0
	v_mov_b32_e32 v66, v0
	v_mov_b32_e32 v67, v0
	v_mov_b32_e32 v68, v0
	v_mov_b32_e32 v69, v0
	v_mov_b32_e32 v70, v0
	v_mov_b32_e32 v71, v0
	v_mov_b32_e32 v80, v0
	v_mov_b32_e32 v81, v0
	v_mov_b32_e32 v82, v0
	v_mov_b32_e32 v83, v0
	v_mov_b32_e32 v84, v0
	v_mov_b32_e32 v85, v0
	v_mov_b32_e32 v86, v0
	v_mov_b32_e32 v87, v0
	v_mov_b32_e32 v96, v0
	v_mov_b32_e32 v97, v0
	v_mov_b32_e32 v98, v0
	v_mov_b32_e32 v99, v0
	v_mov_b32_e32 v100, v0
	v_mov_b32_e32 v101, v0
	v_mov_b32_e32 v102, v0
	v_mov_b32_e32 v103, v0
	v_mov_b32_e32 v112, v0
	v_mov_b32_e32 v113, v0
	v_mov_b32_e32 v114, v0
	v_mov_b32_e32 v115, v0
	v_mov_b32_e32 v116, v0
	v_mov_b32_e32 v117, v0
	v_mov_b32_e32 v118, v0
	v_mov_b32_e32 v119, v0
	v_mov_b32_e32 v72, v0
	v_mov_b32_e32 v73, v0
	v_mov_b32_e32 v74, v0
	v_mov_b32_e32 v75, v0
	v_mov_b32_e32 v76, v0
	v_mov_b32_e32 v77, v0
	v_mov_b32_e32 v78, v0
	v_mov_b32_e32 v79, v0
	v_mov_b32_e32 v88, v0
	v_mov_b32_e32 v89, v0
	v_mov_b32_e32 v90, v0
	v_mov_b32_e32 v91, v0
	v_mov_b32_e32 v92, v0
	v_mov_b32_e32 v93, v0
	v_mov_b32_e32 v94, v0
	v_mov_b32_e32 v95, v0
	v_mov_b32_e32 v104, v0
	v_mov_b32_e32 v105, v0
	v_mov_b32_e32 v106, v0
	v_mov_b32_e32 v107, v0
	v_mov_b32_e32 v108, v0
	v_mov_b32_e32 v109, v0
	v_mov_b32_e32 v110, v0
	v_mov_b32_e32 v111, v0
	v_mov_b32_e32 v120, v0
	v_mov_b32_e32 v121, v0
	v_mov_b32_e32 v122, v0
	v_mov_b32_e32 v123, v0
	v_mov_b32_e32 v124, v0
	v_mov_b32_e32 v125, v0
	v_mov_b32_e32 v126, v0
	v_mov_b32_e32 v127, v0
	s_cmp_ge_u32 s33, 0x1000
	s_cbranch_scc1 .Lsprio_4
	s_setprio 1
.Lsprio_4:
.LBB0_2770:
	ds_read_b128 v[144:147], v153
	ds_read_b128 v[158:161], v153 offset:1024
	ds_read_b128 v[162:165], v153 offset:2048
	ds_read_b128 v[166:169], v153 offset:3072
	ds_read_b128 v[170:173], v154
	ds_read_b128 v[174:177], v154 offset:1024
	ds_read_b128 v[178:181], v154 offset:2048
	ds_read_b128 v[182:185], v154 offset:3072
	s_add_u32 s48, s46, 0xfff00080
	s_addc_u32 s49, s47, -1
	s_cmp_eq_u32 s69, 60
	s_cselect_b32 s51, s31, s49
	s_cselect_b32 s50, s43, s48
	s_cselect_b32 s49, s27, s68
	s_cselect_b32 s48, s66, s67
	s_add_i32 m0, s45, 0xc000
	ds_read_b128 v[186:189], v155
	ds_read_b128 v[190:193], v155 offset:1024
	ds_read_b128 v[194:197], v155 offset:2048
	ds_read_b128 v[198:201], v155 offset:3072
	ds_read_b128 v[202:205], v155 offset:4096
	ds_read_b128 v[206:209], v155 offset:5120
	ds_read_b128 v[210:213], v155 offset:6144
	ds_read_b128 v[214:217], v155 offset:7168
	global_load_lds_dwordx4 v136, s[46:47]
	s_add_i32 m0, s45, 0xe000
	s_nop 0
	global_load_lds_dwordx4 v138, s[46:47]
	s_waitcnt vmcnt(8)
	s_waitcnt lgkmcnt(0)
	s_barrier
; #define PG8_STAGE(bufoff, gbase, voff) do { _Pragma("unroll") for (int _i = 0; _i < 2; ++_i) \
;         __builtin_amdgcn_global_load_lds((const unsigned*)((const char*)(gbase) + (voff)[_i]), (PG8_LAS unsigned*)(lds + (bufoff) + ldsw + _i * 8192), 16, 0, 0); } while (0)
; #define PG8_LDA(dst, b, h) do { _Pragma("unroll") for (int m = 0; m < 4; ++m) _Pragma("unroll") for (int k = 0; k < 2; ++k) dst[m][k] = *(const PG8_LAS bf16x8*)(lds + PG8_SA(b, h) + aoff + m * 2048 + k * 1024); } while (0)
; #define PG8_MMA(ai, bj, At, Bt) do { __builtin_amdgcn_s_setprio(1); _Pragma("unroll") for (int m = 0; m < 4; ++m) _Pragma("unroll") for (int n = 0; n < 2; ++n) _Pragma("unroll") for (int k = 0; k < 2; ++k) \
;         acc[ai][bj][m][n] = __builtin_amdgcn_mfma_f32_16x16x32_bf16(Bt[n][k], At[m][k], acc[ai][bj][m][n], 0, 0, 0); __builtin_amdgcn_s_setprio(0); } while (0)
; #define PG8_WAIT_V(n) asm volatile("s_waitcnt vmcnt(" #n ")" ::: "memory")
; #define PG8_WAIT_L(n) asm volatile("s_waitcnt lgkmcnt(" #n ")" ::: "memory")
; #define PG8_BAR __builtin_amdgcn_s_barrier()
; #define PG8_SCHED __builtin_amdgcn_sched_barrier(0)
; template <class Epi, class Sched, bool ALIGN_EPI = false, bool SP2 = false>
; __device__ __forceinline__ void gemm_phase(PG8_LAS unsigned char* lds, const Gemm g, const Sched& S, const Epi& E) {
;     ...
;             PG8_WAIT_V(8); PG8_WAIT_L(0); PG8_BAR; PG8_MMA(0, 0, At, B0); PG8_MMA(0, 1, At, B1); PG8_BAR; PG8_SCHED;
;             PG8_LDA(At, 0, 1); PG8_STAGE(PG8_SB(0, 0), b2, voffB); PG8_STAGE(PG8_SB(0, 1), b2 + hstep, voffB); PG8_STAGE(PG8_SA(0, 0), a2, voffA);
;             PG8_WAIT_V(8); PG8_WAIT_L(0); PG8_BAR; PG8_MMA(1, 0, At, B0); PG8_MMA(1, 1, At, B1); PG8_BAR; PG8_SCHED;
	v_mfma_f32_16x16x32_bf16 v[124:127], v[144:147], v[186:189], v[124:127]
	v_mfma_f32_16x16x32_bf16 v[120:123], v[162:165], v[186:189], v[120:123]
	v_mfma_f32_16x16x32_bf16 v[108:111], v[144:147], v[194:197], v[108:111]
	v_mfma_f32_16x16x32_bf16 v[104:107], v[162:165], v[194:197], v[104:107]
	v_mfma_f32_16x16x32_bf16 v[92:95], v[144:147], v[202:205], v[92:95]
	v_mfma_f32_16x16x32_bf16 v[88:91], v[162:165], v[202:205], v[88:91]
	v_mfma_f32_16x16x32_bf16 v[76:79], v[144:147], v[210:213], v[76:79]
	v_mfma_f32_16x16x32_bf16 v[72:75], v[162:165], v[210:213], v[72:75]
	v_mfma_f32_16x16x32_bf16 v[124:127], v[158:161], v[190:193], v[124:127]
	v_mfma_f32_16x16x32_bf16 v[120:123], v[166:169], v[190:193], v[120:123]
	v_mfma_f32_16x16x32_bf16 v[108:111], v[158:161], v[198:201], v[108:111]
	v_mfma_f32_16x16x32_bf16 v[104:107], v[166:169], v[198:201], v[104:107]
	v_mfma_f32_16x16x32_bf16 v[92:95], v[158:161], v[206:209], v[92:95]
	v_mfma_f32_16x16x32_bf16 v[88:91], v[166:169], v[206:209], v[88:91]
	v_mfma_f32_16x16x32_bf16 v[76:79], v[158:161], v[214:217], v[76:79]
	v_mfma_f32_16x16x32_bf16 v[72:75], v[166:169], v[214:217], v[72:75]
	v_mfma_f32_16x16x32_bf16 v[116:119], v[170:173], v[186:189], v[116:119]
	v_mfma_f32_16x16x32_bf16 v[112:115], v[178:181], v[186:189], v[112:115]
	v_mfma_f32_16x16x32_bf16 v[100:103], v[170:173], v[194:197], v[100:103]
	v_mfma_f32_16x16x32_bf16 v[96:99], v[178:181], v[194:197], v[96:99]
	v_mfma_f32_16x16x32_bf16 v[84:87], v[170:173], v[202:205], v[84:87]
	v_mfma_f32_16x16x32_bf16 v[80:83], v[178:181], v[202:205], v[80:83]
	v_mfma_f32_16x16x32_bf16 v[68:71], v[170:173], v[210:213], v[68:71]
	v_mfma_f32_16x16x32_bf16 v[64:67], v[178:181], v[210:213], v[64:67]
	v_mfma_f32_16x16x32_bf16 v[116:119], v[174:177], v[190:193], v[116:119]
	v_mfma_f32_16x16x32_bf16 v[112:115], v[182:185], v[190:193], v[112:115]
	v_mfma_f32_16x16x32_bf16 v[100:103], v[174:177], v[198:201], v[100:103]
	v_mfma_f32_16x16x32_bf16 v[96:99], v[182:185], v[198:201], v[96:99]
	v_mfma_f32_16x16x32_bf16 v[84:87], v[174:177], v[206:209], v[84:87]
	v_mfma_f32_16x16x32_bf16 v[80:83], v[182:185], v[206:209], v[80:83]
	v_mfma_f32_16x16x32_bf16 v[68:71], v[174:177], v[214:217], v[68:71]
	v_mfma_f32_16x16x32_bf16 v[64:67], v[182:185], v[214:217], v[64:67]
	s_barrier
	s_add_u32 s98, s48, s16
	s_addc_u32 s99, s49, s17
	s_add_u32 s100, s50, s16
	s_addc_u32 s101, s51, s17
	s_add_i32 s70, s60, s33
	s_mov_b32 m0, s70
	ds_read_b128 v[186:189], v155 offset:16384
	ds_read_b128 v[190:193], v155 offset:17408
	ds_read_b128 v[194:197], v155 offset:18432
	ds_read_b128 v[198:201], v155 offset:19456
	ds_read_b128 v[202:205], v155 offset:20480
	ds_read_b128 v[206:209], v155 offset:21504
	ds_read_b128 v[210:213], v155 offset:22528
	ds_read_b128 v[214:217], v155 offset:23552
	global_load_lds_dwordx4 v130, s[48:49]
	s_add_i32 m0, s70, 0x2000
	s_add_u32 s70, s48, 0x100000
	s_addc_u32 s71, s49, 0
	s_add_i32 s72, s61, s33
	global_load_lds_dwordx4 v134, s[48:49]
	s_mov_b32 m0, s72
	s_nop 0
	global_load_lds_dwordx4 v130, s[70:71]
	s_add_i32 m0, s72, 0x2000
	s_nop 0
	global_load_lds_dwordx4 v134, s[70:71]
	s_mov_b32 m0, s45
	s_nop 0
	global_load_lds_dwordx4 v128, s[50:51]
	s_mov_b32 m0, s52
	s_nop 0
	global_load_lds_dwordx4 v132, s[50:51]
	s_waitcnt vmcnt(8)
	s_waitcnt lgkmcnt(0)
	s_barrier
	v_mfma_f32_16x16x32_bf16 v[60:63], v[144:147], v[186:189], v[60:63]
	v_mfma_f32_16x16x32_bf16 v[56:59], v[162:165], v[186:189], v[56:59]
	v_mfma_f32_16x16x32_bf16 v[44:47], v[144:147], v[194:197], v[44:47]
	v_mfma_f32_16x16x32_bf16 v[40:43], v[162:165], v[194:197], v[40:43]
	v_mfma_f32_16x16x32_bf16 v[28:31], v[144:147], v[202:205], v[28:31]
	v_mfma_f32_16x16x32_bf16 v[24:27], v[162:165], v[202:205], v[24:27]
	v_mfma_f32_16x16x32_bf16 v[12:15], v[144:147], v[210:213], v[12:15]
	v_mfma_f32_16x16x32_bf16 v[8:11], v[162:165], v[210:213], v[8:11]
	v_mfma_f32_16x16x32_bf16 v[60:63], v[158:161], v[190:193], v[60:63]
	v_mfma_f32_16x16x32_bf16 v[56:59], v[166:169], v[190:193], v[56:59]
	v_mfma_f32_16x16x32_bf16 v[44:47], v[158:161], v[198:201], v[44:47]
	v_mfma_f32_16x16x32_bf16 v[40:43], v[166:169], v[198:201], v[40:43]
	v_mfma_f32_16x16x32_bf16 v[28:31], v[158:161], v[206:209], v[28:31]
	v_mfma_f32_16x16x32_bf16 v[24:27], v[166:169], v[206:209], v[24:27]
	v_mfma_f32_16x16x32_bf16 v[12:15], v[158:161], v[214:217], v[12:15]
	v_mfma_f32_16x16x32_bf16 v[8:11], v[166:169], v[214:217], v[8:11]
	v_mfma_f32_16x16x32_bf16 v[52:55], v[170:173], v[186:189], v[52:55]
	v_mfma_f32_16x16x32_bf16 v[48:51], v[178:181], v[186:189], v[48:51]
	v_mfma_f32_16x16x32_bf16 v[36:39], v[170:173], v[194:197], v[36:39]
	v_mfma_f32_16x16x32_bf16 v[32:35], v[178:181], v[194:197], v[32:35]
	v_mfma_f32_16x16x32_bf16 v[20:23], v[170:173], v[202:205], v[20:23]
	v_mfma_f32_16x16x32_bf16 v[16:19], v[178:181], v[202:205], v[16:19]
	v_mfma_f32_16x16x32_bf16 v[4:7], v[170:173], v[210:213], v[4:7]
	v_mfma_f32_16x16x32_bf16 v[0:3], v[178:181], v[210:213], v[0:3]
	v_mfma_f32_16x16x32_bf16 v[52:55], v[174:177], v[190:193], v[52:55]
	v_mfma_f32_16x16x32_bf16 v[48:51], v[182:185], v[190:193], v[48:51]
	v_mfma_f32_16x16x32_bf16 v[36:39], v[174:177], v[198:201], v[36:39]
	v_mfma_f32_16x16x32_bf16 v[32:35], v[182:185], v[198:201], v[32:35]
	v_mfma_f32_16x16x32_bf16 v[20:23], v[174:177], v[206:209], v[20:23]
	v_mfma_f32_16x16x32_bf16 v[16:19], v[182:185], v[206:209], v[16:19]
	v_mfma_f32_16x16x32_bf16 v[4:7], v[174:177], v[214:217], v[4:7]
	v_mfma_f32_16x16x32_bf16 v[0:3], v[182:185], v[214:217], v[0:3]
	s_barrier
; #define PG8_STAGE(bufoff, gbase, voff) do { _Pragma("unroll") for (int _i = 0; _i < 2; ++_i) \
;         __builtin_amdgcn_global_load_lds((const unsigned*)((const char*)(gbase) + (voff)[_i]), (PG8_LAS unsigned*)(lds + (bufoff) + ldsw + _i * 8192), 16, 0, 0); } while (0)
; #define PG8_LDA(dst, b, h) do { _Pragma("unroll") for (int m = 0; m < 4; ++m) _Pragma("unroll") for (int k = 0; k < 2; ++k) dst[m][k] = *(const PG8_LAS bf16x8*)(lds + PG8_SA(b, h) + aoff + m * 2048 + k * 1024); } while (0)
; #define PG8_LDB(dst, b, h) do { _Pragma("unroll") for (int n = 0; n < 2; ++n) _Pragma("unroll") for (int k = 0; k < 2; ++k) dst[n][k] = *(const PG8_LAS bf16x8*)(lds + PG8_SB(b, h) + boff + n * 2048 + k * 1024); } while (0)
; #define PG8_MMA(ai, bj, At, Bt) do { __builtin_amdgcn_s_setprio(1); _Pragma("unroll") for (int m = 0; m < 4; ++m) _Pragma("unroll") for (int n = 0; n < 2; ++n) _Pragma("unroll") for (int k = 0; k < 2; ++k) \
;         acc[ai][bj][m][n] = __builtin_amdgcn_mfma_f32_16x16x32_bf16(Bt[n][k], At[m][k], acc[ai][bj][m][n], 0, 0, 0); __builtin_amdgcn_s_setprio(0); } while (0)
; #define PG8_WAIT_V(n) asm volatile("s_waitcnt vmcnt(" #n ")" ::: "memory")
; #define PG8_WAIT_L(n) asm volatile("s_waitcnt lgkmcnt(" #n ")" ::: "memory")
; #define PG8_BAR __builtin_amdgcn_s_barrier()
; #define PG8_SCHED __builtin_amdgcn_sched_barrier(0)
; template <class Epi, class Sched, bool ALIGN_EPI = false, bool SP2 = false>
; __device__ __forceinline__ void gemm_phase(PG8_LAS unsigned char* lds, const Gemm g, const Sched& S, const Epi& E) {
;     ...
;         for (int t = 0; t < nt; t += 2) {
;     ...
;             PG8_LDB(B0, 1, 0); PG8_LDB(B1, 1, 1); PG8_SCHED; PG8_LDA(At, 1, 0); PG8_STAGE(PG8_SA(0, 1), a2 + hstepA, voffA);
;             PG8_WAIT_V(8); PG8_WAIT_L(0); PG8_BAR; PG8_MMA(0, 0, At, B0); PG8_MMA(0, 1, At, B1); PG8_BAR; PG8_SCHED;
;             PG8_LDA(At, 1, 1); PG8_STAGE(PG8_SB(1, 0), b3, voffB); PG8_STAGE(PG8_SB(1, 1), b3 + hstep, voffB); PG8_STAGE(PG8_SA(1, 0), a3, voffA);
;             PG8_WAIT_V(8); PG8_WAIT_L(0); PG8_BAR; PG8_MMA(1, 0, At, B0); PG8_MMA(1, 1, At, B1); PG8_BAR; PG8_SCHED;
	s_add_i32 s70, 0, 0x18000
	v_add_u32_e32 v157, s70, v151
	s_add_i32 s71, 0, 0x1c000
	ds_read_b128 v[144:147], v157
	ds_read_b128 v[158:161], v157 offset:1024
	ds_read_b128 v[162:165], v157 offset:2048
	ds_read_b128 v[166:169], v157 offset:3072
	v_add_u32_e32 v157, s71, v151
	ds_read_b128 v[170:173], v157
	ds_read_b128 v[174:177], v157 offset:1024
	ds_read_b128 v[178:181], v157 offset:2048
	ds_read_b128 v[182:185], v157 offset:3072
	s_add_u32 s50, s50, 0x100000
	s_addc_u32 s51, s51, 0
	s_mov_b32 m0, s53
	ds_read_b128 v[186:189], v155 offset:32768
	ds_read_b128 v[190:193], v155 offset:33792
	ds_read_b128 v[194:197], v155 offset:34816
	ds_read_b128 v[198:201], v155 offset:35840
	ds_read_b128 v[202:205], v155 offset:36864
	ds_read_b128 v[206:209], v155 offset:37888
	ds_read_b128 v[210:213], v155 offset:38912
	ds_read_b128 v[214:217], v155 offset:39936
	global_load_lds_dwordx4 v128, s[50:51]
	s_mov_b32 m0, s54
	s_nop 0
	global_load_lds_dwordx4 v132, s[50:51]
	s_waitcnt vmcnt(8)
	s_waitcnt lgkmcnt(0)
	s_barrier
	v_mfma_f32_16x16x32_bf16 v[124:127], v[144:147], v[186:189], v[124:127]
	v_mfma_f32_16x16x32_bf16 v[120:123], v[162:165], v[186:189], v[120:123]
	v_mfma_f32_16x16x32_bf16 v[108:111], v[144:147], v[194:197], v[108:111]
	v_mfma_f32_16x16x32_bf16 v[104:107], v[162:165], v[194:197], v[104:107]
	v_mfma_f32_16x16x32_bf16 v[92:95], v[144:147], v[202:205], v[92:95]
	v_mfma_f32_16x16x32_bf16 v[88:91], v[162:165], v[202:205], v[88:91]
	v_mfma_f32_16x16x32_bf16 v[76:79], v[144:147], v[210:213], v[76:79]
	v_mfma_f32_16x16x32_bf16 v[72:75], v[162:165], v[210:213], v[72:75]
	v_mfma_f32_16x16x32_bf16 v[124:127], v[158:161], v[190:193], v[124:127]
	v_mfma_f32_16x16x32_bf16 v[120:123], v[166:169], v[190:193], v[120:123]
	v_mfma_f32_16x16x32_bf16 v[108:111], v[158:161], v[198:201], v[108:111]
	v_mfma_f32_16x16x32_bf16 v[104:107], v[166:169], v[198:201], v[104:107]
	v_mfma_f32_16x16x32_bf16 v[92:95], v[158:161], v[206:209], v[92:95]
	v_mfma_f32_16x16x32_bf16 v[88:91], v[166:169], v[206:209], v[88:91]
	v_mfma_f32_16x16x32_bf16 v[76:79], v[158:161], v[214:217], v[76:79]
	v_mfma_f32_16x16x32_bf16 v[72:75], v[166:169], v[214:217], v[72:75]
	v_mfma_f32_16x16x32_bf16 v[116:119], v[170:173], v[186:189], v[116:119]
	v_mfma_f32_16x16x32_bf16 v[112:115], v[178:181], v[186:189], v[112:115]
	v_mfma_f32_16x16x32_bf16 v[100:103], v[170:173], v[194:197], v[100:103]
	v_mfma_f32_16x16x32_bf16 v[96:99], v[178:181], v[194:197], v[96:99]
	v_mfma_f32_16x16x32_bf16 v[84:87], v[170:173], v[202:205], v[84:87]
	v_mfma_f32_16x16x32_bf16 v[80:83], v[178:181], v[202:205], v[80:83]
	v_mfma_f32_16x16x32_bf16 v[68:71], v[170:173], v[210:213], v[68:71]
	v_mfma_f32_16x16x32_bf16 v[64:67], v[178:181], v[210:213], v[64:67]
	v_mfma_f32_16x16x32_bf16 v[116:119], v[174:177], v[190:193], v[116:119]
	v_mfma_f32_16x16x32_bf16 v[112:115], v[182:185], v[190:193], v[112:115]
	v_mfma_f32_16x16x32_bf16 v[100:103], v[174:177], v[198:201], v[100:103]
	v_mfma_f32_16x16x32_bf16 v[96:99], v[182:185], v[198:201], v[96:99]
	v_mfma_f32_16x16x32_bf16 v[84:87], v[174:177], v[206:209], v[84:87]
	v_mfma_f32_16x16x32_bf16 v[80:83], v[182:185], v[206:209], v[80:83]
	v_mfma_f32_16x16x32_bf16 v[68:71], v[174:177], v[214:217], v[68:71]
	v_mfma_f32_16x16x32_bf16 v[64:67], v[182:185], v[214:217], v[64:67]
	s_barrier
	s_add_i32 s50, s70, s33
	s_mov_b32 m0, s50
	ds_read_b128 v[186:189], v155 offset:49152
	ds_read_b128 v[190:193], v155 offset:50176
	ds_read_b128 v[194:197], v155 offset:51200
	ds_read_b128 v[198:201], v155 offset:52224
	ds_read_b128 v[202:205], v155 offset:53248
	ds_read_b128 v[206:209], v155 offset:54272
	ds_read_b128 v[210:213], v155 offset:55296
	ds_read_b128 v[214:217], v155 offset:56320
	global_load_lds_dwordx4 v130, s[98:99]
	s_add_i32 m0, s50, 0x2000
	s_add_u32 s48, s48, 0x100080
	s_addc_u32 s49, s49, 0
	s_add_i32 s50, s71, s33
	global_load_lds_dwordx4 v134, s[98:99]
	s_mov_b32 m0, s50
	s_nop 0
	global_load_lds_dwordx4 v130, s[48:49]
	s_add_i32 m0, s50, 0x2000
	s_nop 0
	global_load_lds_dwordx4 v134, s[48:49]
	s_mov_b32 m0, s56
	s_nop 0
	global_load_lds_dwordx4 v128, s[100:101]
	s_mov_b32 m0, s57
	s_nop 0
	global_load_lds_dwordx4 v132, s[100:101]
	s_waitcnt vmcnt(8)
	s_waitcnt lgkmcnt(0)
	s_barrier
	v_mfma_f32_16x16x32_bf16 v[60:63], v[144:147], v[186:189], v[60:63]
	v_mfma_f32_16x16x32_bf16 v[56:59], v[162:165], v[186:189], v[56:59]
	v_mfma_f32_16x16x32_bf16 v[44:47], v[144:147], v[194:197], v[44:47]
	v_mfma_f32_16x16x32_bf16 v[40:43], v[162:165], v[194:197], v[40:43]
	v_mfma_f32_16x16x32_bf16 v[28:31], v[144:147], v[202:205], v[28:31]
	v_mfma_f32_16x16x32_bf16 v[24:27], v[162:165], v[202:205], v[24:27]
	v_mfma_f32_16x16x32_bf16 v[12:15], v[144:147], v[210:213], v[12:15]
	v_mfma_f32_16x16x32_bf16 v[8:11], v[162:165], v[210:213], v[8:11]
	v_mfma_f32_16x16x32_bf16 v[60:63], v[158:161], v[190:193], v[60:63]
	v_mfma_f32_16x16x32_bf16 v[56:59], v[166:169], v[190:193], v[56:59]
	v_mfma_f32_16x16x32_bf16 v[44:47], v[158:161], v[198:201], v[44:47]
	v_mfma_f32_16x16x32_bf16 v[40:43], v[166:169], v[198:201], v[40:43]
	v_mfma_f32_16x16x32_bf16 v[28:31], v[158:161], v[206:209], v[28:31]
	v_mfma_f32_16x16x32_bf16 v[24:27], v[166:169], v[206:209], v[24:27]
	v_mfma_f32_16x16x32_bf16 v[12:15], v[158:161], v[214:217], v[12:15]
	v_mfma_f32_16x16x32_bf16 v[8:11], v[166:169], v[214:217], v[8:11]
	v_mfma_f32_16x16x32_bf16 v[52:55], v[170:173], v[186:189], v[52:55]
	v_mfma_f32_16x16x32_bf16 v[48:51], v[178:181], v[186:189], v[48:51]
	v_mfma_f32_16x16x32_bf16 v[36:39], v[170:173], v[194:197], v[36:39]
	v_mfma_f32_16x16x32_bf16 v[32:35], v[178:181], v[194:197], v[32:35]
	v_mfma_f32_16x16x32_bf16 v[20:23], v[170:173], v[202:205], v[20:23]
	v_mfma_f32_16x16x32_bf16 v[16:19], v[178:181], v[202:205], v[16:19]
	v_mfma_f32_16x16x32_bf16 v[4:7], v[170:173], v[210:213], v[4:7]
	v_mfma_f32_16x16x32_bf16 v[0:3], v[178:181], v[210:213], v[0:3]
	v_mfma_f32_16x16x32_bf16 v[52:55], v[174:177], v[190:193], v[52:55]
	v_mfma_f32_16x16x32_bf16 v[48:51], v[182:185], v[190:193], v[48:51]
	v_mfma_f32_16x16x32_bf16 v[36:39], v[174:177], v[198:201], v[36:39]
	v_mfma_f32_16x16x32_bf16 v[32:35], v[182:185], v[198:201], v[32:35]
	v_mfma_f32_16x16x32_bf16 v[20:23], v[174:177], v[206:209], v[20:23]
	v_mfma_f32_16x16x32_bf16 v[16:19], v[182:185], v[206:209], v[16:19]
	v_mfma_f32_16x16x32_bf16 v[4:7], v[174:177], v[214:217], v[4:7]
	v_mfma_f32_16x16x32_bf16 v[0:3], v[182:185], v[214:217], v[0:3]
	s_barrier
	s_add_i32 s69, s69, 2
	s_add_u32 s46, s46, 0x100
	s_addc_u32 s47, s47, 0
	s_add_u32 s67, s67, 0x100
	s_addc_u32 s68, s68, 0
	s_cmp_gt_u32 s69, 61
	s_cbranch_scc0 .LBB0_2770
	s_setprio 0
	s_and_b64 vcc, exec, s[18:19]
	s_cbranch_vccz .LBB0_2773
	s_barrier

; #define PG8_STAGE(bufoff, gbase, voff) do { _Pragma("unroll") for (int _i = 0; _i < 2; ++_i) \
;         __builtin_amdgcn_global_load_lds((const unsigned*)((const char*)(gbase) + (voff)[_i]), (PG8_LAS unsigned*)(lds + (bufoff) + ldsw + _i * 8192), 16, 0, 0); } while (0)
; #define PG8_LDA(dst, b, h) do { _Pragma("unroll") for (int m = 0; m < 4; ++m) _Pragma("unroll") for (int k = 0; k < 2; ++k) dst[m][k] = *(const PG8_LAS bf16x8*)(lds + PG8_SA(b, h) + aoff + m * 2048 + k * 1024); } while (0)
; #define PG8_LDB(dst, b, h) do { _Pragma("unroll") for (int n = 0; n < 2; ++n) _Pragma("unroll") for (int k = 0; k < 2; ++k) dst[n][k] = *(const PG8_LAS bf16x8*)(lds + PG8_SB(b, h) + boff + n * 2048 + k * 1024); } while (0)
; #define PG8_WAIT_V(n) asm volatile("s_waitcnt vmcnt(" #n ")" ::: "memory")
; #define PG8_WAIT_L(n) asm volatile("s_waitcnt lgkmcnt(" #n ")" ::: "memory")
; #define PG8_BAR __builtin_amdgcn_s_barrier()
; template <class Epi, class Sched, bool ALIGN_EPI = false, bool SP2 = false>
; __device__ __forceinline__ void gemm_phase(PG8_LAS unsigned char* lds, const Gemm g, const Sched& S, const Epi& E) {
;     ...
;         const bool has_next = S.next(ui + 1, nxt);
;         const char* nA = has_next ? (const char*)g.A + (size_t)nxt.pm * tstep : cA; const char* nB = has_next ? (const char*)g.Bt + (size_t)nxt.pn * tstep : cB;
;         for (int t = 0; t < nt; t += 2) {
;             const bool last = (t == nt - 2);
;             const char* a1 = cA + (size_t)(t + 1) * kstepA;
;             const char* a2 = last ? nA : cA + (size_t)(t + 2) * kstepA; const char* b2 = last ? nB : cB + (size_t)(t + 2) * kstep;
;             const char* a3 = a2 + kstepA; const char* b3 = b2 + kstep;
;             if (last && has_next) S.a_ready(nxt);
;             if constexpr (SP2) {
;             PG8_LDB(B0, 0, 0); PG8_LDB(B1, 0, 1); PG8_SCHED; PG8_LDA(At, 0, 0); PG8_STAGE(PG8_SA(1, 1), a1 + hstepA, voffA);
;             PG8_WAIT_V(8); PG8_WAIT_L(0); PG8_BAR; PG8_MMA(0, 0, At, B0); PG8_MMA(0, 1, At, B1); PG8_BAR; PG8_SCHED;
;     ...
; #pragma unroll
;         for (int a = 0; a < 2; ++a)
; #pragma unroll
;             for (int b = 0; b < 2; ++b)
; #pragma unroll
;                 for (int m = 0; m < 4; ++m)
; #pragma unroll
;                     for (int n = 0; n < 2; ++n) acc[a][b][m][n] = (f32x4){0.f, 0.f, 0.f, 0.f};
;         cur = nxt; cA = nA; cB = nB; ++ui;
.LBB0_2881:
	s_ashr_i32 s51, s50, 31
	s_lshl_b64 s[52:53], s[50:51], 21
	s_add_u32 s52, s96, s52
	s_addc_u32 s53, s97, s53
	s_and_b64 s[54:55], s[4:5], exec
	s_cselect_b32 s7, s53, s9
	s_cselect_b32 s51, s52, s8
	s_ashr_i32 s49, s48, 31
	s_lshl_b64 s[54:55], s[48:49], 21
	s_add_u32 s54, s29, s54
	s_addc_u32 s55, s33, s55
	s_and_b64 s[58:59], s[4:5], exec
	s_cselect_b32 s49, s55, s11
	s_cselect_b32 s85, s54, s10
	s_add_u32 s86, s10, 0x100
	v_mov_b32_e32 v0, 0
	s_addc_u32 s87, s11, 0
	s_mov_b32 s88, -2
	v_mov_b32_e32 v1, v0
	v_mov_b32_e32 v2, v0
	v_mov_b32_e32 v3, v0
	v_mov_b32_e32 v4, v0
	v_mov_b32_e32 v5, v0
	v_mov_b32_e32 v6, v0
	v_mov_b32_e32 v7, v0
	v_mov_b32_e32 v16, v0
	v_mov_b32_e32 v17, v0
	v_mov_b32_e32 v18, v0
	v_mov_b32_e32 v19, v0
	v_mov_b32_e32 v20, v0
	v_mov_b32_e32 v21, v0
	v_mov_b32_e32 v22, v0
	v_mov_b32_e32 v23, v0
	v_mov_b32_e32 v32, v0
	v_mov_b32_e32 v33, v0
	v_mov_b32_e32 v34, v0
	v_mov_b32_e32 v35, v0
	s_waitcnt vmcnt(0)
	v_mov_b32_e32 v36, v0
	v_mov_b32_e32 v37, v0
	v_mov_b32_e32 v38, v0
	v_mov_b32_e32 v39, v0
	v_mov_b32_e32 v48, v0
	v_mov_b32_e32 v49, v0
	v_mov_b32_e32 v50, v0
	v_mov_b32_e32 v51, v0
	v_mov_b32_e32 v52, v0
	v_mov_b32_e32 v53, v0
	v_mov_b32_e32 v54, v0
	v_mov_b32_e32 v55, v0
	v_mov_b32_e32 v8, v0
	v_mov_b32_e32 v9, v0
	v_mov_b32_e32 v10, v0
	v_mov_b32_e32 v11, v0
	v_mov_b32_e32 v12, v0
	v_mov_b32_e32 v13, v0
	v_mov_b32_e32 v14, v0
	v_mov_b32_e32 v15, v0
	v_mov_b32_e32 v24, v0
	v_mov_b32_e32 v25, v0
	v_mov_b32_e32 v26, v0
	v_mov_b32_e32 v27, v0
	v_mov_b32_e32 v28, v0
	v_mov_b32_e32 v29, v0
	v_mov_b32_e32 v30, v0
	v_mov_b32_e32 v31, v0
	v_mov_b32_e32 v40, v0
	v_mov_b32_e32 v41, v0
	v_mov_b32_e32 v42, v0
	v_mov_b32_e32 v43, v0
	v_mov_b32_e32 v44, v0
	v_mov_b32_e32 v45, v0
	v_mov_b32_e32 v46, v0
	v_mov_b32_e32 v47, v0
	v_mov_b32_e32 v56, v0
	v_mov_b32_e32 v57, v0
	v_mov_b32_e32 v58, v0
	v_mov_b32_e32 v59, v0
	v_mov_b32_e32 v60, v0
	v_mov_b32_e32 v61, v0
	v_mov_b32_e32 v62, v0
	v_mov_b32_e32 v63, v0
	v_mov_b32_e32 v64, v0
	v_mov_b32_e32 v65, v0
	v_mov_b32_e32 v66, v0
	v_mov_b32_e32 v67, v0
	v_mov_b32_e32 v68, v0
	v_mov_b32_e32 v69, v0
	v_mov_b32_e32 v70, v0
	v_mov_b32_e32 v71, v0
	v_mov_b32_e32 v80, v0
	v_mov_b32_e32 v81, v0
	v_mov_b32_e32 v82, v0
	v_mov_b32_e32 v83, v0
	v_mov_b32_e32 v84, v0
	v_mov_b32_e32 v85, v0
	v_mov_b32_e32 v86, v0
	v_mov_b32_e32 v87, v0
	v_mov_b32_e32 v96, v0
	v_mov_b32_e32 v97, v0
	v_mov_b32_e32 v98, v0
	v_mov_b32_e32 v99, v0
	v_mov_b32_e32 v100, v0
	v_mov_b32_e32 v101, v0
	v_mov_b32_e32 v102, v0
	v_mov_b32_e32 v103, v0
	v_mov_b32_e32 v112, v0
	v_mov_b32_e32 v113, v0
	v_mov_b32_e32 v114, v0
	v_mov_b32_e32 v115, v0
	v_mov_b32_e32 v116, v0
	v_mov_b32_e32 v117, v0
	v_mov_b32_e32 v118, v0
	v_mov_b32_e32 v119, v0
	v_mov_b32_e32 v72, v0
	v_mov_b32_e32 v73, v0
	v_mov_b32_e32 v74, v0
	v_mov_b32_e32 v75, v0
	v_mov_b32_e32 v76, v0
	v_mov_b32_e32 v77, v0
	v_mov_b32_e32 v78, v0
	v_mov_b32_e32 v79, v0
	v_mov_b32_e32 v88, v0
	v_mov_b32_e32 v89, v0
	v_mov_b32_e32 v90, v0
	v_mov_b32_e32 v91, v0
	v_mov_b32_e32 v92, v0
	v_mov_b32_e32 v93, v0
	v_mov_b32_e32 v94, v0
	v_mov_b32_e32 v95, v0
	v_mov_b32_e32 v104, v0
	v_mov_b32_e32 v105, v0
	v_mov_b32_e32 v106, v0
	v_mov_b32_e32 v107, v0
	v_mov_b32_e32 v108, v0
	v_mov_b32_e32 v109, v0
	v_mov_b32_e32 v110, v0
	v_mov_b32_e32 v111, v0
	v_mov_b32_e32 v120, v0
	v_mov_b32_e32 v121, v0
	v_mov_b32_e32 v122, v0
	v_mov_b32_e32 v123, v0
	v_mov_b32_e32 v124, v0
	v_mov_b32_e32 v125, v0
	v_mov_b32_e32 v126, v0
	v_mov_b32_e32 v127, v0
	s_cmp_ge_u32 s63, 0x1000
	s_cbranch_scc1 .Lsprio_3
	s_setprio 1
.Lsprio_3:
.LBB0_2882:
	ds_read_b128 v[128:131], v236
	ds_read_b128 v[132:135], v236 offset:1024
	ds_read_b128 v[136:139], v236 offset:2048
	ds_read_b128 v[140:143], v236 offset:3072
	ds_read_b128 v[144:147], v237
	ds_read_b128 v[148:151], v237 offset:1024
	ds_read_b128 v[152:155], v237 offset:2048
	ds_read_b128 v[156:159], v237 offset:3072
	s_add_u32 s10, s8, 0x100
	s_addc_u32 s11, s9, 0
	s_cmp_eq_u32 s88, 60
	s_cselect_b32 s61, s7, s11
	s_cselect_b32 s60, s51, s10
	s_cselect_b32 s59, s49, s87
	s_cselect_b32 s58, s85, s86
	v_lshl_add_u64 v[164:165], s[8:9], 0, v[178:179]
	s_add_i32 m0, s57, 0xc000
	ds_read_b128 v[160:163], v238
	ds_read_b128 v[186:189], v238 offset:1024
	ds_read_b128 v[190:193], v238 offset:2048
	ds_read_b128 v[194:197], v238 offset:3072
	ds_read_b128 v[198:201], v238 offset:4096
	ds_read_b128 v[202:205], v238 offset:5120
	ds_read_b128 v[206:209], v238 offset:6144
	ds_read_b128 v[210:213], v238 offset:7168
	global_load_lds_dwordx4 v[164:165], off
	v_lshl_add_u64 v[164:165], s[8:9], 0, v[180:181]
	s_add_i32 m0, s57, 0xe000
	s_nop 0
	global_load_lds_dwordx4 v[164:165], off
	s_waitcnt vmcnt(8)
	s_waitcnt lgkmcnt(0)
	s_barrier
; #define PG8_STAGE(bufoff, gbase, voff) do { _Pragma("unroll") for (int _i = 0; _i < 2; ++_i) \
;         __builtin_amdgcn_global_load_lds((const unsigned*)((const char*)(gbase) + (voff)[_i]), (PG8_LAS unsigned*)(lds + (bufoff) + ldsw + _i * 8192), 16, 0, 0); } while (0)
; #define PG8_LDA(dst, b, h) do { _Pragma("unroll") for (int m = 0; m < 4; ++m) _Pragma("unroll") for (int k = 0; k < 2; ++k) dst[m][k] = *(const PG8_LAS bf16x8*)(lds + PG8_SA(b, h) + aoff + m * 2048 + k * 1024); } while (0)
; #define PG8_MMA(ai, bj, At, Bt) do { __builtin_amdgcn_s_setprio(1); _Pragma("unroll") for (int m = 0; m < 4; ++m) _Pragma("unroll") for (int n = 0; n < 2; ++n) _Pragma("unroll") for (int k = 0; k < 2; ++k) \
;         acc[ai][bj][m][n] = __builtin_amdgcn_mfma_f32_16x16x32_bf16(Bt[n][k], At[m][k], acc[ai][bj][m][n], 0, 0, 0); __builtin_amdgcn_s_setprio(0); } while (0)
; #define PG8_WAIT_V(n) asm volatile("s_waitcnt vmcnt(" #n ")" ::: "memory")
; #define PG8_WAIT_L(n) asm volatile("s_waitcnt lgkmcnt(" #n ")" ::: "memory")
; #define PG8_BAR __builtin_amdgcn_s_barrier()
; #define PG8_SCHED __builtin_amdgcn_sched_barrier(0)
; template <class Epi, class Sched, bool ALIGN_EPI = false, bool SP2 = false>
; __device__ __forceinline__ void gemm_phase(PG8_LAS unsigned char* lds, const Gemm g, const Sched& S, const Epi& E) {
;     ...
;             PG8_WAIT_V(8); PG8_WAIT_L(0); PG8_BAR; PG8_MMA(0, 0, At, B0); PG8_MMA(0, 1, At, B1); PG8_BAR; PG8_SCHED;
;             PG8_LDA(At, 0, 1); PG8_STAGE(PG8_SB(0, 0), b2, voffB); PG8_STAGE(PG8_SB(0, 1), b2 + hstep, voffB); PG8_STAGE(PG8_SA(0, 0), a2, voffA);
;             PG8_WAIT_V(8); PG8_WAIT_L(0); PG8_BAR; PG8_MMA(1, 0, At, B0); PG8_MMA(1, 1, At, B1); PG8_BAR; PG8_SCHED;
	v_mfma_f32_16x16x32_bf16 v[124:127], v[128:131], v[160:163], v[124:127]
	v_mfma_f32_16x16x32_bf16 v[120:123], v[136:139], v[160:163], v[120:123]
	v_mfma_f32_16x16x32_bf16 v[108:111], v[128:131], v[190:193], v[108:111]
	v_mfma_f32_16x16x32_bf16 v[104:107], v[136:139], v[190:193], v[104:107]
	v_mfma_f32_16x16x32_bf16 v[92:95], v[128:131], v[198:201], v[92:95]
	v_mfma_f32_16x16x32_bf16 v[88:91], v[136:139], v[198:201], v[88:91]
	v_mfma_f32_16x16x32_bf16 v[76:79], v[128:131], v[206:209], v[76:79]
	v_mfma_f32_16x16x32_bf16 v[72:75], v[136:139], v[206:209], v[72:75]
	v_mfma_f32_16x16x32_bf16 v[124:127], v[132:135], v[186:189], v[124:127]
	v_mfma_f32_16x16x32_bf16 v[120:123], v[140:143], v[186:189], v[120:123]
	v_mfma_f32_16x16x32_bf16 v[108:111], v[132:135], v[194:197], v[108:111]
	v_mfma_f32_16x16x32_bf16 v[104:107], v[140:143], v[194:197], v[104:107]
	v_mfma_f32_16x16x32_bf16 v[92:95], v[132:135], v[202:205], v[92:95]
	v_mfma_f32_16x16x32_bf16 v[88:91], v[140:143], v[202:205], v[88:91]
	v_mfma_f32_16x16x32_bf16 v[76:79], v[132:135], v[210:213], v[76:79]
	v_mfma_f32_16x16x32_bf16 v[72:75], v[140:143], v[210:213], v[72:75]
	v_mfma_f32_16x16x32_bf16 v[116:119], v[144:147], v[160:163], v[116:119]
	v_mfma_f32_16x16x32_bf16 v[112:115], v[152:155], v[160:163], v[112:115]
	v_mfma_f32_16x16x32_bf16 v[100:103], v[144:147], v[190:193], v[100:103]
	v_mfma_f32_16x16x32_bf16 v[96:99], v[152:155], v[190:193], v[96:99]
	v_mfma_f32_16x16x32_bf16 v[84:87], v[144:147], v[198:201], v[84:87]
	v_mfma_f32_16x16x32_bf16 v[80:83], v[152:155], v[198:201], v[80:83]
	v_mfma_f32_16x16x32_bf16 v[68:71], v[144:147], v[206:209], v[68:71]
	v_mfma_f32_16x16x32_bf16 v[64:67], v[152:155], v[206:209], v[64:67]
	v_mfma_f32_16x16x32_bf16 v[116:119], v[148:151], v[186:189], v[116:119]
	v_mfma_f32_16x16x32_bf16 v[112:115], v[156:159], v[186:189], v[112:115]
	v_mfma_f32_16x16x32_bf16 v[100:103], v[148:151], v[194:197], v[100:103]
	v_mfma_f32_16x16x32_bf16 v[96:99], v[156:159], v[194:197], v[96:99]
	v_mfma_f32_16x16x32_bf16 v[84:87], v[148:151], v[202:205], v[84:87]
	v_mfma_f32_16x16x32_bf16 v[80:83], v[156:159], v[202:205], v[80:83]
	v_mfma_f32_16x16x32_bf16 v[68:71], v[148:151], v[210:213], v[68:71]
	v_mfma_f32_16x16x32_bf16 v[64:67], v[156:159], v[210:213], v[64:67]
	s_barrier
	s_add_u32 s98, s58, s16
	s_addc_u32 s99, s59, s17
	s_add_u32 s100, s60, s16
	s_addc_u32 s101, s61, s17
	s_add_i32 s8, s72, s63
	s_mov_b32 m0, s8
	ds_read_b128 v[160:163], v238 offset:16384
	ds_read_b128 v[186:189], v238 offset:17408
	ds_read_b128 v[190:193], v238 offset:18432
	ds_read_b128 v[194:197], v238 offset:19456
	ds_read_b128 v[198:201], v238 offset:20480
	ds_read_b128 v[202:205], v238 offset:21504
	ds_read_b128 v[206:209], v238 offset:22528
	ds_read_b128 v[210:213], v238 offset:23552
	global_load_lds_dwordx4 v168, s[58:59]
	s_add_i32 m0, s8, 0x2000
	s_add_u32 s8, s58, 0x100000
	s_addc_u32 s9, s59, 0
	s_add_i32 s89, s73, s63
	global_load_lds_dwordx4 v172, s[58:59]
	s_mov_b32 m0, s89
	s_nop 0
	global_load_lds_dwordx4 v168, s[8:9]
	s_add_i32 m0, s89, 0x2000
	s_nop 0
	global_load_lds_dwordx4 v172, s[8:9]
	s_mov_b32 m0, s57
	s_nop 0
	global_load_lds_dwordx4 v166, s[60:61]
	s_mov_b32 m0, s64
	s_nop 0
	global_load_lds_dwordx4 v170, s[60:61]
	s_waitcnt vmcnt(8)
	s_waitcnt lgkmcnt(0)
	s_barrier
	v_mfma_f32_16x16x32_bf16 v[60:63], v[128:131], v[160:163], v[60:63]
	v_mfma_f32_16x16x32_bf16 v[56:59], v[136:139], v[160:163], v[56:59]
	v_mfma_f32_16x16x32_bf16 v[44:47], v[128:131], v[190:193], v[44:47]
	v_mfma_f32_16x16x32_bf16 v[40:43], v[136:139], v[190:193], v[40:43]
	v_mfma_f32_16x16x32_bf16 v[28:31], v[128:131], v[198:201], v[28:31]
	v_mfma_f32_16x16x32_bf16 v[24:27], v[136:139], v[198:201], v[24:27]
	v_mfma_f32_16x16x32_bf16 v[12:15], v[128:131], v[206:209], v[12:15]
	v_mfma_f32_16x16x32_bf16 v[8:11], v[136:139], v[206:209], v[8:11]
	v_mfma_f32_16x16x32_bf16 v[60:63], v[132:135], v[186:189], v[60:63]
	v_mfma_f32_16x16x32_bf16 v[56:59], v[140:143], v[186:189], v[56:59]
	v_mfma_f32_16x16x32_bf16 v[44:47], v[132:135], v[194:197], v[44:47]
	v_mfma_f32_16x16x32_bf16 v[40:43], v[140:143], v[194:197], v[40:43]
	v_mfma_f32_16x16x32_bf16 v[28:31], v[132:135], v[202:205], v[28:31]
	v_mfma_f32_16x16x32_bf16 v[24:27], v[140:143], v[202:205], v[24:27]
	v_mfma_f32_16x16x32_bf16 v[12:15], v[132:135], v[210:213], v[12:15]
	v_mfma_f32_16x16x32_bf16 v[8:11], v[140:143], v[210:213], v[8:11]
	v_mfma_f32_16x16x32_bf16 v[52:55], v[144:147], v[160:163], v[52:55]
	v_mfma_f32_16x16x32_bf16 v[48:51], v[152:155], v[160:163], v[48:51]
	v_mfma_f32_16x16x32_bf16 v[36:39], v[144:147], v[190:193], v[36:39]
	v_mfma_f32_16x16x32_bf16 v[32:35], v[152:155], v[190:193], v[32:35]
	v_mfma_f32_16x16x32_bf16 v[20:23], v[144:147], v[198:201], v[20:23]
	v_mfma_f32_16x16x32_bf16 v[16:19], v[152:155], v[198:201], v[16:19]
	v_mfma_f32_16x16x32_bf16 v[4:7], v[144:147], v[206:209], v[4:7]
	v_mfma_f32_16x16x32_bf16 v[0:3], v[152:155], v[206:209], v[0:3]
	v_mfma_f32_16x16x32_bf16 v[52:55], v[148:151], v[186:189], v[52:55]
	v_mfma_f32_16x16x32_bf16 v[48:51], v[156:159], v[186:189], v[48:51]
	v_mfma_f32_16x16x32_bf16 v[36:39], v[148:151], v[194:197], v[36:39]
	v_mfma_f32_16x16x32_bf16 v[32:35], v[156:159], v[194:197], v[32:35]
	v_mfma_f32_16x16x32_bf16 v[20:23], v[148:151], v[202:205], v[20:23]
	v_mfma_f32_16x16x32_bf16 v[16:19], v[156:159], v[202:205], v[16:19]
	v_mfma_f32_16x16x32_bf16 v[4:7], v[148:151], v[210:213], v[4:7]
	v_mfma_f32_16x16x32_bf16 v[0:3], v[156:159], v[210:213], v[0:3]
	s_barrier
; #define PG8_STAGE(bufoff, gbase, voff) do { _Pragma("unroll") for (int _i = 0; _i < 2; ++_i) \
;         __builtin_amdgcn_global_load_lds((const unsigned*)((const char*)(gbase) + (voff)[_i]), (PG8_LAS unsigned*)(lds + (bufoff) + ldsw + _i * 8192), 16, 0, 0); } while (0)
; #define PG8_LDA(dst, b, h) do { _Pragma("unroll") for (int m = 0; m < 4; ++m) _Pragma("unroll") for (int k = 0; k < 2; ++k) dst[m][k] = *(const PG8_LAS bf16x8*)(lds + PG8_SA(b, h) + aoff + m * 2048 + k * 1024); } while (0)
; #define PG8_LDB(dst, b, h) do { _Pragma("unroll") for (int n = 0; n < 2; ++n) _Pragma("unroll") for (int k = 0; k < 2; ++k) dst[n][k] = *(const PG8_LAS bf16x8*)(lds + PG8_SB(b, h) + boff + n * 2048 + k * 1024); } while (0)
; #define PG8_MMA(ai, bj, At, Bt) do { __builtin_amdgcn_s_setprio(1); _Pragma("unroll") for (int m = 0; m < 4; ++m) _Pragma("unroll") for (int n = 0; n < 2; ++n) _Pragma("unroll") for (int k = 0; k < 2; ++k) \
;         acc[ai][bj][m][n] = __builtin_amdgcn_mfma_f32_16x16x32_bf16(Bt[n][k], At[m][k], acc[ai][bj][m][n], 0, 0, 0); __builtin_amdgcn_s_setprio(0); } while (0)
; #define PG8_WAIT_V(n) asm volatile("s_waitcnt vmcnt(" #n ")" ::: "memory")
; #define PG8_WAIT_L(n) asm volatile("s_waitcnt lgkmcnt(" #n ")" ::: "memory")
; #define PG8_BAR __builtin_amdgcn_s_barrier()
; #define PG8_SCHED __builtin_amdgcn_sched_barrier(0)
; template <class Epi, class Sched, bool ALIGN_EPI = false, bool SP2 = false>
; __device__ __forceinline__ void gemm_phase(PG8_LAS unsigned char* lds, const Gemm g, const Sched& S, const Epi& E) {
;     ...
;         for (int t = 0; t < nt; t += 2) {
;     ...
;             PG8_LDB(B0, 1, 0); PG8_LDB(B1, 1, 1); PG8_SCHED; PG8_LDA(At, 1, 0); PG8_STAGE(PG8_SA(0, 1), a2 + hstepA, voffA);
;             PG8_WAIT_V(8); PG8_WAIT_L(0); PG8_BAR; PG8_MMA(0, 0, At, B0); PG8_MMA(0, 1, At, B1); PG8_BAR; PG8_SCHED;
;             PG8_LDA(At, 1, 1); PG8_STAGE(PG8_SB(1, 0), b3, voffB); PG8_STAGE(PG8_SB(1, 1), b3 + hstep, voffB); PG8_STAGE(PG8_SA(1, 0), a3, voffA);
;             PG8_WAIT_V(8); PG8_WAIT_L(0); PG8_BAR; PG8_MMA(1, 0, At, B0); PG8_MMA(1, 1, At, B1); PG8_BAR; PG8_SCHED;
	s_add_i32 s89, 0, 0x18000
	s_add_i32 s90, 0, 0x1c000
	v_add_u32_e32 v140, s89, v234
	v_add_u32_e32 v156, s90, v234
	ds_read_b128 v[128:131], v140
	ds_read_b128 v[132:135], v140 offset:1024
	ds_read_b128 v[136:139], v140 offset:2048
	ds_read_b128 v[140:143], v140 offset:3072
	ds_read_b128 v[144:147], v156
	ds_read_b128 v[148:151], v156 offset:1024
	ds_read_b128 v[152:155], v156 offset:2048
	ds_read_b128 v[156:159], v156 offset:3072
	s_add_u32 s8, s60, 0x100000
	s_addc_u32 s9, s61, 0
	s_mov_b32 m0, s65
	ds_read_b128 v[160:163], v238 offset:32768
	ds_read_b128 v[186:189], v238 offset:33792
	ds_read_b128 v[190:193], v238 offset:34816
	ds_read_b128 v[194:197], v238 offset:35840
	ds_read_b128 v[198:201], v238 offset:36864
	ds_read_b128 v[202:205], v238 offset:37888
	ds_read_b128 v[206:209], v238 offset:38912
	ds_read_b128 v[210:213], v238 offset:39936
	global_load_lds_dwordx4 v166, s[8:9]
	s_mov_b32 m0, s66
	s_nop 0
	global_load_lds_dwordx4 v170, s[8:9]
	s_waitcnt vmcnt(8)
	s_waitcnt lgkmcnt(0)
	s_barrier
	v_mfma_f32_16x16x32_bf16 v[124:127], v[128:131], v[160:163], v[124:127]
	v_mfma_f32_16x16x32_bf16 v[120:123], v[136:139], v[160:163], v[120:123]
	v_mfma_f32_16x16x32_bf16 v[108:111], v[128:131], v[190:193], v[108:111]
	v_mfma_f32_16x16x32_bf16 v[104:107], v[136:139], v[190:193], v[104:107]
	v_mfma_f32_16x16x32_bf16 v[92:95], v[128:131], v[198:201], v[92:95]
	v_mfma_f32_16x16x32_bf16 v[88:91], v[136:139], v[198:201], v[88:91]
	v_mfma_f32_16x16x32_bf16 v[76:79], v[128:131], v[206:209], v[76:79]
	v_mfma_f32_16x16x32_bf16 v[72:75], v[136:139], v[206:209], v[72:75]
	v_mfma_f32_16x16x32_bf16 v[124:127], v[132:135], v[186:189], v[124:127]
	v_mfma_f32_16x16x32_bf16 v[120:123], v[140:143], v[186:189], v[120:123]
	v_mfma_f32_16x16x32_bf16 v[108:111], v[132:135], v[194:197], v[108:111]
	v_mfma_f32_16x16x32_bf16 v[104:107], v[140:143], v[194:197], v[104:107]
	v_mfma_f32_16x16x32_bf16 v[92:95], v[132:135], v[202:205], v[92:95]
	v_mfma_f32_16x16x32_bf16 v[88:91], v[140:143], v[202:205], v[88:91]
	v_mfma_f32_16x16x32_bf16 v[76:79], v[132:135], v[210:213], v[76:79]
	v_mfma_f32_16x16x32_bf16 v[72:75], v[140:143], v[210:213], v[72:75]
	v_mfma_f32_16x16x32_bf16 v[116:119], v[144:147], v[160:163], v[116:119]
	v_mfma_f32_16x16x32_bf16 v[112:115], v[152:155], v[160:163], v[112:115]
	v_mfma_f32_16x16x32_bf16 v[100:103], v[144:147], v[190:193], v[100:103]
	v_mfma_f32_16x16x32_bf16 v[96:99], v[152:155], v[190:193], v[96:99]
	v_mfma_f32_16x16x32_bf16 v[84:87], v[144:147], v[198:201], v[84:87]
	v_mfma_f32_16x16x32_bf16 v[80:83], v[152:155], v[198:201], v[80:83]
	v_mfma_f32_16x16x32_bf16 v[68:71], v[144:147], v[206:209], v[68:71]
	v_mfma_f32_16x16x32_bf16 v[64:67], v[152:155], v[206:209], v[64:67]
	v_mfma_f32_16x16x32_bf16 v[116:119], v[148:151], v[186:189], v[116:119]
	v_mfma_f32_16x16x32_bf16 v[112:115], v[156:159], v[186:189], v[112:115]
	v_mfma_f32_16x16x32_bf16 v[100:103], v[148:151], v[194:197], v[100:103]
	v_mfma_f32_16x16x32_bf16 v[96:99], v[156:159], v[194:197], v[96:99]
	v_mfma_f32_16x16x32_bf16 v[84:87], v[148:151], v[202:205], v[84:87]
	v_mfma_f32_16x16x32_bf16 v[80:83], v[156:159], v[202:205], v[80:83]
	v_mfma_f32_16x16x32_bf16 v[68:71], v[148:151], v[210:213], v[68:71]
	v_mfma_f32_16x16x32_bf16 v[64:67], v[156:159], v[210:213], v[64:67]
	s_barrier
	s_add_i32 s8, s89, s63
	s_mov_b32 m0, s8
	ds_read_b128 v[160:163], v238 offset:49152
	ds_read_b128 v[186:189], v238 offset:50176
	ds_read_b128 v[190:193], v238 offset:51200
	ds_read_b128 v[194:197], v238 offset:52224
	ds_read_b128 v[198:201], v238 offset:53248
	ds_read_b128 v[202:205], v238 offset:54272
	ds_read_b128 v[206:209], v238 offset:55296
	ds_read_b128 v[210:213], v238 offset:56320
	global_load_lds_dwordx4 v168, s[98:99]
	s_add_i32 m0, s8, 0x2000
	s_add_u32 s8, s58, 0x100080
	s_addc_u32 s9, s59, 0
	s_add_i32 s58, s90, s63
	global_load_lds_dwordx4 v172, s[98:99]
	s_mov_b32 m0, s58
	s_nop 0
	global_load_lds_dwordx4 v168, s[8:9]
	s_add_i32 m0, s58, 0x2000
	s_nop 0
	global_load_lds_dwordx4 v172, s[8:9]
	s_mov_b32 m0, s70
	s_nop 0
	global_load_lds_dwordx4 v166, s[100:101]
	s_mov_b32 m0, s71
	s_nop 0
	global_load_lds_dwordx4 v170, s[100:101]
	s_waitcnt vmcnt(8)
	s_waitcnt lgkmcnt(0)
	s_barrier
	v_mfma_f32_16x16x32_bf16 v[60:63], v[128:131], v[160:163], v[60:63]
	v_mfma_f32_16x16x32_bf16 v[56:59], v[136:139], v[160:163], v[56:59]
	v_mfma_f32_16x16x32_bf16 v[44:47], v[128:131], v[190:193], v[44:47]
	v_mfma_f32_16x16x32_bf16 v[40:43], v[136:139], v[190:193], v[40:43]
	v_mfma_f32_16x16x32_bf16 v[28:31], v[128:131], v[198:201], v[28:31]
	v_mfma_f32_16x16x32_bf16 v[24:27], v[136:139], v[198:201], v[24:27]
	v_mfma_f32_16x16x32_bf16 v[12:15], v[128:131], v[206:209], v[12:15]
	v_mfma_f32_16x16x32_bf16 v[8:11], v[136:139], v[206:209], v[8:11]
	v_mfma_f32_16x16x32_bf16 v[60:63], v[132:135], v[186:189], v[60:63]
	v_mfma_f32_16x16x32_bf16 v[56:59], v[140:143], v[186:189], v[56:59]
	v_mfma_f32_16x16x32_bf16 v[44:47], v[132:135], v[194:197], v[44:47]
	v_mfma_f32_16x16x32_bf16 v[40:43], v[140:143], v[194:197], v[40:43]
	v_mfma_f32_16x16x32_bf16 v[28:31], v[132:135], v[202:205], v[28:31]
	v_mfma_f32_16x16x32_bf16 v[24:27], v[140:143], v[202:205], v[24:27]
	v_mfma_f32_16x16x32_bf16 v[12:15], v[132:135], v[210:213], v[12:15]
	v_mfma_f32_16x16x32_bf16 v[8:11], v[140:143], v[210:213], v[8:11]
	v_mfma_f32_16x16x32_bf16 v[52:55], v[144:147], v[160:163], v[52:55]
	v_mfma_f32_16x16x32_bf16 v[48:51], v[152:155], v[160:163], v[48:51]
	v_mfma_f32_16x16x32_bf16 v[36:39], v[144:147], v[190:193], v[36:39]
	v_mfma_f32_16x16x32_bf16 v[32:35], v[152:155], v[190:193], v[32:35]
	v_mfma_f32_16x16x32_bf16 v[20:23], v[144:147], v[198:201], v[20:23]
	v_mfma_f32_16x16x32_bf16 v[16:19], v[152:155], v[198:201], v[16:19]
	v_mfma_f32_16x16x32_bf16 v[4:7], v[144:147], v[206:209], v[4:7]
	v_mfma_f32_16x16x32_bf16 v[0:3], v[152:155], v[206:209], v[0:3]
	v_mfma_f32_16x16x32_bf16 v[52:55], v[148:151], v[186:189], v[52:55]
	v_mfma_f32_16x16x32_bf16 v[48:51], v[156:159], v[186:189], v[48:51]
	v_mfma_f32_16x16x32_bf16 v[36:39], v[148:151], v[194:197], v[36:39]
	v_mfma_f32_16x16x32_bf16 v[32:35], v[156:159], v[194:197], v[32:35]
	v_mfma_f32_16x16x32_bf16 v[20:23], v[148:151], v[202:205], v[20:23]
	v_mfma_f32_16x16x32_bf16 v[16:19], v[156:159], v[202:205], v[16:19]
	v_mfma_f32_16x16x32_bf16 v[4:7], v[148:151], v[210:213], v[4:7]
	v_mfma_f32_16x16x32_bf16 v[0:3], v[156:159], v[210:213], v[0:3]
	s_barrier
	s_add_i32 s88, s88, 2
	s_add_u32 s86, s86, 0x100
	s_addc_u32 s87, s87, 0
	s_cmp_gt_u32 s88, 61
	s_mov_b64 s[8:9], s[10:11]
	s_cbranch_scc0 .LBB0_2882
	s_setprio 0
	s_and_b64 vcc, exec, s[18:19]
	s_cbranch_vccz .LBB0_2885
	s_barrier

; #define PG8_STAGE(bufoff, gbase, voff) do { _Pragma("unroll") for (int _i = 0; _i < 2; ++_i) \
;         __builtin_amdgcn_global_load_lds((const unsigned*)((const char*)(gbase) + (voff)[_i]), (PG8_LAS unsigned*)(lds + (bufoff) + ldsw + _i * 8192), 16, 0, 0); } while (0)
; #define PG8_LDA(dst, b, h) do { _Pragma("unroll") for (int m = 0; m < 4; ++m) _Pragma("unroll") for (int k = 0; k < 2; ++k) dst[m][k] = *(const PG8_LAS bf16x8*)(lds + PG8_SA(b, h) + aoff + m * 2048 + k * 1024); } while (0)
; #define PG8_LDB(dst, b, h) do { _Pragma("unroll") for (int n = 0; n < 2; ++n) _Pragma("unroll") for (int k = 0; k < 2; ++k) dst[n][k] = *(const PG8_LAS bf16x8*)(lds + PG8_SB(b, h) + boff + n * 2048 + k * 1024); } while (0)
; #define PG8_MMA(ai, bj, At, Bt) do { __builtin_amdgcn_s_setprio(1); _Pragma("unroll") for (int m = 0; m < 4; ++m) _Pragma("unroll") for (int n = 0; n < 2; ++n) _Pragma("unroll") for (int k = 0; k < 2; ++k) \
;         acc[ai][bj][m][n] = __builtin_amdgcn_mfma_f32_16x16x32_bf16(Bt[n][k], At[m][k], acc[ai][bj][m][n], 0, 0, 0); __builtin_amdgcn_s_setprio(0); } while (0)
; #define PG8_WAIT_V(n) asm volatile("s_waitcnt vmcnt(" #n ")" ::: "memory")
; template <class Epi, class Sched, bool ALIGN_EPI = false, bool SP2 = false>
; __device__ __forceinline__ void gemm_phase(PG8_LAS unsigned char* lds, const Gemm g, const Sched& S, const Epi& E) {
;     ...
;         for (int t = 0; t < nt; t += 2) {
;             const bool last = (t == nt - 2);
;             const char* a1 = cA + (size_t)(t + 1) * kstepA;
;             const char* a2 = last ? nA : cA + (size_t)(t + 2) * kstepA; const char* b2 = last ? nB : cB + (size_t)(t + 2) * kstep;
;             const char* a3 = a2 + kstepA; const char* b3 = b2 + kstep;
;             if (last && has_next) S.a_ready(nxt);
;             if constexpr (SP2) {
;             PG8_LDB(B0, 0, 0); PG8_LDB(B1, 0, 1); PG8_SCHED; PG8_LDA(At, 0, 0); PG8_STAGE(PG8_SA(1, 1), a1 + hstepA, voffA);
;             PG8_WAIT_V(8); PG8_WAIT_L(0); PG8_BAR; PG8_MMA(0, 0, At, B0); PG8_MMA(0, 1, At, B1); PG8_BAR; PG8_SCHED;
;     ...
; #pragma unroll
;         for (int a = 0; a < 2; ++a)
; #pragma unroll
;             for (int b = 0; b < 2; ++b)
; #pragma unroll
;                 for (int m = 0; m < 4; ++m)
; #pragma unroll
;                     for (int n = 0; n < 2; ++n) acc[a][b][m][n] = (f32x4){0.f, 0.f, 0.f, 0.f};
;         cur = nxt; cA = nA; cB = nB; ++ui;
.LBB0_3086:
	s_add_u32 s63, s34, 0x100
	s_addc_u32 s64, s35, 0
	s_add_u32 s34, s36, 0xc000
	v_mov_b32_e32 v0, 0
	s_addc_u32 s35, s37, 0
	s_mov_b32 s65, -2
	s_waitcnt lgkmcnt(0)
	v_mov_b32_e32 v1, v0
	v_mov_b32_e32 v2, v0
	v_mov_b32_e32 v3, v0
	v_mov_b32_e32 v4, v0
	v_mov_b32_e32 v5, v0
	v_mov_b32_e32 v6, v0
	v_mov_b32_e32 v7, v0
	v_mov_b32_e32 v16, v0
	v_mov_b32_e32 v17, v0
	v_mov_b32_e32 v18, v0
	v_mov_b32_e32 v19, v0
	v_mov_b32_e32 v20, v0
	v_mov_b32_e32 v21, v0
	v_mov_b32_e32 v22, v0
	v_mov_b32_e32 v23, v0
	v_mov_b32_e32 v32, v0
	v_mov_b32_e32 v33, v0
	v_mov_b32_e32 v34, v0
	v_mov_b32_e32 v35, v0
	s_waitcnt vmcnt(0)
	v_mov_b32_e32 v36, v0
	v_mov_b32_e32 v37, v0
	v_mov_b32_e32 v38, v0
	v_mov_b32_e32 v39, v0
	v_mov_b32_e32 v48, v0
	v_mov_b32_e32 v49, v0
	v_mov_b32_e32 v50, v0
	v_mov_b32_e32 v51, v0
	v_mov_b32_e32 v52, v0
	v_mov_b32_e32 v53, v0
	v_mov_b32_e32 v54, v0
	v_mov_b32_e32 v55, v0
	v_mov_b32_e32 v8, v0
	v_mov_b32_e32 v9, v0
	v_mov_b32_e32 v10, v0
	v_mov_b32_e32 v11, v0
	v_mov_b32_e32 v12, v0
	v_mov_b32_e32 v13, v0
	v_mov_b32_e32 v14, v0
	v_mov_b32_e32 v15, v0
	v_mov_b32_e32 v24, v0
	v_mov_b32_e32 v25, v0
	v_mov_b32_e32 v26, v0
	v_mov_b32_e32 v27, v0
	v_mov_b32_e32 v28, v0
	v_mov_b32_e32 v29, v0
	v_mov_b32_e32 v30, v0
	v_mov_b32_e32 v31, v0
	v_mov_b32_e32 v40, v0
	v_mov_b32_e32 v41, v0
	v_mov_b32_e32 v42, v0
	v_mov_b32_e32 v43, v0
	v_mov_b32_e32 v44, v0
	v_mov_b32_e32 v45, v0
	v_mov_b32_e32 v46, v0
	v_mov_b32_e32 v47, v0
	v_mov_b32_e32 v56, v0
	v_mov_b32_e32 v57, v0
	v_mov_b32_e32 v58, v0
	v_mov_b32_e32 v59, v0
	v_mov_b32_e32 v60, v0
	v_mov_b32_e32 v61, v0
	v_mov_b32_e32 v62, v0
	v_mov_b32_e32 v63, v0
	v_mov_b32_e32 v64, v0
	v_mov_b32_e32 v65, v0
	v_mov_b32_e32 v66, v0
	v_mov_b32_e32 v67, v0
	v_mov_b32_e32 v68, v0
	v_mov_b32_e32 v69, v0
	v_mov_b32_e32 v70, v0
	v_mov_b32_e32 v71, v0
	v_mov_b32_e32 v80, v0
	v_mov_b32_e32 v81, v0
	v_mov_b32_e32 v82, v0
	v_mov_b32_e32 v83, v0
	v_mov_b32_e32 v84, v0
	v_mov_b32_e32 v85, v0
	v_mov_b32_e32 v86, v0
	v_mov_b32_e32 v87, v0
	v_mov_b32_e32 v96, v0
	v_mov_b32_e32 v97, v0
	v_mov_b32_e32 v98, v0
	v_mov_b32_e32 v99, v0
	v_mov_b32_e32 v100, v0
	v_mov_b32_e32 v101, v0
	v_mov_b32_e32 v102, v0
	v_mov_b32_e32 v103, v0
	v_mov_b32_e32 v112, v0
	v_mov_b32_e32 v113, v0
	v_mov_b32_e32 v114, v0
	v_mov_b32_e32 v115, v0
	v_mov_b32_e32 v116, v0
	v_mov_b32_e32 v117, v0
	v_mov_b32_e32 v118, v0
	v_mov_b32_e32 v119, v0
	v_mov_b32_e32 v72, v0
	v_mov_b32_e32 v73, v0
	v_mov_b32_e32 v74, v0
	v_mov_b32_e32 v75, v0
	v_mov_b32_e32 v76, v0
	v_mov_b32_e32 v77, v0
	v_mov_b32_e32 v78, v0
	v_mov_b32_e32 v79, v0
	v_mov_b32_e32 v88, v0
	v_mov_b32_e32 v89, v0
	v_mov_b32_e32 v90, v0
	v_mov_b32_e32 v91, v0
	v_mov_b32_e32 v92, v0
	v_mov_b32_e32 v93, v0
	v_mov_b32_e32 v94, v0
	v_mov_b32_e32 v95, v0
	v_mov_b32_e32 v104, v0
	v_mov_b32_e32 v105, v0
	v_mov_b32_e32 v106, v0
	v_mov_b32_e32 v107, v0
	v_mov_b32_e32 v108, v0
	v_mov_b32_e32 v109, v0
	v_mov_b32_e32 v110, v0
	v_mov_b32_e32 v111, v0
	v_mov_b32_e32 v120, v0
	v_mov_b32_e32 v121, v0
	v_mov_b32_e32 v122, v0
	v_mov_b32_e32 v123, v0
	v_mov_b32_e32 v124, v0
	v_mov_b32_e32 v125, v0
	v_mov_b32_e32 v126, v0
	v_mov_b32_e32 v127, v0
	s_cmp_ge_u32 s33, 0x1000
	s_cbranch_scc1 .Lsprio_2
	s_setprio 1
.Lsprio_2:
.LBB0_3087:
	ds_read_b128 v[144:147], v153
	ds_read_b128 v[158:161], v153 offset:1024
	ds_read_b128 v[162:165], v153 offset:2048
	ds_read_b128 v[166:169], v153 offset:3072
	ds_read_b128 v[170:173], v154
	ds_read_b128 v[174:177], v154 offset:1024
	ds_read_b128 v[178:181], v154 offset:2048
	ds_read_b128 v[182:185], v154 offset:3072
	s_add_u32 s36, s34, 0x4000
	s_addc_u32 s37, s35, 0
	s_cmpk_eq_i32 s65, 0xa8
	s_cselect_b32 s42, s6, s36
	s_cselect_b32 s43, s7, s37
	s_cselect_b32 s40, s30, s63
	s_cselect_b32 s41, s31, s64
	s_add_u32 s36, s42, 0x8000
	s_addc_u32 s37, s43, 0
	s_add_i32 m0, s44, 0xc000
	ds_read_b128 v[186:189], v155
	ds_read_b128 v[190:193], v155 offset:1024
	ds_read_b128 v[194:197], v155 offset:2048
	ds_read_b128 v[198:201], v155 offset:3072
	ds_read_b128 v[202:205], v155 offset:4096
	ds_read_b128 v[206:209], v155 offset:5120
	ds_read_b128 v[210:213], v155 offset:6144
	ds_read_b128 v[214:217], v155 offset:7168
	global_load_lds_dwordx4 v136, s[34:35]
	s_add_i32 m0, s44, 0xe000
	s_nop 0
	global_load_lds_dwordx4 v138, s[34:35]
	s_waitcnt vmcnt(8)
	s_waitcnt lgkmcnt(0)
	s_barrier
	v_mfma_f32_16x16x32_bf16 v[124:127], v[144:147], v[186:189], v[124:127]
	v_mfma_f32_16x16x32_bf16 v[120:123], v[162:165], v[186:189], v[120:123]
	v_mfma_f32_16x16x32_bf16 v[108:111], v[144:147], v[194:197], v[108:111]
	v_mfma_f32_16x16x32_bf16 v[104:107], v[162:165], v[194:197], v[104:107]
	v_mfma_f32_16x16x32_bf16 v[92:95], v[144:147], v[202:205], v[92:95]
	v_mfma_f32_16x16x32_bf16 v[88:91], v[162:165], v[202:205], v[88:91]
	v_mfma_f32_16x16x32_bf16 v[76:79], v[144:147], v[210:213], v[76:79]
	v_mfma_f32_16x16x32_bf16 v[72:75], v[162:165], v[210:213], v[72:75]
	v_mfma_f32_16x16x32_bf16 v[124:127], v[158:161], v[190:193], v[124:127]
	v_mfma_f32_16x16x32_bf16 v[120:123], v[166:169], v[190:193], v[120:123]
	v_mfma_f32_16x16x32_bf16 v[108:111], v[158:161], v[198:201], v[108:111]
	v_mfma_f32_16x16x32_bf16 v[104:107], v[166:169], v[198:201], v[104:107]
	v_mfma_f32_16x16x32_bf16 v[92:95], v[158:161], v[206:209], v[92:95]
	v_mfma_f32_16x16x32_bf16 v[88:91], v[166:169], v[206:209], v[88:91]
	v_mfma_f32_16x16x32_bf16 v[76:79], v[158:161], v[214:217], v[76:79]
	v_mfma_f32_16x16x32_bf16 v[72:75], v[166:169], v[214:217], v[72:75]
	v_mfma_f32_16x16x32_bf16 v[116:119], v[170:173], v[186:189], v[116:119]
	v_mfma_f32_16x16x32_bf16 v[112:115], v[178:181], v[186:189], v[112:115]
	v_mfma_f32_16x16x32_bf16 v[100:103], v[170:173], v[194:197], v[100:103]
	v_mfma_f32_16x16x32_bf16 v[96:99], v[178:181], v[194:197], v[96:99]
	v_mfma_f32_16x16x32_bf16 v[84:87], v[170:173], v[202:205], v[84:87]
	v_mfma_f32_16x16x32_bf16 v[80:83], v[178:181], v[202:205], v[80:83]
	v_mfma_f32_16x16x32_bf16 v[68:71], v[170:173], v[210:213], v[68:71]
	v_mfma_f32_16x16x32_bf16 v[64:67], v[178:181], v[210:213], v[64:67]
	v_mfma_f32_16x16x32_bf16 v[116:119], v[174:177], v[190:193], v[116:119]
	v_mfma_f32_16x16x32_bf16 v[112:115], v[182:185], v[190:193], v[112:115]
	v_mfma_f32_16x16x32_bf16 v[100:103], v[174:177], v[198:201], v[100:103]
	v_mfma_f32_16x16x32_bf16 v[96:99], v[182:185], v[198:201], v[96:99]
	v_mfma_f32_16x16x32_bf16 v[84:87], v[174:177], v[206:209], v[84:87]
	v_mfma_f32_16x16x32_bf16 v[80:83], v[182:185], v[206:209], v[80:83]
	v_mfma_f32_16x16x32_bf16 v[68:71], v[174:177], v[214:217], v[68:71]
	v_mfma_f32_16x16x32_bf16 v[64:67], v[182:185], v[214:217], v[64:67]
	s_barrier
; #define PG8_STAGE(bufoff, gbase, voff) do { _Pragma("unroll") for (int _i = 0; _i < 2; ++_i) \
;         __builtin_amdgcn_global_load_lds((const unsigned*)((const char*)(gbase) + (voff)[_i]), (PG8_LAS unsigned*)(lds + (bufoff) + ldsw + _i * 8192), 16, 0, 0); } while (0)
; #define PG8_LDA(dst, b, h) do { _Pragma("unroll") for (int m = 0; m < 4; ++m) _Pragma("unroll") for (int k = 0; k < 2; ++k) dst[m][k] = *(const PG8_LAS bf16x8*)(lds + PG8_SA(b, h) + aoff + m * 2048 + k * 1024); } while (0)
; #define PG8_LDB(dst, b, h) do { _Pragma("unroll") for (int n = 0; n < 2; ++n) _Pragma("unroll") for (int k = 0; k < 2; ++k) dst[n][k] = *(const PG8_LAS bf16x8*)(lds + PG8_SB(b, h) + boff + n * 2048 + k * 1024); } while (0)
; #define PG8_MMA(ai, bj, At, Bt) do { __builtin_amdgcn_s_setprio(1); _Pragma("unroll") for (int m = 0; m < 4; ++m) _Pragma("unroll") for (int n = 0; n < 2; ++n) _Pragma("unroll") for (int k = 0; k < 2; ++k) \
;         acc[ai][bj][m][n] = __builtin_amdgcn_mfma_f32_16x16x32_bf16(Bt[n][k], At[m][k], acc[ai][bj][m][n], 0, 0, 0); __builtin_amdgcn_s_setprio(0); } while (0)
; #define PG8_WAIT_V(n) asm volatile("s_waitcnt vmcnt(" #n ")" ::: "memory")
; #define PG8_WAIT_L(n) asm volatile("s_waitcnt lgkmcnt(" #n ")" ::: "memory")
; #define PG8_BAR __builtin_amdgcn_s_barrier()
; #define PG8_SCHED __builtin_amdgcn_sched_barrier(0)
; template <class Epi, class Sched, bool ALIGN_EPI = false, bool SP2 = false>
; __device__ __forceinline__ void gemm_phase(PG8_LAS unsigned char* lds, const Gemm g, const Sched& S, const Epi& E) {
;     ...
;             PG8_LDA(At, 0, 1); PG8_STAGE(PG8_SB(0, 0), b2, voffB); PG8_STAGE(PG8_SB(0, 1), b2 + hstep, voffB); PG8_STAGE(PG8_SA(0, 0), a2, voffA);
;             PG8_WAIT_V(8); PG8_WAIT_L(0); PG8_BAR; PG8_MMA(1, 0, At, B0); PG8_MMA(1, 1, At, B1); PG8_BAR; PG8_SCHED;
;             PG8_LDB(B0, 1, 0); PG8_LDB(B1, 1, 1); PG8_SCHED; PG8_LDA(At, 1, 0); PG8_STAGE(PG8_SA(0, 1), a2 + hstepA, voffA);
;             PG8_WAIT_V(8); PG8_WAIT_L(0); PG8_BAR; PG8_MMA(0, 0, At, B0); PG8_MMA(0, 1, At, B1); PG8_BAR; PG8_SCHED;
	s_add_u32 s98, s40, s16
	s_addc_u32 s99, s41, s17
	s_add_i32 s66, s53, s33
	s_mov_b32 m0, s66
	ds_read_b128 v[186:189], v155 offset:16384
	ds_read_b128 v[190:193], v155 offset:17408
	ds_read_b128 v[194:197], v155 offset:18432
	ds_read_b128 v[198:201], v155 offset:19456
	ds_read_b128 v[202:205], v155 offset:20480
	ds_read_b128 v[206:209], v155 offset:21504
	ds_read_b128 v[210:213], v155 offset:22528
	ds_read_b128 v[214:217], v155 offset:23552
	global_load_lds_dwordx4 v130, s[40:41]
	s_add_i32 m0, s66, 0x2000
	s_add_u32 s66, s40, 0x2b0000
	s_addc_u32 s67, s41, 0
	s_add_i32 s68, s54, s33
	global_load_lds_dwordx4 v134, s[40:41]
	s_mov_b32 m0, s68
	s_nop 0
	global_load_lds_dwordx4 v130, s[66:67]
	s_add_i32 m0, s68, 0x2000
	s_nop 0
	global_load_lds_dwordx4 v134, s[66:67]
	s_mov_b32 m0, s44
	s_nop 0
	global_load_lds_dwordx4 v128, s[42:43]
	s_mov_b32 m0, s45
	s_nop 0
	global_load_lds_dwordx4 v132, s[42:43]
	s_waitcnt vmcnt(8)
	s_waitcnt lgkmcnt(0)
	s_barrier
	v_mfma_f32_16x16x32_bf16 v[60:63], v[144:147], v[186:189], v[60:63]
	v_mfma_f32_16x16x32_bf16 v[56:59], v[162:165], v[186:189], v[56:59]
	v_mfma_f32_16x16x32_bf16 v[44:47], v[144:147], v[194:197], v[44:47]
	v_mfma_f32_16x16x32_bf16 v[40:43], v[162:165], v[194:197], v[40:43]
	v_mfma_f32_16x16x32_bf16 v[28:31], v[144:147], v[202:205], v[28:31]
	v_mfma_f32_16x16x32_bf16 v[24:27], v[162:165], v[202:205], v[24:27]
	v_mfma_f32_16x16x32_bf16 v[12:15], v[144:147], v[210:213], v[12:15]
	v_mfma_f32_16x16x32_bf16 v[8:11], v[162:165], v[210:213], v[8:11]
	v_mfma_f32_16x16x32_bf16 v[60:63], v[158:161], v[190:193], v[60:63]
	v_mfma_f32_16x16x32_bf16 v[56:59], v[166:169], v[190:193], v[56:59]
	v_mfma_f32_16x16x32_bf16 v[44:47], v[158:161], v[198:201], v[44:47]
	v_mfma_f32_16x16x32_bf16 v[40:43], v[166:169], v[198:201], v[40:43]
	v_mfma_f32_16x16x32_bf16 v[28:31], v[158:161], v[206:209], v[28:31]
	v_mfma_f32_16x16x32_bf16 v[24:27], v[166:169], v[206:209], v[24:27]
	v_mfma_f32_16x16x32_bf16 v[12:15], v[158:161], v[214:217], v[12:15]
	v_mfma_f32_16x16x32_bf16 v[8:11], v[166:169], v[214:217], v[8:11]
	v_mfma_f32_16x16x32_bf16 v[52:55], v[170:173], v[186:189], v[52:55]
	v_mfma_f32_16x16x32_bf16 v[48:51], v[178:181], v[186:189], v[48:51]
	v_mfma_f32_16x16x32_bf16 v[36:39], v[170:173], v[194:197], v[36:39]
	v_mfma_f32_16x16x32_bf16 v[32:35], v[178:181], v[194:197], v[32:35]
	v_mfma_f32_16x16x32_bf16 v[20:23], v[170:173], v[202:205], v[20:23]
	v_mfma_f32_16x16x32_bf16 v[16:19], v[178:181], v[202:205], v[16:19]
	v_mfma_f32_16x16x32_bf16 v[4:7], v[170:173], v[210:213], v[4:7]
	v_mfma_f32_16x16x32_bf16 v[0:3], v[178:181], v[210:213], v[0:3]
	v_mfma_f32_16x16x32_bf16 v[52:55], v[174:177], v[190:193], v[52:55]
	v_mfma_f32_16x16x32_bf16 v[48:51], v[182:185], v[190:193], v[48:51]
	v_mfma_f32_16x16x32_bf16 v[36:39], v[174:177], v[198:201], v[36:39]
	v_mfma_f32_16x16x32_bf16 v[32:35], v[182:185], v[198:201], v[32:35]
	v_mfma_f32_16x16x32_bf16 v[20:23], v[174:177], v[206:209], v[20:23]
	v_mfma_f32_16x16x32_bf16 v[16:19], v[182:185], v[206:209], v[16:19]
	v_mfma_f32_16x16x32_bf16 v[4:7], v[174:177], v[214:217], v[4:7]
	v_mfma_f32_16x16x32_bf16 v[0:3], v[182:185], v[214:217], v[0:3]
	s_barrier
	s_add_i32 s66, 0, 0x18000
	v_add_u32_e32 v157, s66, v151
	s_add_i32 s67, 0, 0x1c000
	ds_read_b128 v[144:147], v157
	ds_read_b128 v[158:161], v157 offset:1024
	ds_read_b128 v[162:165], v157 offset:2048
	ds_read_b128 v[166:169], v157 offset:3072
	v_add_u32_e32 v157, s67, v151
	ds_read_b128 v[170:173], v157
	ds_read_b128 v[174:177], v157 offset:1024
	ds_read_b128 v[178:181], v157 offset:2048
	ds_read_b128 v[182:185], v157 offset:3072
	s_add_u32 s42, s42, 0x4000
	s_addc_u32 s43, s43, 0
	s_mov_b32 m0, s46
	ds_read_b128 v[186:189], v155 offset:32768
	ds_read_b128 v[190:193], v155 offset:33792
	ds_read_b128 v[194:197], v155 offset:34816
	ds_read_b128 v[198:201], v155 offset:35840
	ds_read_b128 v[202:205], v155 offset:36864
	ds_read_b128 v[206:209], v155 offset:37888
	ds_read_b128 v[210:213], v155 offset:38912
	ds_read_b128 v[214:217], v155 offset:39936
	global_load_lds_dwordx4 v128, s[42:43]
	s_mov_b32 m0, s47
	s_nop 0
	global_load_lds_dwordx4 v132, s[42:43]
	s_waitcnt vmcnt(8)
	s_waitcnt lgkmcnt(0)
	s_barrier
; #define PG8_STAGE(bufoff, gbase, voff) do { _Pragma("unroll") for (int _i = 0; _i < 2; ++_i) \
;         __builtin_amdgcn_global_load_lds((const unsigned*)((const char*)(gbase) + (voff)[_i]), (PG8_LAS unsigned*)(lds + (bufoff) + ldsw + _i * 8192), 16, 0, 0); } while (0)
; #define PG8_LDA(dst, b, h) do { _Pragma("unroll") for (int m = 0; m < 4; ++m) _Pragma("unroll") for (int k = 0; k < 2; ++k) dst[m][k] = *(const PG8_LAS bf16x8*)(lds + PG8_SA(b, h) + aoff + m * 2048 + k * 1024); } while (0)
; #define PG8_MMA(ai, bj, At, Bt) do { __builtin_amdgcn_s_setprio(1); _Pragma("unroll") for (int m = 0; m < 4; ++m) _Pragma("unroll") for (int n = 0; n < 2; ++n) _Pragma("unroll") for (int k = 0; k < 2; ++k) \
;         acc[ai][bj][m][n] = __builtin_amdgcn_mfma_f32_16x16x32_bf16(Bt[n][k], At[m][k], acc[ai][bj][m][n], 0, 0, 0); __builtin_amdgcn_s_setprio(0); } while (0)
; #define PG8_WAIT_V(n) asm volatile("s_waitcnt vmcnt(" #n ")" ::: "memory")
; #define PG8_WAIT_L(n) asm volatile("s_waitcnt lgkmcnt(" #n ")" ::: "memory")
; #define PG8_BAR __builtin_amdgcn_s_barrier()
; #define PG8_SCHED __builtin_amdgcn_sched_barrier(0)
; template <class Epi, class Sched, bool ALIGN_EPI = false, bool SP2 = false>
; __device__ __forceinline__ void gemm_phase(PG8_LAS unsigned char* lds, const Gemm g, const Sched& S, const Epi& E) {
;     ...
;         for (int t = 0; t < nt; t += 2) {
;     ...
;             PG8_WAIT_V(8); PG8_WAIT_L(0); PG8_BAR; PG8_MMA(0, 0, At, B0); PG8_MMA(0, 1, At, B1); PG8_BAR; PG8_SCHED;
;             PG8_LDA(At, 1, 1); PG8_STAGE(PG8_SB(1, 0), b3, voffB); PG8_STAGE(PG8_SB(1, 1), b3 + hstep, voffB); PG8_STAGE(PG8_SA(1, 0), a3, voffA);
;             PG8_WAIT_V(8); PG8_WAIT_L(0); PG8_BAR; PG8_MMA(1, 0, At, B0); PG8_MMA(1, 1, At, B1); PG8_BAR; PG8_SCHED;
	v_mfma_f32_16x16x32_bf16 v[124:127], v[144:147], v[186:189], v[124:127]
	v_mfma_f32_16x16x32_bf16 v[120:123], v[162:165], v[186:189], v[120:123]
	v_mfma_f32_16x16x32_bf16 v[108:111], v[144:147], v[194:197], v[108:111]
	v_mfma_f32_16x16x32_bf16 v[104:107], v[162:165], v[194:197], v[104:107]
	v_mfma_f32_16x16x32_bf16 v[92:95], v[144:147], v[202:205], v[92:95]
	v_mfma_f32_16x16x32_bf16 v[88:91], v[162:165], v[202:205], v[88:91]
	v_mfma_f32_16x16x32_bf16 v[76:79], v[144:147], v[210:213], v[76:79]
	v_mfma_f32_16x16x32_bf16 v[72:75], v[162:165], v[210:213], v[72:75]
	v_mfma_f32_16x16x32_bf16 v[124:127], v[158:161], v[190:193], v[124:127]
	v_mfma_f32_16x16x32_bf16 v[120:123], v[166:169], v[190:193], v[120:123]
	v_mfma_f32_16x16x32_bf16 v[108:111], v[158:161], v[198:201], v[108:111]
	v_mfma_f32_16x16x32_bf16 v[104:107], v[166:169], v[198:201], v[104:107]
	v_mfma_f32_16x16x32_bf16 v[92:95], v[158:161], v[206:209], v[92:95]
	v_mfma_f32_16x16x32_bf16 v[88:91], v[166:169], v[206:209], v[88:91]
	v_mfma_f32_16x16x32_bf16 v[76:79], v[158:161], v[214:217], v[76:79]
	v_mfma_f32_16x16x32_bf16 v[72:75], v[166:169], v[214:217], v[72:75]
	v_mfma_f32_16x16x32_bf16 v[116:119], v[170:173], v[186:189], v[116:119]
	v_mfma_f32_16x16x32_bf16 v[112:115], v[178:181], v[186:189], v[112:115]
	v_mfma_f32_16x16x32_bf16 v[100:103], v[170:173], v[194:197], v[100:103]
	v_mfma_f32_16x16x32_bf16 v[96:99], v[178:181], v[194:197], v[96:99]
	v_mfma_f32_16x16x32_bf16 v[84:87], v[170:173], v[202:205], v[84:87]
	v_mfma_f32_16x16x32_bf16 v[80:83], v[178:181], v[202:205], v[80:83]
	v_mfma_f32_16x16x32_bf16 v[68:71], v[170:173], v[210:213], v[68:71]
	v_mfma_f32_16x16x32_bf16 v[64:67], v[178:181], v[210:213], v[64:67]
	v_mfma_f32_16x16x32_bf16 v[116:119], v[174:177], v[190:193], v[116:119]
	v_mfma_f32_16x16x32_bf16 v[112:115], v[182:185], v[190:193], v[112:115]
	v_mfma_f32_16x16x32_bf16 v[100:103], v[174:177], v[198:201], v[100:103]
	v_mfma_f32_16x16x32_bf16 v[96:99], v[182:185], v[198:201], v[96:99]
	v_mfma_f32_16x16x32_bf16 v[84:87], v[174:177], v[206:209], v[84:87]
	v_mfma_f32_16x16x32_bf16 v[80:83], v[182:185], v[206:209], v[80:83]
	v_mfma_f32_16x16x32_bf16 v[68:71], v[174:177], v[214:217], v[68:71]
	v_mfma_f32_16x16x32_bf16 v[64:67], v[182:185], v[214:217], v[64:67]
	s_barrier
	s_add_i32 s42, s66, s33
	s_mov_b32 m0, s42
	ds_read_b128 v[186:189], v155 offset:49152
	ds_read_b128 v[190:193], v155 offset:50176
	ds_read_b128 v[194:197], v155 offset:51200
	ds_read_b128 v[198:201], v155 offset:52224
	ds_read_b128 v[202:205], v155 offset:53248
	ds_read_b128 v[206:209], v155 offset:54272
	ds_read_b128 v[210:213], v155 offset:55296
	ds_read_b128 v[214:217], v155 offset:56320
	global_load_lds_dwordx4 v130, s[98:99]
	s_add_i32 m0, s42, 0x2000
	s_add_u32 s40, s40, 0x2b0080
	s_addc_u32 s41, s41, 0
	s_add_i32 s42, s67, s33
	global_load_lds_dwordx4 v134, s[98:99]
	s_mov_b32 m0, s42
	s_nop 0
	global_load_lds_dwordx4 v130, s[40:41]
	s_add_i32 m0, s42, 0x2000
	s_nop 0
	global_load_lds_dwordx4 v134, s[40:41]
	s_mov_b32 m0, s49
	s_nop 0
	global_load_lds_dwordx4 v128, s[36:37]
	s_mov_b32 m0, s50
	s_nop 0
	global_load_lds_dwordx4 v132, s[36:37]
	s_waitcnt vmcnt(8)
	s_waitcnt lgkmcnt(0)
	s_barrier
	v_mfma_f32_16x16x32_bf16 v[60:63], v[144:147], v[186:189], v[60:63]
	v_mfma_f32_16x16x32_bf16 v[56:59], v[162:165], v[186:189], v[56:59]
	v_mfma_f32_16x16x32_bf16 v[44:47], v[144:147], v[194:197], v[44:47]
	v_mfma_f32_16x16x32_bf16 v[40:43], v[162:165], v[194:197], v[40:43]
	v_mfma_f32_16x16x32_bf16 v[28:31], v[144:147], v[202:205], v[28:31]
	v_mfma_f32_16x16x32_bf16 v[24:27], v[162:165], v[202:205], v[24:27]
	v_mfma_f32_16x16x32_bf16 v[12:15], v[144:147], v[210:213], v[12:15]
	v_mfma_f32_16x16x32_bf16 v[8:11], v[162:165], v[210:213], v[8:11]
	v_mfma_f32_16x16x32_bf16 v[60:63], v[158:161], v[190:193], v[60:63]
	v_mfma_f32_16x16x32_bf16 v[56:59], v[166:169], v[190:193], v[56:59]
	v_mfma_f32_16x16x32_bf16 v[44:47], v[158:161], v[198:201], v[44:47]
	v_mfma_f32_16x16x32_bf16 v[40:43], v[166:169], v[198:201], v[40:43]
	v_mfma_f32_16x16x32_bf16 v[28:31], v[158:161], v[206:209], v[28:31]
	v_mfma_f32_16x16x32_bf16 v[24:27], v[166:169], v[206:209], v[24:27]
	v_mfma_f32_16x16x32_bf16 v[12:15], v[158:161], v[214:217], v[12:15]
	v_mfma_f32_16x16x32_bf16 v[8:11], v[166:169], v[214:217], v[8:11]
	v_mfma_f32_16x16x32_bf16 v[52:55], v[170:173], v[186:189], v[52:55]
	v_mfma_f32_16x16x32_bf16 v[48:51], v[178:181], v[186:189], v[48:51]
	v_mfma_f32_16x16x32_bf16 v[36:39], v[170:173], v[194:197], v[36:39]
	v_mfma_f32_16x16x32_bf16 v[32:35], v[178:181], v[194:197], v[32:35]
	v_mfma_f32_16x16x32_bf16 v[20:23], v[170:173], v[202:205], v[20:23]
	v_mfma_f32_16x16x32_bf16 v[16:19], v[178:181], v[202:205], v[16:19]
	v_mfma_f32_16x16x32_bf16 v[4:7], v[170:173], v[210:213], v[4:7]
	v_mfma_f32_16x16x32_bf16 v[0:3], v[178:181], v[210:213], v[0:3]
	v_mfma_f32_16x16x32_bf16 v[52:55], v[174:177], v[190:193], v[52:55]
	v_mfma_f32_16x16x32_bf16 v[48:51], v[182:185], v[190:193], v[48:51]
	v_mfma_f32_16x16x32_bf16 v[36:39], v[174:177], v[198:201], v[36:39]
	v_mfma_f32_16x16x32_bf16 v[32:35], v[182:185], v[198:201], v[32:35]
	v_mfma_f32_16x16x32_bf16 v[20:23], v[174:177], v[206:209], v[20:23]
	v_mfma_f32_16x16x32_bf16 v[16:19], v[182:185], v[206:209], v[16:19]
	v_mfma_f32_16x16x32_bf16 v[4:7], v[174:177], v[214:217], v[4:7]
	v_mfma_f32_16x16x32_bf16 v[0:3], v[182:185], v[214:217], v[0:3]
	s_barrier
	s_add_i32 s65, s65, 2
	s_add_u32 s63, s63, 0x100
	s_addc_u32 s64, s64, 0
	s_add_u32 s34, s34, 0x10000
	s_addc_u32 s35, s35, 0
	s_cmpk_gt_u32 s65, 0xa9
	s_cbranch_scc0 .LBB0_3087
	s_setprio 0
	s_and_b64 vcc, exec, s[18:19]
	s_cbranch_vccz .LBB0_3090
	s_barrier

; #define PG8_STAGE(bufoff, gbase, voff) do { _Pragma("unroll") for (int _i = 0; _i < 2; ++_i) \
;         __builtin_amdgcn_global_load_lds((const unsigned*)((const char*)(gbase) + (voff)[_i]), (PG8_LAS unsigned*)(lds + (bufoff) + ldsw + _i * 8192), 16, 0, 0); } while (0)
; #define PG8_LDA(dst, b, h) do { _Pragma("unroll") for (int m = 0; m < 4; ++m) _Pragma("unroll") for (int k = 0; k < 2; ++k) dst[m][k] = *(const PG8_LAS bf16x8*)(lds + PG8_SA(b, h) + aoff + m * 2048 + k * 1024); } while (0)
; #define PG8_LDB(dst, b, h) do { _Pragma("unroll") for (int n = 0; n < 2; ++n) _Pragma("unroll") for (int k = 0; k < 2; ++k) dst[n][k] = *(const PG8_LAS bf16x8*)(lds + PG8_SB(b, h) + boff + n * 2048 + k * 1024); } while (0)
; #define PG8_WAIT_V(n) asm volatile("s_waitcnt vmcnt(" #n ")" ::: "memory")
; #define PG8_WAIT_L(n) asm volatile("s_waitcnt lgkmcnt(" #n ")" ::: "memory")
; #define PG8_BAR __builtin_amdgcn_s_barrier()
; template <class Epi, class Sched, bool ALIGN_EPI = false, bool SP2 = false>
; __device__ __forceinline__ void gemm_phase(PG8_LAS unsigned char* lds, const Gemm g, const Sched& S, const Epi& E) {
;     ...
;         const bool has_next = S.next(ui + 1, nxt);
;         const char* nA = has_next ? (const char*)g.A + (size_t)nxt.pm * tstep : cA; const char* nB = has_next ? (const char*)g.Bt + (size_t)nxt.pn * tstep : cB;
;         for (int t = 0; t < nt; t += 2) {
;             const bool last = (t == nt - 2);
;             const char* a1 = cA + (size_t)(t + 1) * kstepA;
;             const char* a2 = last ? nA : cA + (size_t)(t + 2) * kstepA; const char* b2 = last ? nB : cB + (size_t)(t + 2) * kstep;
;             const char* a3 = a2 + kstepA; const char* b3 = b2 + kstep;
;             if (last && has_next) S.a_ready(nxt);
;             if constexpr (SP2) {
;             PG8_LDB(B0, 0, 0); PG8_LDB(B1, 0, 1); PG8_SCHED; PG8_LDA(At, 0, 0); PG8_STAGE(PG8_SA(1, 1), a1 + hstepA, voffA);
;             PG8_WAIT_V(8); PG8_WAIT_L(0); PG8_BAR; PG8_MMA(0, 0, At, B0); PG8_MMA(0, 1, At, B1); PG8_BAR; PG8_SCHED;
;     ...
; #pragma unroll
;         for (int a = 0; a < 2; ++a)
; #pragma unroll
;             for (int b = 0; b < 2; ++b)
; #pragma unroll
;                 for (int m = 0; m < 4; ++m)
; #pragma unroll
;                     for (int n = 0; n < 2; ++n) acc[a][b][m][n] = (f32x4){0.f, 0.f, 0.f, 0.f};
;         cur = nxt; cA = nA; cB = nB; ++ui;
.LBB0_3202:
	s_ashr_i32 s47, s46, 31
	s_lshl_b64 s[48:49], s[46:47], 21
	s_add_u32 s48, s96, s48
	s_addc_u32 s49, s97, s49
	s_and_b64 s[50:51], s[4:5], exec
	s_cselect_b32 s47, s49, s57
	s_cselect_b32 s53, s48, s56
	s_ashr_i32 s45, s44, 31
	s_lshl_b64 s[50:51], s[44:45], 21
	s_add_u32 s50, s14, s50
	s_addc_u32 s51, s15, s51
	s_and_b64 s[60:61], s[4:5], exec
	s_cselect_b32 s45, s51, s59
	s_cselect_b32 s71, s50, s58
	s_add_u32 s56, s56, 0x100080
	s_addc_u32 s57, s57, 0
	s_add_u32 s72, s58, 0x100
	v_mov_b32_e32 v0, 0
	s_addc_u32 s73, s59, 0
	s_mov_b32 s74, -2
	s_waitcnt lgkmcnt(0)
	v_mov_b32_e32 v1, v0
	v_mov_b32_e32 v2, v0
	v_mov_b32_e32 v3, v0
	v_mov_b32_e32 v4, v0
	v_mov_b32_e32 v5, v0
	v_mov_b32_e32 v6, v0
	v_mov_b32_e32 v7, v0
	v_mov_b32_e32 v16, v0
	v_mov_b32_e32 v17, v0
	v_mov_b32_e32 v18, v0
	v_mov_b32_e32 v19, v0
	v_mov_b32_e32 v20, v0
	v_mov_b32_e32 v21, v0
	v_mov_b32_e32 v22, v0
	v_mov_b32_e32 v23, v0
	v_mov_b32_e32 v32, v0
	v_mov_b32_e32 v33, v0
	v_mov_b32_e32 v34, v0
	v_mov_b32_e32 v35, v0
	s_waitcnt vmcnt(0)
	v_mov_b32_e32 v36, v0
	v_mov_b32_e32 v37, v0
	v_mov_b32_e32 v38, v0
	v_mov_b32_e32 v39, v0
	v_mov_b32_e32 v48, v0
	v_mov_b32_e32 v49, v0
	v_mov_b32_e32 v50, v0
	v_mov_b32_e32 v51, v0
	v_mov_b32_e32 v52, v0
	v_mov_b32_e32 v53, v0
	v_mov_b32_e32 v54, v0
	v_mov_b32_e32 v55, v0
	v_mov_b32_e32 v8, v0
	v_mov_b32_e32 v9, v0
	v_mov_b32_e32 v10, v0
	v_mov_b32_e32 v11, v0
	v_mov_b32_e32 v12, v0
	v_mov_b32_e32 v13, v0
	v_mov_b32_e32 v14, v0
	v_mov_b32_e32 v15, v0
	v_mov_b32_e32 v24, v0
	v_mov_b32_e32 v25, v0
	v_mov_b32_e32 v26, v0
	v_mov_b32_e32 v27, v0
	v_mov_b32_e32 v28, v0
	v_mov_b32_e32 v29, v0
	v_mov_b32_e32 v30, v0
	v_mov_b32_e32 v31, v0
	v_mov_b32_e32 v40, v0
	v_mov_b32_e32 v41, v0
	v_mov_b32_e32 v42, v0
	v_mov_b32_e32 v43, v0
	v_mov_b32_e32 v44, v0
	v_mov_b32_e32 v45, v0
	v_mov_b32_e32 v46, v0
	v_mov_b32_e32 v47, v0
	v_mov_b32_e32 v56, v0
	v_mov_b32_e32 v57, v0
	v_mov_b32_e32 v58, v0
	v_mov_b32_e32 v59, v0
	v_mov_b32_e32 v60, v0
	v_mov_b32_e32 v61, v0
	v_mov_b32_e32 v62, v0
	v_mov_b32_e32 v63, v0
	v_mov_b32_e32 v64, v0
	v_mov_b32_e32 v65, v0
	v_mov_b32_e32 v66, v0
	v_mov_b32_e32 v67, v0
	v_mov_b32_e32 v76, v0
	v_mov_b32_e32 v77, v0
	v_mov_b32_e32 v78, v0
	v_mov_b32_e32 v79, v0
	v_mov_b32_e32 v100, v0
	v_mov_b32_e32 v101, v0
	v_mov_b32_e32 v102, v0
	v_mov_b32_e32 v103, v0
	v_mov_b32_e32 v104, v0
	v_mov_b32_e32 v105, v0
	v_mov_b32_e32 v106, v0
	v_mov_b32_e32 v107, v0
	v_mov_b32_e32 v80, v0
	v_mov_b32_e32 v81, v0
	v_mov_b32_e32 v82, v0
	v_mov_b32_e32 v83, v0
	v_mov_b32_e32 v112, v0
	v_mov_b32_e32 v113, v0
	v_mov_b32_e32 v114, v0
	v_mov_b32_e32 v115, v0
	v_mov_b32_e32 v84, v0
	v_mov_b32_e32 v85, v0
	v_mov_b32_e32 v86, v0
	v_mov_b32_e32 v87, v0
	v_mov_b32_e32 v120, v0
	v_mov_b32_e32 v121, v0
	v_mov_b32_e32 v122, v0
	v_mov_b32_e32 v123, v0
	v_mov_b32_e32 v88, v0
	v_mov_b32_e32 v89, v0
	v_mov_b32_e32 v90, v0
	v_mov_b32_e32 v91, v0
	v_mov_b32_e32 v92, v0
	v_mov_b32_e32 v93, v0
	v_mov_b32_e32 v94, v0
	v_mov_b32_e32 v95, v0
	v_mov_b32_e32 v96, v0
	v_mov_b32_e32 v97, v0
	v_mov_b32_e32 v98, v0
	v_mov_b32_e32 v99, v0
	v_mov_b32_e32 v108, v0
	v_mov_b32_e32 v109, v0
	v_mov_b32_e32 v110, v0
	v_mov_b32_e32 v111, v0
	v_mov_b32_e32 v68, v0
	v_mov_b32_e32 v69, v0
	v_mov_b32_e32 v70, v0
	v_mov_b32_e32 v71, v0
	v_mov_b32_e32 v116, v0
	v_mov_b32_e32 v117, v0
	v_mov_b32_e32 v118, v0
	v_mov_b32_e32 v119, v0
	v_mov_b32_e32 v72, v0
	v_mov_b32_e32 v73, v0
	v_mov_b32_e32 v74, v0
	v_mov_b32_e32 v75, v0
	v_mov_b32_e32 v124, v0
	v_mov_b32_e32 v125, v0
	v_mov_b32_e32 v126, v0
	v_mov_b32_e32 v127, v0
	s_cmp_ge_u32 s3, 0x1000
	s_cbranch_scc1 .Lsprio_1
	s_setprio 1
.Lsprio_1:
.LBB0_3203:
	ds_read_b128 v[144:147], v155
	ds_read_b128 v[148:151], v155 offset:1024
	ds_read_b128 v[160:163], v155 offset:2048
	ds_read_b128 v[164:167], v155 offset:3072
	ds_read_b128 v[168:171], v156
	ds_read_b128 v[172:175], v156 offset:1024
	ds_read_b128 v[176:179], v156 offset:2048
	ds_read_b128 v[180:183], v156 offset:3072
	s_add_u32 s58, s56, 0xfff00080
	s_addc_u32 s59, s57, -1
	s_cmp_eq_u32 s74, 60
	s_cselect_b32 s61, s47, s59
	s_cselect_b32 s60, s53, s58
	s_cselect_b32 s59, s45, s73
	s_cselect_b32 s58, s71, s72
	s_add_i32 m0, s29, 0xc000
	ds_read_b128 v[184:187], v157
	ds_read_b128 v[188:191], v157 offset:1024
	ds_read_b128 v[192:195], v157 offset:2048
	ds_read_b128 v[196:199], v157 offset:3072
	ds_read_b128 v[200:203], v157 offset:4096
	ds_read_b128 v[204:207], v157 offset:5120
	ds_read_b128 v[208:211], v157 offset:6144
	ds_read_b128 v[212:215], v157 offset:7168
	global_load_lds_dwordx4 v136, s[56:57]
	s_add_i32 m0, s29, 0xe000
	s_nop 0
	global_load_lds_dwordx4 v138, s[56:57]
	s_waitcnt vmcnt(8)
	s_waitcnt lgkmcnt(0)
	s_barrier
; #define PG8_STAGE(bufoff, gbase, voff) do { _Pragma("unroll") for (int _i = 0; _i < 2; ++_i) \
;         __builtin_amdgcn_global_load_lds((const unsigned*)((const char*)(gbase) + (voff)[_i]), (PG8_LAS unsigned*)(lds + (bufoff) + ldsw + _i * 8192), 16, 0, 0); } while (0)
; #define PG8_LDA(dst, b, h) do { _Pragma("unroll") for (int m = 0; m < 4; ++m) _Pragma("unroll") for (int k = 0; k < 2; ++k) dst[m][k] = *(const PG8_LAS bf16x8*)(lds + PG8_SA(b, h) + aoff + m * 2048 + k * 1024); } while (0)
; #define PG8_MMA(ai, bj, At, Bt) do { __builtin_amdgcn_s_setprio(1); _Pragma("unroll") for (int m = 0; m < 4; ++m) _Pragma("unroll") for (int n = 0; n < 2; ++n) _Pragma("unroll") for (int k = 0; k < 2; ++k) \
;         acc[ai][bj][m][n] = __builtin_amdgcn_mfma_f32_16x16x32_bf16(Bt[n][k], At[m][k], acc[ai][bj][m][n], 0, 0, 0); __builtin_amdgcn_s_setprio(0); } while (0)
; #define PG8_WAIT_V(n) asm volatile("s_waitcnt vmcnt(" #n ")" ::: "memory")
; #define PG8_WAIT_L(n) asm volatile("s_waitcnt lgkmcnt(" #n ")" ::: "memory")
; #define PG8_BAR __builtin_amdgcn_s_barrier()
; #define PG8_SCHED __builtin_amdgcn_sched_barrier(0)
; template <class Epi, class Sched, bool ALIGN_EPI = false, bool SP2 = false>
; __device__ __forceinline__ void gemm_phase(PG8_LAS unsigned char* lds, const Gemm g, const Sched& S, const Epi& E) {
;     ...
;             PG8_WAIT_V(8); PG8_WAIT_L(0); PG8_BAR; PG8_MMA(0, 0, At, B0); PG8_MMA(0, 1, At, B1); PG8_BAR; PG8_SCHED;
;             PG8_LDA(At, 0, 1); PG8_STAGE(PG8_SB(0, 0), b2, voffB); PG8_STAGE(PG8_SB(0, 1), b2 + hstep, voffB); PG8_STAGE(PG8_SA(0, 0), a2, voffA);
;             PG8_WAIT_V(8); PG8_WAIT_L(0); PG8_BAR; PG8_MMA(1, 0, At, B0); PG8_MMA(1, 1, At, B1); PG8_BAR; PG8_SCHED;
	v_mfma_f32_16x16x32_bf16 v[124:127], v[144:147], v[184:187], v[124:127]
	v_mfma_f32_16x16x32_bf16 v[72:75], v[160:163], v[184:187], v[72:75]
	v_mfma_f32_16x16x32_bf16 v[116:119], v[144:147], v[192:195], v[116:119]
	v_mfma_f32_16x16x32_bf16 v[68:71], v[160:163], v[192:195], v[68:71]
	v_mfma_f32_16x16x32_bf16 v[108:111], v[144:147], v[200:203], v[108:111]
	v_mfma_f32_16x16x32_bf16 v[96:99], v[160:163], v[200:203], v[96:99]
	v_mfma_f32_16x16x32_bf16 v[92:95], v[144:147], v[208:211], v[92:95]
	v_mfma_f32_16x16x32_bf16 v[88:91], v[160:163], v[208:211], v[88:91]
	v_mfma_f32_16x16x32_bf16 v[124:127], v[148:151], v[188:191], v[124:127]
	v_mfma_f32_16x16x32_bf16 v[72:75], v[164:167], v[188:191], v[72:75]
	v_mfma_f32_16x16x32_bf16 v[116:119], v[148:151], v[196:199], v[116:119]
	v_mfma_f32_16x16x32_bf16 v[68:71], v[164:167], v[196:199], v[68:71]
	v_mfma_f32_16x16x32_bf16 v[108:111], v[148:151], v[204:207], v[108:111]
	v_mfma_f32_16x16x32_bf16 v[96:99], v[164:167], v[204:207], v[96:99]
	v_mfma_f32_16x16x32_bf16 v[92:95], v[148:151], v[212:215], v[92:95]
	v_mfma_f32_16x16x32_bf16 v[88:91], v[164:167], v[212:215], v[88:91]
	v_mfma_f32_16x16x32_bf16 v[120:123], v[168:171], v[184:187], v[120:123]
	v_mfma_f32_16x16x32_bf16 v[84:87], v[176:179], v[184:187], v[84:87]
	v_mfma_f32_16x16x32_bf16 v[112:115], v[168:171], v[192:195], v[112:115]
	v_mfma_f32_16x16x32_bf16 v[80:83], v[176:179], v[192:195], v[80:83]
	v_mfma_f32_16x16x32_bf16 v[104:107], v[168:171], v[200:203], v[104:107]
	v_mfma_f32_16x16x32_bf16 v[100:103], v[176:179], v[200:203], v[100:103]
	v_mfma_f32_16x16x32_bf16 v[76:79], v[168:171], v[208:211], v[76:79]
	v_mfma_f32_16x16x32_bf16 v[64:67], v[176:179], v[208:211], v[64:67]
	v_mfma_f32_16x16x32_bf16 v[120:123], v[172:175], v[188:191], v[120:123]
	v_mfma_f32_16x16x32_bf16 v[84:87], v[180:183], v[188:191], v[84:87]
	v_mfma_f32_16x16x32_bf16 v[112:115], v[172:175], v[196:199], v[112:115]
	v_mfma_f32_16x16x32_bf16 v[80:83], v[180:183], v[196:199], v[80:83]
	v_mfma_f32_16x16x32_bf16 v[104:107], v[172:175], v[204:207], v[104:107]
	v_mfma_f32_16x16x32_bf16 v[100:103], v[180:183], v[204:207], v[100:103]
	v_mfma_f32_16x16x32_bf16 v[76:79], v[172:175], v[212:215], v[76:79]
	v_mfma_f32_16x16x32_bf16 v[64:67], v[180:183], v[212:215], v[64:67]
	s_barrier
	s_add_u32 s98, s58, s20
	s_addc_u32 s99, s59, s21
	s_add_u32 s100, s60, s20
	s_addc_u32 s101, s61, s21
	s_add_i32 s75, s68, s3
	s_mov_b32 m0, s75
	ds_read_b128 v[184:187], v157 offset:16384
	ds_read_b128 v[188:191], v157 offset:17408
	ds_read_b128 v[192:195], v157 offset:18432
	ds_read_b128 v[196:199], v157 offset:19456
	ds_read_b128 v[200:203], v157 offset:20480
	ds_read_b128 v[204:207], v157 offset:21504
	ds_read_b128 v[208:211], v157 offset:22528
	ds_read_b128 v[212:215], v157 offset:23552
	global_load_lds_dwordx4 v130, s[58:59]
	s_add_i32 m0, s75, 0x2000
	s_add_u32 s84, s58, 0x100000
	s_addc_u32 s85, s59, 0
	s_add_i32 s75, s69, s3
	global_load_lds_dwordx4 v134, s[58:59]
	s_mov_b32 m0, s75
	s_nop 0
	global_load_lds_dwordx4 v130, s[84:85]
	s_add_i32 m0, s75, 0x2000
	s_nop 0
	global_load_lds_dwordx4 v134, s[84:85]
	s_mov_b32 m0, s29
	s_nop 0
	global_load_lds_dwordx4 v128, s[60:61]
	s_mov_b32 m0, s33
	s_nop 0
	global_load_lds_dwordx4 v132, s[60:61]
	s_waitcnt vmcnt(8)
	s_waitcnt lgkmcnt(0)
	s_barrier
	v_mfma_f32_16x16x32_bf16 v[60:63], v[144:147], v[184:187], v[60:63]
	v_mfma_f32_16x16x32_bf16 v[56:59], v[160:163], v[184:187], v[56:59]
	v_mfma_f32_16x16x32_bf16 v[44:47], v[144:147], v[192:195], v[44:47]
	v_mfma_f32_16x16x32_bf16 v[40:43], v[160:163], v[192:195], v[40:43]
	v_mfma_f32_16x16x32_bf16 v[28:31], v[144:147], v[200:203], v[28:31]
	v_mfma_f32_16x16x32_bf16 v[24:27], v[160:163], v[200:203], v[24:27]
	v_mfma_f32_16x16x32_bf16 v[12:15], v[144:147], v[208:211], v[12:15]
	v_mfma_f32_16x16x32_bf16 v[8:11], v[160:163], v[208:211], v[8:11]
	v_mfma_f32_16x16x32_bf16 v[60:63], v[148:151], v[188:191], v[60:63]
	v_mfma_f32_16x16x32_bf16 v[56:59], v[164:167], v[188:191], v[56:59]
	v_mfma_f32_16x16x32_bf16 v[44:47], v[148:151], v[196:199], v[44:47]
	v_mfma_f32_16x16x32_bf16 v[40:43], v[164:167], v[196:199], v[40:43]
	v_mfma_f32_16x16x32_bf16 v[28:31], v[148:151], v[204:207], v[28:31]
	v_mfma_f32_16x16x32_bf16 v[24:27], v[164:167], v[204:207], v[24:27]
	v_mfma_f32_16x16x32_bf16 v[12:15], v[148:151], v[212:215], v[12:15]
	v_mfma_f32_16x16x32_bf16 v[8:11], v[164:167], v[212:215], v[8:11]
	v_mfma_f32_16x16x32_bf16 v[52:55], v[168:171], v[184:187], v[52:55]
	v_mfma_f32_16x16x32_bf16 v[48:51], v[176:179], v[184:187], v[48:51]
	v_mfma_f32_16x16x32_bf16 v[36:39], v[168:171], v[192:195], v[36:39]
	v_mfma_f32_16x16x32_bf16 v[32:35], v[176:179], v[192:195], v[32:35]
	v_mfma_f32_16x16x32_bf16 v[20:23], v[168:171], v[200:203], v[20:23]
	v_mfma_f32_16x16x32_bf16 v[16:19], v[176:179], v[200:203], v[16:19]
	v_mfma_f32_16x16x32_bf16 v[4:7], v[168:171], v[208:211], v[4:7]
	v_mfma_f32_16x16x32_bf16 v[0:3], v[176:179], v[208:211], v[0:3]
	v_mfma_f32_16x16x32_bf16 v[52:55], v[172:175], v[188:191], v[52:55]
	v_mfma_f32_16x16x32_bf16 v[48:51], v[180:183], v[188:191], v[48:51]
	v_mfma_f32_16x16x32_bf16 v[36:39], v[172:175], v[196:199], v[36:39]
	v_mfma_f32_16x16x32_bf16 v[32:35], v[180:183], v[196:199], v[32:35]
	v_mfma_f32_16x16x32_bf16 v[20:23], v[172:175], v[204:207], v[20:23]
	v_mfma_f32_16x16x32_bf16 v[16:19], v[180:183], v[204:207], v[16:19]
	v_mfma_f32_16x16x32_bf16 v[4:7], v[172:175], v[212:215], v[4:7]
	v_mfma_f32_16x16x32_bf16 v[0:3], v[180:183], v[212:215], v[0:3]
	s_barrier
; #define PG8_STAGE(bufoff, gbase, voff) do { _Pragma("unroll") for (int _i = 0; _i < 2; ++_i) \
;         __builtin_amdgcn_global_load_lds((const unsigned*)((const char*)(gbase) + (voff)[_i]), (PG8_LAS unsigned*)(lds + (bufoff) + ldsw + _i * 8192), 16, 0, 0); } while (0)
; #define PG8_LDA(dst, b, h) do { _Pragma("unroll") for (int m = 0; m < 4; ++m) _Pragma("unroll") for (int k = 0; k < 2; ++k) dst[m][k] = *(const PG8_LAS bf16x8*)(lds + PG8_SA(b, h) + aoff + m * 2048 + k * 1024); } while (0)
; #define PG8_LDB(dst, b, h) do { _Pragma("unroll") for (int n = 0; n < 2; ++n) _Pragma("unroll") for (int k = 0; k < 2; ++k) dst[n][k] = *(const PG8_LAS bf16x8*)(lds + PG8_SB(b, h) + boff + n * 2048 + k * 1024); } while (0)
; #define PG8_MMA(ai, bj, At, Bt) do { __builtin_amdgcn_s_setprio(1); _Pragma("unroll") for (int m = 0; m < 4; ++m) _Pragma("unroll") for (int n = 0; n < 2; ++n) _Pragma("unroll") for (int k = 0; k < 2; ++k) \
;         acc[ai][bj][m][n] = __builtin_amdgcn_mfma_f32_16x16x32_bf16(Bt[n][k], At[m][k], acc[ai][bj][m][n], 0, 0, 0); __builtin_amdgcn_s_setprio(0); } while (0)
; #define PG8_WAIT_V(n) asm volatile("s_waitcnt vmcnt(" #n ")" ::: "memory")
; #define PG8_WAIT_L(n) asm volatile("s_waitcnt lgkmcnt(" #n ")" ::: "memory")
; #define PG8_BAR __builtin_amdgcn_s_barrier()
; #define PG8_SCHED __builtin_amdgcn_sched_barrier(0)
; template <class Epi, class Sched, bool ALIGN_EPI = false, bool SP2 = false>
; __device__ __forceinline__ void gemm_phase(PG8_LAS unsigned char* lds, const Gemm g, const Sched& S, const Epi& E) {
;     ...
;         for (int t = 0; t < nt; t += 2) {
;     ...
;             PG8_LDB(B0, 1, 0); PG8_LDB(B1, 1, 1); PG8_SCHED; PG8_LDA(At, 1, 0); PG8_STAGE(PG8_SA(0, 1), a2 + hstepA, voffA);
;             PG8_WAIT_V(8); PG8_WAIT_L(0); PG8_BAR; PG8_MMA(0, 0, At, B0); PG8_MMA(0, 1, At, B1); PG8_BAR; PG8_SCHED;
;             PG8_LDA(At, 1, 1); PG8_STAGE(PG8_SB(1, 0), b3, voffB); PG8_STAGE(PG8_SB(1, 1), b3 + hstep, voffB); PG8_STAGE(PG8_SA(1, 0), a3, voffA);
;             PG8_WAIT_V(8); PG8_WAIT_L(0); PG8_BAR; PG8_MMA(1, 0, At, B0); PG8_MMA(1, 1, At, B1); PG8_BAR; PG8_SCHED;
	s_add_i32 s75, 0, 0x18000
	s_add_i32 s84, 0, 0x1c000
	v_add_u32_e32 v164, s75, v153
	v_add_u32_e32 v180, s84, v153
	ds_read_b128 v[144:147], v164
	ds_read_b128 v[148:151], v164 offset:1024
	ds_read_b128 v[160:163], v164 offset:2048
	ds_read_b128 v[164:167], v164 offset:3072
	ds_read_b128 v[168:171], v180
	ds_read_b128 v[172:175], v180 offset:1024
	ds_read_b128 v[176:179], v180 offset:2048
	ds_read_b128 v[180:183], v180 offset:3072
	s_add_u32 s60, s60, 0x100000
	s_addc_u32 s61, s61, 0
	s_mov_b32 m0, s55
	ds_read_b128 v[184:187], v157 offset:32768
	ds_read_b128 v[188:191], v157 offset:33792
	ds_read_b128 v[192:195], v157 offset:34816
	ds_read_b128 v[196:199], v157 offset:35840
	ds_read_b128 v[200:203], v157 offset:36864
	ds_read_b128 v[204:207], v157 offset:37888
	ds_read_b128 v[208:211], v157 offset:38912
	ds_read_b128 v[212:215], v157 offset:39936
	global_load_lds_dwordx4 v128, s[60:61]
	s_mov_b32 m0, s62
	s_nop 0
	global_load_lds_dwordx4 v132, s[60:61]
	s_waitcnt vmcnt(8)
	s_waitcnt lgkmcnt(0)
	s_barrier
	v_mfma_f32_16x16x32_bf16 v[124:127], v[144:147], v[184:187], v[124:127]
	v_mfma_f32_16x16x32_bf16 v[72:75], v[160:163], v[184:187], v[72:75]
	v_mfma_f32_16x16x32_bf16 v[116:119], v[144:147], v[192:195], v[116:119]
	v_mfma_f32_16x16x32_bf16 v[68:71], v[160:163], v[192:195], v[68:71]
	v_mfma_f32_16x16x32_bf16 v[108:111], v[144:147], v[200:203], v[108:111]
	v_mfma_f32_16x16x32_bf16 v[96:99], v[160:163], v[200:203], v[96:99]
	v_mfma_f32_16x16x32_bf16 v[92:95], v[144:147], v[208:211], v[92:95]
	v_mfma_f32_16x16x32_bf16 v[88:91], v[160:163], v[208:211], v[88:91]
	v_mfma_f32_16x16x32_bf16 v[124:127], v[148:151], v[188:191], v[124:127]
	v_mfma_f32_16x16x32_bf16 v[72:75], v[164:167], v[188:191], v[72:75]
	v_mfma_f32_16x16x32_bf16 v[116:119], v[148:151], v[196:199], v[116:119]
	v_mfma_f32_16x16x32_bf16 v[68:71], v[164:167], v[196:199], v[68:71]
	v_mfma_f32_16x16x32_bf16 v[108:111], v[148:151], v[204:207], v[108:111]
	v_mfma_f32_16x16x32_bf16 v[96:99], v[164:167], v[204:207], v[96:99]
	v_mfma_f32_16x16x32_bf16 v[92:95], v[148:151], v[212:215], v[92:95]
	v_mfma_f32_16x16x32_bf16 v[88:91], v[164:167], v[212:215], v[88:91]
	v_mfma_f32_16x16x32_bf16 v[120:123], v[168:171], v[184:187], v[120:123]
	v_mfma_f32_16x16x32_bf16 v[84:87], v[176:179], v[184:187], v[84:87]
	v_mfma_f32_16x16x32_bf16 v[112:115], v[168:171], v[192:195], v[112:115]
	v_mfma_f32_16x16x32_bf16 v[80:83], v[176:179], v[192:195], v[80:83]
	v_mfma_f32_16x16x32_bf16 v[104:107], v[168:171], v[200:203], v[104:107]
	v_mfma_f32_16x16x32_bf16 v[100:103], v[176:179], v[200:203], v[100:103]
	v_mfma_f32_16x16x32_bf16 v[76:79], v[168:171], v[208:211], v[76:79]
	v_mfma_f32_16x16x32_bf16 v[64:67], v[176:179], v[208:211], v[64:67]
	v_mfma_f32_16x16x32_bf16 v[120:123], v[172:175], v[188:191], v[120:123]
	v_mfma_f32_16x16x32_bf16 v[84:87], v[180:183], v[188:191], v[84:87]
	v_mfma_f32_16x16x32_bf16 v[112:115], v[172:175], v[196:199], v[112:115]
	v_mfma_f32_16x16x32_bf16 v[80:83], v[180:183], v[196:199], v[80:83]
	v_mfma_f32_16x16x32_bf16 v[104:107], v[172:175], v[204:207], v[104:107]
	v_mfma_f32_16x16x32_bf16 v[100:103], v[180:183], v[204:207], v[100:103]
	v_mfma_f32_16x16x32_bf16 v[76:79], v[172:175], v[212:215], v[76:79]
	v_mfma_f32_16x16x32_bf16 v[64:67], v[180:183], v[212:215], v[64:67]
	s_barrier
	s_add_i32 s60, s75, s3
	s_mov_b32 m0, s60
	ds_read_b128 v[184:187], v157 offset:49152
	ds_read_b128 v[188:191], v157 offset:50176
	ds_read_b128 v[192:195], v157 offset:51200
	ds_read_b128 v[196:199], v157 offset:52224
	ds_read_b128 v[200:203], v157 offset:53248
	ds_read_b128 v[204:207], v157 offset:54272
	ds_read_b128 v[208:211], v157 offset:55296
	ds_read_b128 v[212:215], v157 offset:56320
	global_load_lds_dwordx4 v130, s[98:99]
	s_add_i32 m0, s60, 0x2000
	s_add_u32 s58, s58, 0x100080
	s_addc_u32 s59, s59, 0
	s_add_i32 s60, s84, s3
	global_load_lds_dwordx4 v134, s[98:99]
	s_mov_b32 m0, s60
	s_nop 0
	global_load_lds_dwordx4 v130, s[58:59]
	s_add_i32 m0, s60, 0x2000
	s_nop 0
	global_load_lds_dwordx4 v134, s[58:59]
	s_mov_b32 m0, s64
	s_nop 0
	global_load_lds_dwordx4 v128, s[100:101]
	s_mov_b32 m0, s65
	s_nop 0
	global_load_lds_dwordx4 v132, s[100:101]
	s_waitcnt vmcnt(8)
	s_waitcnt lgkmcnt(0)
	s_barrier
	v_mfma_f32_16x16x32_bf16 v[60:63], v[144:147], v[184:187], v[60:63]
	v_mfma_f32_16x16x32_bf16 v[56:59], v[160:163], v[184:187], v[56:59]
	v_mfma_f32_16x16x32_bf16 v[44:47], v[144:147], v[192:195], v[44:47]
	v_mfma_f32_16x16x32_bf16 v[40:43], v[160:163], v[192:195], v[40:43]
	v_mfma_f32_16x16x32_bf16 v[28:31], v[144:147], v[200:203], v[28:31]
	v_mfma_f32_16x16x32_bf16 v[24:27], v[160:163], v[200:203], v[24:27]
	v_mfma_f32_16x16x32_bf16 v[12:15], v[144:147], v[208:211], v[12:15]
	v_mfma_f32_16x16x32_bf16 v[8:11], v[160:163], v[208:211], v[8:11]
	v_mfma_f32_16x16x32_bf16 v[60:63], v[148:151], v[188:191], v[60:63]
	v_mfma_f32_16x16x32_bf16 v[56:59], v[164:167], v[188:191], v[56:59]
	v_mfma_f32_16x16x32_bf16 v[44:47], v[148:151], v[196:199], v[44:47]
	v_mfma_f32_16x16x32_bf16 v[40:43], v[164:167], v[196:199], v[40:43]
	v_mfma_f32_16x16x32_bf16 v[28:31], v[148:151], v[204:207], v[28:31]
	v_mfma_f32_16x16x32_bf16 v[24:27], v[164:167], v[204:207], v[24:27]
	v_mfma_f32_16x16x32_bf16 v[12:15], v[148:151], v[212:215], v[12:15]
	v_mfma_f32_16x16x32_bf16 v[8:11], v[164:167], v[212:215], v[8:11]
	v_mfma_f32_16x16x32_bf16 v[52:55], v[168:171], v[184:187], v[52:55]
	v_mfma_f32_16x16x32_bf16 v[48:51], v[176:179], v[184:187], v[48:51]
	v_mfma_f32_16x16x32_bf16 v[36:39], v[168:171], v[192:195], v[36:39]
	v_mfma_f32_16x16x32_bf16 v[32:35], v[176:179], v[192:195], v[32:35]
	v_mfma_f32_16x16x32_bf16 v[20:23], v[168:171], v[200:203], v[20:23]
	v_mfma_f32_16x16x32_bf16 v[16:19], v[176:179], v[200:203], v[16:19]
	v_mfma_f32_16x16x32_bf16 v[4:7], v[168:171], v[208:211], v[4:7]
	v_mfma_f32_16x16x32_bf16 v[0:3], v[176:179], v[208:211], v[0:3]
	v_mfma_f32_16x16x32_bf16 v[52:55], v[172:175], v[188:191], v[52:55]
	v_mfma_f32_16x16x32_bf16 v[48:51], v[180:183], v[188:191], v[48:51]
	v_mfma_f32_16x16x32_bf16 v[36:39], v[172:175], v[196:199], v[36:39]
	v_mfma_f32_16x16x32_bf16 v[32:35], v[180:183], v[196:199], v[32:35]
	v_mfma_f32_16x16x32_bf16 v[20:23], v[172:175], v[204:207], v[20:23]
	v_mfma_f32_16x16x32_bf16 v[16:19], v[180:183], v[204:207], v[16:19]
	v_mfma_f32_16x16x32_bf16 v[4:7], v[172:175], v[212:215], v[4:7]
	v_mfma_f32_16x16x32_bf16 v[0:3], v[180:183], v[212:215], v[0:3]
	s_barrier
	s_add_i32 s74, s74, 2
	s_add_u32 s56, s56, 0x100
	s_addc_u32 s57, s57, 0
	s_add_u32 s72, s72, 0x100
	s_addc_u32 s73, s73, 0
	s_cmp_gt_u32 s74, 61
	s_cbranch_scc0 .LBB0_3203
	s_setprio 0
	s_and_b64 vcc, exec, s[22:23]
	s_cbranch_vccz .LBB0_3206
	s_barrier
